# FOLD weight-conversion tile rewritten: per-lane row loads + v_readlane broadcast instead of 256 wave-uniform loads
# baseline (speedup 1.0000x reference)
; __device__ __forceinline__ void cvt_job(int& tbase, const float* __restrict__ src, int Nsrc, int K, bf16_t* __restrict__ dst, int ndst, int mode,
;                                         const float* __restrict__ gain, const float* __restrict__ up_f, const float* __restrict__ up_b, int bi, int nb) {
;     ...
;         const int n0 = (t % nT) << 6, k0 = (t / nT) << 6, n = n0 + lane;
;         int col = n; float scale = 1.f;
;         if (mode == CM_SWIGLU) { const int j = n & 255, pn = n >> 8; col = (j < 128) ? pn * 128 + j : FF + pn * 128 + (j - 128); }
;         else if (mode == CM_WIN_A) { scale = (n < 512) ? 0.08838834764831845f : 1.f; }
;         else if (mode == CM_WIN_B) { col = 3104 + n; }
;         float v[64];
;         if (mode == CM_FOLD) {
;             const int dirb = n >> 9, c = n & 511; const float* up = dirb ? up_b : up_f;
;             float upv[16];
; #pragma unroll
;             for (int r = 0; r < 16; ++r) upv[r] = up[r * 512 + c];
; #pragma unroll
;             for (int j = 0; j < 64; ++j) { const float* wp = src + (size_t)(k0 + j) * Nsrc + 3072 + 16 * dirb; float sacc = 0.f;
; #pragma unroll
;                 for (int r = 0; r < 16; ++r) sacc += wp[r] * upv[r];
;                 v[j] = sacc; }
;         } else {
;             const float* sp = src + (size_t)k0 * Nsrc + col;
; #pragma unroll
;             for (int j = 0; j < 64; ++j) v[j] = sp[(size_t)j * Nsrc];
;         }
;         bf16_t* dp = dst + (size_t)n * K + k0;
.LBB0_102:
	v_ashrrev_i32_e32 v0, 31, v47
	v_lshrrev_b32_e32 v0, 28, v0
	v_add_u32_e32 v0, v47, v0
	v_ashrrev_i32_e32 v2, 4, v0
	v_and_b32_e32 v0, -16, v0
	v_lshlrev_b32_e32 v1, 10, v2
	v_sub_u32_e32 v0, v47, v0
	v_sub_u32_e32 v42, v48, v1
	v_and_b32_e32 v3, 0x1ff, v42
	v_cmp_gt_u32_e32 vcc, 8, v0
	v_lshlrev_b32_e32 v36, 2, v3
	v_lshlrev_b32_e32 v40, 6, v2
	v_cndmask_b32_e32 v1, v50, v51, vcc
	v_cndmask_b32_e32 v0, v52, v53, vcc
	v_lshl_add_u64 v[4:5], v[0:1], 0, v[36:37]
	v_lshlrev_b32_e32 v0, 5, v2
	v_sub_u32_e32 v0, v49, v0
	v_and_b32_e32 v0, -16, v0
	v_ashrrev_i32_e32 v1, 31, v0
	v_lshlrev_b64 v[44:45], 2, v[0:1]
	v_ashrrev_i32_e32 v41, 31, v40
	v_add_u32_e32 v166, v40, v165
	v_mad_i64_i32 v[166:167], s[26:27], v166, s42, v[38:39]
	v_lshl_add_u64 v[166:167], v[166:167], 0, v[44:45]
	v_lshl_add_u64 v[166:167], v[166:167], 0, s[18:19]
	global_load_dwordx4 v[126:129], v[166:167], off
	global_load_dwordx4 v[130:133], v[166:167], off offset:16
	global_load_dwordx4 v[134:137], v[166:167], off offset:32
	global_load_dwordx4 v[138:141], v[166:167], off offset:48
	v_add_co_u32_e32 v168, vcc, s35, v4
	s_nop 1
	v_addc_co_u32_e32 v169, vcc, 0, v5, vcc
	v_add_co_u32_e32 v170, vcc, s37, v4
	s_nop 1
	v_addc_co_u32_e32 v171, vcc, 0, v5, vcc
	v_add_co_u32_e32 v172, vcc, s39, v4
	s_nop 1
	v_addc_co_u32_e32 v173, vcc, 0, v5, vcc
	v_add_co_u32_e32 v182, vcc, s41, v4
	s_nop 1
	v_addc_co_u32_e32 v183, vcc, 0, v5, vcc
	global_load_dword v142, v[168:169], off offset:-4096
	global_load_dword v143, v[168:169], off offset:-2048
	global_load_dword v144, v[168:169], off
	global_load_dword v145, v[168:169], off offset:2048
	global_load_dword v146, v[170:171], off offset:-4096
	global_load_dword v147, v[170:171], off offset:-2048
	global_load_dword v148, v[170:171], off
	global_load_dword v149, v[170:171], off offset:2048
	global_load_dword v150, v[172:173], off offset:-4096
	global_load_dword v151, v[172:173], off offset:-2048
	global_load_dword v154, v[172:173], off
	global_load_dword v155, v[172:173], off offset:2048
	global_load_dword v156, v[182:183], off offset:-4096
	global_load_dword v157, v[182:183], off offset:-2048
	global_load_dword v158, v[182:183], off
	global_load_dword v159, v[182:183], off offset:2048
	s_waitcnt vmcnt(0)
	v_readlane_b32 s98, v126, 0
	v_readlane_b32 s99, v127, 0
	v_readlane_b32 s100, v128, 0
	v_readlane_b32 s101, v129, 0
	v_fma_f32 v36, s98, v142, 0
	v_fmac_f32_e32 v36, s99, v143
	v_fmac_f32_e32 v36, s100, v144
	v_fmac_f32_e32 v36, s101, v145
	v_readlane_b32 s98, v130, 0
	v_readlane_b32 s99, v131, 0
	v_readlane_b32 s100, v132, 0
	v_readlane_b32 s101, v133, 0
	v_fmac_f32_e32 v36, s98, v146
	v_fmac_f32_e32 v36, s99, v147
	v_fmac_f32_e32 v36, s100, v148
	v_fmac_f32_e32 v36, s101, v149
	v_readlane_b32 s98, v134, 0
	v_readlane_b32 s99, v135, 0
	v_readlane_b32 s100, v136, 0
	v_readlane_b32 s101, v137, 0
	v_fmac_f32_e32 v36, s98, v150
	v_fmac_f32_e32 v36, s99, v151
	v_fmac_f32_e32 v36, s100, v154
	v_fmac_f32_e32 v36, s101, v155
	v_readlane_b32 s98, v138, 0
	v_readlane_b32 s99, v139, 0
	v_readlane_b32 s100, v140, 0
	v_readlane_b32 s101, v141, 0
	v_fmac_f32_e32 v36, s98, v156
	v_fmac_f32_e32 v36, s99, v157
	v_fmac_f32_e32 v36, s100, v158
	v_fmac_f32_e32 v36, s101, v159
	v_readlane_b32 s98, v126, 1
	v_readlane_b32 s99, v127, 1
	v_readlane_b32 s100, v128, 1
	v_readlane_b32 s101, v129, 1
	v_fma_f32 v61, s98, v142, 0
	v_fmac_f32_e32 v61, s99, v143
	v_fmac_f32_e32 v61, s100, v144
	v_fmac_f32_e32 v61, s101, v145
	v_readlane_b32 s98, v130, 1
	v_readlane_b32 s99, v131, 1
	v_readlane_b32 s100, v132, 1
	v_readlane_b32 s101, v133, 1
	v_fmac_f32_e32 v61, s98, v146
	v_fmac_f32_e32 v61, s99, v147
	v_fmac_f32_e32 v61, s100, v148
	v_fmac_f32_e32 v61, s101, v149
	v_readlane_b32 s98, v134, 1
	v_readlane_b32 s99, v135, 1
	v_readlane_b32 s100, v136, 1
	v_readlane_b32 s101, v137, 1
	v_fmac_f32_e32 v61, s98, v150
	v_fmac_f32_e32 v61, s99, v151
	v_fmac_f32_e32 v61, s100, v154
	v_fmac_f32_e32 v61, s101, v155
	v_readlane_b32 s98, v138, 1
	v_readlane_b32 s99, v139, 1
	v_readlane_b32 s100, v140, 1
	v_readlane_b32 s101, v141, 1
	v_fmac_f32_e32 v61, s98, v156
	v_fmac_f32_e32 v61, s99, v157
	v_fmac_f32_e32 v61, s100, v158
	v_fmac_f32_e32 v61, s101, v159
	v_readlane_b32 s98, v126, 2
	v_readlane_b32 s99, v127, 2
	v_readlane_b32 s100, v128, 2
	v_readlane_b32 s101, v129, 2
	v_fma_f32 v62, s98, v142, 0
	v_fmac_f32_e32 v62, s99, v143
	v_fmac_f32_e32 v62, s100, v144
	v_fmac_f32_e32 v62, s101, v145
	v_readlane_b32 s98, v130, 2
	v_readlane_b32 s99, v131, 2
	v_readlane_b32 s100, v132, 2
	v_readlane_b32 s101, v133, 2
	v_fmac_f32_e32 v62, s98, v146
	v_fmac_f32_e32 v62, s99, v147
	v_fmac_f32_e32 v62, s100, v148
	v_fmac_f32_e32 v62, s101, v149
	v_readlane_b32 s98, v134, 2
	v_readlane_b32 s99, v135, 2
	v_readlane_b32 s100, v136, 2
	v_readlane_b32 s101, v137, 2
	v_fmac_f32_e32 v62, s98, v150
	v_fmac_f32_e32 v62, s99, v151
	v_fmac_f32_e32 v62, s100, v154
	v_fmac_f32_e32 v62, s101, v155
	v_readlane_b32 s98, v138, 2
	v_readlane_b32 s99, v139, 2
	v_readlane_b32 s100, v140, 2
	v_readlane_b32 s101, v141, 2
	v_fmac_f32_e32 v62, s98, v156
	v_fmac_f32_e32 v62, s99, v157
	v_fmac_f32_e32 v62, s100, v158
	v_fmac_f32_e32 v62, s101, v159
	v_readlane_b32 s98, v126, 3
	v_readlane_b32 s99, v127, 3
	v_readlane_b32 s100, v128, 3
	v_readlane_b32 s101, v129, 3
	v_fma_f32 v63, s98, v142, 0
	v_fmac_f32_e32 v63, s99, v143
	v_fmac_f32_e32 v63, s100, v144
	v_fmac_f32_e32 v63, s101, v145
	v_readlane_b32 s98, v130, 3
	v_readlane_b32 s99, v131, 3
	v_readlane_b32 s100, v132, 3
	v_readlane_b32 s101, v133, 3
	v_fmac_f32_e32 v63, s98, v146
	v_fmac_f32_e32 v63, s99, v147
	v_fmac_f32_e32 v63, s100, v148
; __device__ __forceinline__ void cvt_job(int& tbase, const float* __restrict__ src, int Nsrc, int K, bf16_t* __restrict__ dst, int ndst, int mode,
;                                         const float* __restrict__ gain, const float* __restrict__ up_f, const float* __restrict__ up_b, int bi, int nb) {
;     ...
;             for (int j = 0; j < 64; ++j) { const float* wp = src + (size_t)(k0 + j) * Nsrc + 3072 + 16 * dirb; float sacc = 0.f;
; #pragma unroll
;                 for (int r = 0; r < 16; ++r) sacc += wp[r] * upv[r];
;                 v[j] = sacc; }
	v_fmac_f32_e32 v63, s101, v149
	v_readlane_b32 s98, v134, 3
	v_readlane_b32 s99, v135, 3
	v_readlane_b32 s100, v136, 3
	v_readlane_b32 s101, v137, 3
	v_fmac_f32_e32 v63, s98, v150
	v_fmac_f32_e32 v63, s99, v151
	v_fmac_f32_e32 v63, s100, v154
	v_fmac_f32_e32 v63, s101, v155
	v_readlane_b32 s98, v138, 3
	v_readlane_b32 s99, v139, 3
	v_readlane_b32 s100, v140, 3
	v_readlane_b32 s101, v141, 3
	v_fmac_f32_e32 v63, s98, v156
	v_fmac_f32_e32 v63, s99, v157
	v_fmac_f32_e32 v63, s100, v158
	v_fmac_f32_e32 v63, s101, v159
	v_readlane_b32 s98, v126, 4
	v_readlane_b32 s99, v127, 4
	v_readlane_b32 s100, v128, 4
	v_readlane_b32 s101, v129, 4
	v_fma_f32 v64, s98, v142, 0
	v_fmac_f32_e32 v64, s99, v143
	v_fmac_f32_e32 v64, s100, v144
	v_fmac_f32_e32 v64, s101, v145
	v_readlane_b32 s98, v130, 4
	v_readlane_b32 s99, v131, 4
	v_readlane_b32 s100, v132, 4
	v_readlane_b32 s101, v133, 4
	v_fmac_f32_e32 v64, s98, v146
	v_fmac_f32_e32 v64, s99, v147
	v_fmac_f32_e32 v64, s100, v148
	v_fmac_f32_e32 v64, s101, v149
	v_readlane_b32 s98, v134, 4
	v_readlane_b32 s99, v135, 4
	v_readlane_b32 s100, v136, 4
	v_readlane_b32 s101, v137, 4
	v_fmac_f32_e32 v64, s98, v150
	v_fmac_f32_e32 v64, s99, v151
	v_fmac_f32_e32 v64, s100, v154
	v_fmac_f32_e32 v64, s101, v155
	v_readlane_b32 s98, v138, 4
	v_readlane_b32 s99, v139, 4
	v_readlane_b32 s100, v140, 4
	v_readlane_b32 s101, v141, 4
	v_fmac_f32_e32 v64, s98, v156
	v_fmac_f32_e32 v64, s99, v157
	v_fmac_f32_e32 v64, s100, v158
	v_fmac_f32_e32 v64, s101, v159
	v_readlane_b32 s98, v126, 5
	v_readlane_b32 s99, v127, 5
	v_readlane_b32 s100, v128, 5
	v_readlane_b32 s101, v129, 5
	v_fma_f32 v65, s98, v142, 0
	v_fmac_f32_e32 v65, s99, v143
	v_fmac_f32_e32 v65, s100, v144
	v_fmac_f32_e32 v65, s101, v145
	v_readlane_b32 s98, v130, 5
	v_readlane_b32 s99, v131, 5
	v_readlane_b32 s100, v132, 5
	v_readlane_b32 s101, v133, 5
	v_fmac_f32_e32 v65, s98, v146
	v_fmac_f32_e32 v65, s99, v147
	v_fmac_f32_e32 v65, s100, v148
	v_fmac_f32_e32 v65, s101, v149
	v_readlane_b32 s98, v134, 5
	v_readlane_b32 s99, v135, 5
	v_readlane_b32 s100, v136, 5
	v_readlane_b32 s101, v137, 5
	v_fmac_f32_e32 v65, s98, v150
	v_fmac_f32_e32 v65, s99, v151
	v_fmac_f32_e32 v65, s100, v154
	v_fmac_f32_e32 v65, s101, v155
	v_readlane_b32 s98, v138, 5
	v_readlane_b32 s99, v139, 5
	v_readlane_b32 s100, v140, 5
	v_readlane_b32 s101, v141, 5
	v_fmac_f32_e32 v65, s98, v156
	v_fmac_f32_e32 v65, s99, v157
	v_fmac_f32_e32 v65, s100, v158
	v_fmac_f32_e32 v65, s101, v159
	v_readlane_b32 s98, v126, 6
	v_readlane_b32 s99, v127, 6
	v_readlane_b32 s100, v128, 6
	v_readlane_b32 s101, v129, 6
	v_fma_f32 v66, s98, v142, 0
	v_fmac_f32_e32 v66, s99, v143
	v_fmac_f32_e32 v66, s100, v144
	v_fmac_f32_e32 v66, s101, v145
	v_readlane_b32 s98, v130, 6
	v_readlane_b32 s99, v131, 6
	v_readlane_b32 s100, v132, 6
	v_readlane_b32 s101, v133, 6
	v_fmac_f32_e32 v66, s98, v146
	v_fmac_f32_e32 v66, s99, v147
	v_fmac_f32_e32 v66, s100, v148
	v_fmac_f32_e32 v66, s101, v149
	v_readlane_b32 s98, v134, 6
	v_readlane_b32 s99, v135, 6
	v_readlane_b32 s100, v136, 6
	v_readlane_b32 s101, v137, 6
	v_fmac_f32_e32 v66, s98, v150
	v_fmac_f32_e32 v66, s99, v151
	v_fmac_f32_e32 v66, s100, v154
	v_fmac_f32_e32 v66, s101, v155
	v_readlane_b32 s98, v138, 6
	v_readlane_b32 s99, v139, 6
	v_readlane_b32 s100, v140, 6
	v_readlane_b32 s101, v141, 6
	v_fmac_f32_e32 v66, s98, v156
	v_fmac_f32_e32 v66, s99, v157
	v_fmac_f32_e32 v66, s100, v158
	v_fmac_f32_e32 v66, s101, v159
	v_readlane_b32 s98, v126, 7
	v_readlane_b32 s99, v127, 7
	v_readlane_b32 s100, v128, 7
	v_readlane_b32 s101, v129, 7
	v_fma_f32 v71, s98, v142, 0
	v_fmac_f32_e32 v71, s99, v143
	v_fmac_f32_e32 v71, s100, v144
	v_fmac_f32_e32 v71, s101, v145
	v_readlane_b32 s98, v130, 7
	v_readlane_b32 s99, v131, 7
	v_readlane_b32 s100, v132, 7
	v_readlane_b32 s101, v133, 7
	v_fmac_f32_e32 v71, s98, v146
	v_fmac_f32_e32 v71, s99, v147
	v_fmac_f32_e32 v71, s100, v148
	v_fmac_f32_e32 v71, s101, v149
	v_readlane_b32 s98, v134, 7
	v_readlane_b32 s99, v135, 7
	v_readlane_b32 s100, v136, 7
	v_readlane_b32 s101, v137, 7
	v_fmac_f32_e32 v71, s98, v150
	v_fmac_f32_e32 v71, s99, v151
	v_fmac_f32_e32 v71, s100, v154
	v_fmac_f32_e32 v71, s101, v155
	v_readlane_b32 s98, v138, 7
	v_readlane_b32 s99, v139, 7
	v_readlane_b32 s100, v140, 7
	v_readlane_b32 s101, v141, 7
	v_fmac_f32_e32 v71, s98, v156
	v_fmac_f32_e32 v71, s99, v157
	v_fmac_f32_e32 v71, s100, v158
	v_fmac_f32_e32 v71, s101, v159
	v_readlane_b32 s98, v126, 8
	v_readlane_b32 s99, v127, 8
	v_readlane_b32 s100, v128, 8
	v_readlane_b32 s101, v129, 8
	v_fma_f32 v72, s98, v142, 0
	v_fmac_f32_e32 v72, s99, v143
	v_fmac_f32_e32 v72, s100, v144
	v_fmac_f32_e32 v72, s101, v145
	v_readlane_b32 s98, v130, 8
	v_readlane_b32 s99, v131, 8
	v_readlane_b32 s100, v132, 8
	v_readlane_b32 s101, v133, 8
	v_fmac_f32_e32 v72, s98, v146
	v_fmac_f32_e32 v72, s99, v147
	v_fmac_f32_e32 v72, s100, v148
	v_fmac_f32_e32 v72, s101, v149
	v_readlane_b32 s98, v134, 8
	v_readlane_b32 s99, v135, 8
	v_readlane_b32 s100, v136, 8
	v_readlane_b32 s101, v137, 8
	v_fmac_f32_e32 v72, s98, v150
	v_fmac_f32_e32 v72, s99, v151
	v_fmac_f32_e32 v72, s100, v154
	v_fmac_f32_e32 v72, s101, v155
	v_readlane_b32 s98, v138, 8
	v_readlane_b32 s99, v139, 8
	v_readlane_b32 s100, v140, 8
	v_readlane_b32 s101, v141, 8
	v_fmac_f32_e32 v72, s98, v156
	v_fmac_f32_e32 v72, s99, v157
	v_fmac_f32_e32 v72, s100, v158
	v_fmac_f32_e32 v72, s101, v159
	v_readlane_b32 s98, v126, 9
	v_readlane_b32 s99, v127, 9
	v_readlane_b32 s100, v128, 9
	v_readlane_b32 s101, v129, 9
	v_fma_f32 v73, s98, v142, 0
	v_fmac_f32_e32 v73, s99, v143
	v_fmac_f32_e32 v73, s100, v144
	v_fmac_f32_e32 v73, s101, v145
; __device__ __forceinline__ void cvt_job(int& tbase, const float* __restrict__ src, int Nsrc, int K, bf16_t* __restrict__ dst, int ndst, int mode,
;                                         const float* __restrict__ gain, const float* __restrict__ up_f, const float* __restrict__ up_b, int bi, int nb) {
;     ...
;             for (int j = 0; j < 64; ++j) { const float* wp = src + (size_t)(k0 + j) * Nsrc + 3072 + 16 * dirb; float sacc = 0.f;
; #pragma unroll
;                 for (int r = 0; r < 16; ++r) sacc += wp[r] * upv[r];
;                 v[j] = sacc; }
	v_readlane_b32 s98, v130, 9
	v_readlane_b32 s99, v131, 9
	v_readlane_b32 s100, v132, 9
	v_readlane_b32 s101, v133, 9
	v_fmac_f32_e32 v73, s98, v146
	v_fmac_f32_e32 v73, s99, v147
	v_fmac_f32_e32 v73, s100, v148
	v_fmac_f32_e32 v73, s101, v149
	v_readlane_b32 s98, v134, 9
	v_readlane_b32 s99, v135, 9
	v_readlane_b32 s100, v136, 9
	v_readlane_b32 s101, v137, 9
	v_fmac_f32_e32 v73, s98, v150
	v_fmac_f32_e32 v73, s99, v151
	v_fmac_f32_e32 v73, s100, v154
	v_fmac_f32_e32 v73, s101, v155
	v_readlane_b32 s98, v138, 9
	v_readlane_b32 s99, v139, 9
	v_readlane_b32 s100, v140, 9
	v_readlane_b32 s101, v141, 9
	v_fmac_f32_e32 v73, s98, v156
	v_fmac_f32_e32 v73, s99, v157
	v_fmac_f32_e32 v73, s100, v158
	v_fmac_f32_e32 v73, s101, v159
	v_readlane_b32 s98, v126, 10
	v_readlane_b32 s99, v127, 10
	v_readlane_b32 s100, v128, 10
	v_readlane_b32 s101, v129, 10
	v_fma_f32 v74, s98, v142, 0
	v_fmac_f32_e32 v74, s99, v143
	v_fmac_f32_e32 v74, s100, v144
	v_fmac_f32_e32 v74, s101, v145
	v_readlane_b32 s98, v130, 10
	v_readlane_b32 s99, v131, 10
	v_readlane_b32 s100, v132, 10
	v_readlane_b32 s101, v133, 10
	v_fmac_f32_e32 v74, s98, v146
	v_fmac_f32_e32 v74, s99, v147
	v_fmac_f32_e32 v74, s100, v148
	v_fmac_f32_e32 v74, s101, v149
	v_readlane_b32 s98, v134, 10
	v_readlane_b32 s99, v135, 10
	v_readlane_b32 s100, v136, 10
	v_readlane_b32 s101, v137, 10
	v_fmac_f32_e32 v74, s98, v150
	v_fmac_f32_e32 v74, s99, v151
	v_fmac_f32_e32 v74, s100, v154
	v_fmac_f32_e32 v74, s101, v155
	v_readlane_b32 s98, v138, 10
	v_readlane_b32 s99, v139, 10
	v_readlane_b32 s100, v140, 10
	v_readlane_b32 s101, v141, 10
	v_fmac_f32_e32 v74, s98, v156
	v_fmac_f32_e32 v74, s99, v157
	v_fmac_f32_e32 v74, s100, v158
	v_fmac_f32_e32 v74, s101, v159
	v_readlane_b32 s98, v126, 11
	v_readlane_b32 s99, v127, 11
	v_readlane_b32 s100, v128, 11
	v_readlane_b32 s101, v129, 11
	v_fma_f32 v79, s98, v142, 0
	v_fmac_f32_e32 v79, s99, v143
	v_fmac_f32_e32 v79, s100, v144
	v_fmac_f32_e32 v79, s101, v145
	v_readlane_b32 s98, v130, 11
	v_readlane_b32 s99, v131, 11
	v_readlane_b32 s100, v132, 11
	v_readlane_b32 s101, v133, 11
	v_fmac_f32_e32 v79, s98, v146
	v_fmac_f32_e32 v79, s99, v147
	v_fmac_f32_e32 v79, s100, v148
	v_fmac_f32_e32 v79, s101, v149
	v_readlane_b32 s98, v134, 11
	v_readlane_b32 s99, v135, 11
	v_readlane_b32 s100, v136, 11
	v_readlane_b32 s101, v137, 11
	v_fmac_f32_e32 v79, s98, v150
	v_fmac_f32_e32 v79, s99, v151
	v_fmac_f32_e32 v79, s100, v154
	v_fmac_f32_e32 v79, s101, v155
	v_readlane_b32 s98, v138, 11
	v_readlane_b32 s99, v139, 11
	v_readlane_b32 s100, v140, 11
	v_readlane_b32 s101, v141, 11
	v_fmac_f32_e32 v79, s98, v156
	v_fmac_f32_e32 v79, s99, v157
	v_fmac_f32_e32 v79, s100, v158
	v_fmac_f32_e32 v79, s101, v159
	v_readlane_b32 s98, v126, 12
	v_readlane_b32 s99, v127, 12
	v_readlane_b32 s100, v128, 12
	v_readlane_b32 s101, v129, 12
	v_fma_f32 v80, s98, v142, 0
	v_fmac_f32_e32 v80, s99, v143
	v_fmac_f32_e32 v80, s100, v144
	v_fmac_f32_e32 v80, s101, v145
	v_readlane_b32 s98, v130, 12
	v_readlane_b32 s99, v131, 12
	v_readlane_b32 s100, v132, 12
	v_readlane_b32 s101, v133, 12
	v_fmac_f32_e32 v80, s98, v146
	v_fmac_f32_e32 v80, s99, v147
	v_fmac_f32_e32 v80, s100, v148
	v_fmac_f32_e32 v80, s101, v149
	v_readlane_b32 s98, v134, 12
	v_readlane_b32 s99, v135, 12
	v_readlane_b32 s100, v136, 12
	v_readlane_b32 s101, v137, 12
	v_fmac_f32_e32 v80, s98, v150
	v_fmac_f32_e32 v80, s99, v151
	v_fmac_f32_e32 v80, s100, v154
	v_fmac_f32_e32 v80, s101, v155
	v_readlane_b32 s98, v138, 12
	v_readlane_b32 s99, v139, 12
	v_readlane_b32 s100, v140, 12
	v_readlane_b32 s101, v141, 12
	v_fmac_f32_e32 v80, s98, v156
	v_fmac_f32_e32 v80, s99, v157
	v_fmac_f32_e32 v80, s100, v158
	v_fmac_f32_e32 v80, s101, v159
	v_readlane_b32 s98, v126, 13
	v_readlane_b32 s99, v127, 13
	v_readlane_b32 s100, v128, 13
	v_readlane_b32 s101, v129, 13
	v_fma_f32 v81, s98, v142, 0
	v_fmac_f32_e32 v81, s99, v143
	v_fmac_f32_e32 v81, s100, v144
	v_fmac_f32_e32 v81, s101, v145
	v_readlane_b32 s98, v130, 13
	v_readlane_b32 s99, v131, 13
	v_readlane_b32 s100, v132, 13
	v_readlane_b32 s101, v133, 13
	v_fmac_f32_e32 v81, s98, v146
	v_fmac_f32_e32 v81, s99, v147
	v_fmac_f32_e32 v81, s100, v148
	v_fmac_f32_e32 v81, s101, v149
	v_readlane_b32 s98, v134, 13
	v_readlane_b32 s99, v135, 13
	v_readlane_b32 s100, v136, 13
	v_readlane_b32 s101, v137, 13
	v_fmac_f32_e32 v81, s98, v150
	v_fmac_f32_e32 v81, s99, v151
	v_fmac_f32_e32 v81, s100, v154
	v_fmac_f32_e32 v81, s101, v155
	v_readlane_b32 s98, v138, 13
	v_readlane_b32 s99, v139, 13
	v_readlane_b32 s100, v140, 13
	v_readlane_b32 s101, v141, 13
	v_fmac_f32_e32 v81, s98, v156
	v_fmac_f32_e32 v81, s99, v157
	v_fmac_f32_e32 v81, s100, v158
	v_fmac_f32_e32 v81, s101, v159
	v_readlane_b32 s98, v126, 14
	v_readlane_b32 s99, v127, 14
	v_readlane_b32 s100, v128, 14
	v_readlane_b32 s101, v129, 14
	v_fma_f32 v82, s98, v142, 0
	v_fmac_f32_e32 v82, s99, v143
	v_fmac_f32_e32 v82, s100, v144
	v_fmac_f32_e32 v82, s101, v145
	v_readlane_b32 s98, v130, 14
	v_readlane_b32 s99, v131, 14
	v_readlane_b32 s100, v132, 14
	v_readlane_b32 s101, v133, 14
	v_fmac_f32_e32 v82, s98, v146
	v_fmac_f32_e32 v82, s99, v147
	v_fmac_f32_e32 v82, s100, v148
	v_fmac_f32_e32 v82, s101, v149
	v_readlane_b32 s98, v134, 14
	v_readlane_b32 s99, v135, 14
	v_readlane_b32 s100, v136, 14
	v_readlane_b32 s101, v137, 14
	v_fmac_f32_e32 v82, s98, v150
	v_fmac_f32_e32 v82, s99, v151
	v_fmac_f32_e32 v82, s100, v154
	v_fmac_f32_e32 v82, s101, v155
	v_readlane_b32 s98, v138, 14
	v_readlane_b32 s99, v139, 14
	v_readlane_b32 s100, v140, 14
	v_readlane_b32 s101, v141, 14
	v_fmac_f32_e32 v82, s98, v156
	v_fmac_f32_e32 v82, s99, v157
	v_fmac_f32_e32 v82, s100, v158
; __device__ __forceinline__ void cvt_job(int& tbase, const float* __restrict__ src, int Nsrc, int K, bf16_t* __restrict__ dst, int ndst, int mode,
;                                         const float* __restrict__ gain, const float* __restrict__ up_f, const float* __restrict__ up_b, int bi, int nb) {
;     ...
;             for (int j = 0; j < 64; ++j) { const float* wp = src + (size_t)(k0 + j) * Nsrc + 3072 + 16 * dirb; float sacc = 0.f;
; #pragma unroll
;                 for (int r = 0; r < 16; ++r) sacc += wp[r] * upv[r];
;                 v[j] = sacc; }
	v_fmac_f32_e32 v82, s101, v159
	v_readlane_b32 s98, v126, 15
	v_readlane_b32 s99, v127, 15
	v_readlane_b32 s100, v128, 15
	v_readlane_b32 s101, v129, 15
	v_fma_f32 v83, s98, v142, 0
	v_fmac_f32_e32 v83, s99, v143
	v_fmac_f32_e32 v83, s100, v144
	v_fmac_f32_e32 v83, s101, v145
	v_readlane_b32 s98, v130, 15
	v_readlane_b32 s99, v131, 15
	v_readlane_b32 s100, v132, 15
	v_readlane_b32 s101, v133, 15
	v_fmac_f32_e32 v83, s98, v146
	v_fmac_f32_e32 v83, s99, v147
	v_fmac_f32_e32 v83, s100, v148
	v_fmac_f32_e32 v83, s101, v149
	v_readlane_b32 s98, v134, 15
	v_readlane_b32 s99, v135, 15
	v_readlane_b32 s100, v136, 15
	v_readlane_b32 s101, v137, 15
	v_fmac_f32_e32 v83, s98, v150
	v_fmac_f32_e32 v83, s99, v151
	v_fmac_f32_e32 v83, s100, v154
	v_fmac_f32_e32 v83, s101, v155
	v_readlane_b32 s98, v138, 15
	v_readlane_b32 s99, v139, 15
	v_readlane_b32 s100, v140, 15
	v_readlane_b32 s101, v141, 15
	v_fmac_f32_e32 v83, s98, v156
	v_fmac_f32_e32 v83, s99, v157
	v_fmac_f32_e32 v83, s100, v158
	v_fmac_f32_e32 v83, s101, v159
	v_readlane_b32 s98, v126, 16
	v_readlane_b32 s99, v127, 16
	v_readlane_b32 s100, v128, 16
	v_readlane_b32 s101, v129, 16
	v_fma_f32 v84, s98, v142, 0
	v_fmac_f32_e32 v84, s99, v143
	v_fmac_f32_e32 v84, s100, v144
	v_fmac_f32_e32 v84, s101, v145
	v_readlane_b32 s98, v130, 16
	v_readlane_b32 s99, v131, 16
	v_readlane_b32 s100, v132, 16
	v_readlane_b32 s101, v133, 16
	v_fmac_f32_e32 v84, s98, v146
	v_fmac_f32_e32 v84, s99, v147
	v_fmac_f32_e32 v84, s100, v148
	v_fmac_f32_e32 v84, s101, v149
	v_readlane_b32 s98, v134, 16
	v_readlane_b32 s99, v135, 16
	v_readlane_b32 s100, v136, 16
	v_readlane_b32 s101, v137, 16
	v_fmac_f32_e32 v84, s98, v150
	v_fmac_f32_e32 v84, s99, v151
	v_fmac_f32_e32 v84, s100, v154
	v_fmac_f32_e32 v84, s101, v155
	v_readlane_b32 s98, v138, 16
	v_readlane_b32 s99, v139, 16
	v_readlane_b32 s100, v140, 16
	v_readlane_b32 s101, v141, 16
	v_fmac_f32_e32 v84, s98, v156
	v_fmac_f32_e32 v84, s99, v157
	v_fmac_f32_e32 v84, s100, v158
	v_fmac_f32_e32 v84, s101, v159
	v_readlane_b32 s98, v126, 17
	v_readlane_b32 s99, v127, 17
	v_readlane_b32 s100, v128, 17
	v_readlane_b32 s101, v129, 17
	v_fma_f32 v85, s98, v142, 0
	v_fmac_f32_e32 v85, s99, v143
	v_fmac_f32_e32 v85, s100, v144
	v_fmac_f32_e32 v85, s101, v145
	v_readlane_b32 s98, v130, 17
	v_readlane_b32 s99, v131, 17
	v_readlane_b32 s100, v132, 17
	v_readlane_b32 s101, v133, 17
	v_fmac_f32_e32 v85, s98, v146
	v_fmac_f32_e32 v85, s99, v147
	v_fmac_f32_e32 v85, s100, v148
	v_fmac_f32_e32 v85, s101, v149
	v_readlane_b32 s98, v134, 17
	v_readlane_b32 s99, v135, 17
	v_readlane_b32 s100, v136, 17
	v_readlane_b32 s101, v137, 17
	v_fmac_f32_e32 v85, s98, v150
	v_fmac_f32_e32 v85, s99, v151
	v_fmac_f32_e32 v85, s100, v154
	v_fmac_f32_e32 v85, s101, v155
	v_readlane_b32 s98, v138, 17
	v_readlane_b32 s99, v139, 17
	v_readlane_b32 s100, v140, 17
	v_readlane_b32 s101, v141, 17
	v_fmac_f32_e32 v85, s98, v156
	v_fmac_f32_e32 v85, s99, v157
	v_fmac_f32_e32 v85, s100, v158
	v_fmac_f32_e32 v85, s101, v159
	v_readlane_b32 s98, v126, 18
	v_readlane_b32 s99, v127, 18
	v_readlane_b32 s100, v128, 18
	v_readlane_b32 s101, v129, 18
	v_fma_f32 v86, s98, v142, 0
	v_fmac_f32_e32 v86, s99, v143
	v_fmac_f32_e32 v86, s100, v144
	v_fmac_f32_e32 v86, s101, v145
	v_readlane_b32 s98, v130, 18
	v_readlane_b32 s99, v131, 18
	v_readlane_b32 s100, v132, 18
	v_readlane_b32 s101, v133, 18
	v_fmac_f32_e32 v86, s98, v146
	v_fmac_f32_e32 v86, s99, v147
	v_fmac_f32_e32 v86, s100, v148
	v_fmac_f32_e32 v86, s101, v149
	v_readlane_b32 s98, v134, 18
	v_readlane_b32 s99, v135, 18
	v_readlane_b32 s100, v136, 18
	v_readlane_b32 s101, v137, 18
	v_fmac_f32_e32 v86, s98, v150
	v_fmac_f32_e32 v86, s99, v151
	v_fmac_f32_e32 v86, s100, v154
	v_fmac_f32_e32 v86, s101, v155
	v_readlane_b32 s98, v138, 18
	v_readlane_b32 s99, v139, 18
	v_readlane_b32 s100, v140, 18
	v_readlane_b32 s101, v141, 18
	v_fmac_f32_e32 v86, s98, v156
	v_fmac_f32_e32 v86, s99, v157
	v_fmac_f32_e32 v86, s100, v158
	v_fmac_f32_e32 v86, s101, v159
	v_readlane_b32 s98, v126, 19
	v_readlane_b32 s99, v127, 19
	v_readlane_b32 s100, v128, 19
	v_readlane_b32 s101, v129, 19
	v_fma_f32 v87, s98, v142, 0
	v_fmac_f32_e32 v87, s99, v143
	v_fmac_f32_e32 v87, s100, v144
	v_fmac_f32_e32 v87, s101, v145
	v_readlane_b32 s98, v130, 19
	v_readlane_b32 s99, v131, 19
	v_readlane_b32 s100, v132, 19
	v_readlane_b32 s101, v133, 19
	v_fmac_f32_e32 v87, s98, v146
	v_fmac_f32_e32 v87, s99, v147
	v_fmac_f32_e32 v87, s100, v148
	v_fmac_f32_e32 v87, s101, v149
	v_readlane_b32 s98, v134, 19
	v_readlane_b32 s99, v135, 19
	v_readlane_b32 s100, v136, 19
	v_readlane_b32 s101, v137, 19
	v_fmac_f32_e32 v87, s98, v150
	v_fmac_f32_e32 v87, s99, v151
	v_fmac_f32_e32 v87, s100, v154
	v_fmac_f32_e32 v87, s101, v155
	v_readlane_b32 s98, v138, 19
	v_readlane_b32 s99, v139, 19
	v_readlane_b32 s100, v140, 19
	v_readlane_b32 s101, v141, 19
	v_fmac_f32_e32 v87, s98, v156
	v_fmac_f32_e32 v87, s99, v157
	v_fmac_f32_e32 v87, s100, v158
	v_fmac_f32_e32 v87, s101, v159
	v_readlane_b32 s98, v126, 20
	v_readlane_b32 s99, v127, 20
	v_readlane_b32 s100, v128, 20
	v_readlane_b32 s101, v129, 20
	v_fma_f32 v88, s98, v142, 0
	v_fmac_f32_e32 v88, s99, v143
	v_fmac_f32_e32 v88, s100, v144
	v_fmac_f32_e32 v88, s101, v145
	v_readlane_b32 s98, v130, 20
	v_readlane_b32 s99, v131, 20
	v_readlane_b32 s100, v132, 20
	v_readlane_b32 s101, v133, 20
	v_fmac_f32_e32 v88, s98, v146
	v_fmac_f32_e32 v88, s99, v147
	v_fmac_f32_e32 v88, s100, v148
	v_fmac_f32_e32 v88, s101, v149
	v_readlane_b32 s98, v134, 20
	v_readlane_b32 s99, v135, 20
	v_readlane_b32 s100, v136, 20
	v_readlane_b32 s101, v137, 20
	v_fmac_f32_e32 v88, s98, v150
; __device__ __forceinline__ void cvt_job(int& tbase, const float* __restrict__ src, int Nsrc, int K, bf16_t* __restrict__ dst, int ndst, int mode,
;                                         const float* __restrict__ gain, const float* __restrict__ up_f, const float* __restrict__ up_b, int bi, int nb) {
;     ...
;             for (int j = 0; j < 64; ++j) { const float* wp = src + (size_t)(k0 + j) * Nsrc + 3072 + 16 * dirb; float sacc = 0.f;
; #pragma unroll
;                 for (int r = 0; r < 16; ++r) sacc += wp[r] * upv[r];
;                 v[j] = sacc; }
	v_fmac_f32_e32 v88, s99, v151
	v_fmac_f32_e32 v88, s100, v154
	v_fmac_f32_e32 v88, s101, v155
	v_readlane_b32 s98, v138, 20
	v_readlane_b32 s99, v139, 20
	v_readlane_b32 s100, v140, 20
	v_readlane_b32 s101, v141, 20
	v_fmac_f32_e32 v88, s98, v156
	v_fmac_f32_e32 v88, s99, v157
	v_fmac_f32_e32 v88, s100, v158
	v_fmac_f32_e32 v88, s101, v159
	v_readlane_b32 s98, v126, 21
	v_readlane_b32 s99, v127, 21
	v_readlane_b32 s100, v128, 21
	v_readlane_b32 s101, v129, 21
	v_fma_f32 v89, s98, v142, 0
	v_fmac_f32_e32 v89, s99, v143
	v_fmac_f32_e32 v89, s100, v144
	v_fmac_f32_e32 v89, s101, v145
	v_readlane_b32 s98, v130, 21
	v_readlane_b32 s99, v131, 21
	v_readlane_b32 s100, v132, 21
	v_readlane_b32 s101, v133, 21
	v_fmac_f32_e32 v89, s98, v146
	v_fmac_f32_e32 v89, s99, v147
	v_fmac_f32_e32 v89, s100, v148
	v_fmac_f32_e32 v89, s101, v149
	v_readlane_b32 s98, v134, 21
	v_readlane_b32 s99, v135, 21
	v_readlane_b32 s100, v136, 21
	v_readlane_b32 s101, v137, 21
	v_fmac_f32_e32 v89, s98, v150
	v_fmac_f32_e32 v89, s99, v151
	v_fmac_f32_e32 v89, s100, v154
	v_fmac_f32_e32 v89, s101, v155
	v_readlane_b32 s98, v138, 21
	v_readlane_b32 s99, v139, 21
	v_readlane_b32 s100, v140, 21
	v_readlane_b32 s101, v141, 21
	v_fmac_f32_e32 v89, s98, v156
	v_fmac_f32_e32 v89, s99, v157
	v_fmac_f32_e32 v89, s100, v158
	v_fmac_f32_e32 v89, s101, v159
	v_readlane_b32 s98, v126, 22
	v_readlane_b32 s99, v127, 22
	v_readlane_b32 s100, v128, 22
	v_readlane_b32 s101, v129, 22
	v_fma_f32 v90, s98, v142, 0
	v_fmac_f32_e32 v90, s99, v143
	v_fmac_f32_e32 v90, s100, v144
	v_fmac_f32_e32 v90, s101, v145
	v_readlane_b32 s98, v130, 22
	v_readlane_b32 s99, v131, 22
	v_readlane_b32 s100, v132, 22
	v_readlane_b32 s101, v133, 22
	v_fmac_f32_e32 v90, s98, v146
	v_fmac_f32_e32 v90, s99, v147
	v_fmac_f32_e32 v90, s100, v148
	v_fmac_f32_e32 v90, s101, v149
	v_readlane_b32 s98, v134, 22
	v_readlane_b32 s99, v135, 22
	v_readlane_b32 s100, v136, 22
	v_readlane_b32 s101, v137, 22
	v_fmac_f32_e32 v90, s98, v150
	v_fmac_f32_e32 v90, s99, v151
	v_fmac_f32_e32 v90, s100, v154
	v_fmac_f32_e32 v90, s101, v155
	v_readlane_b32 s98, v138, 22
	v_readlane_b32 s99, v139, 22
	v_readlane_b32 s100, v140, 22
	v_readlane_b32 s101, v141, 22
	v_fmac_f32_e32 v90, s98, v156
	v_fmac_f32_e32 v90, s99, v157
	v_fmac_f32_e32 v90, s100, v158
	v_fmac_f32_e32 v90, s101, v159
	v_readlane_b32 s98, v126, 23
	v_readlane_b32 s99, v127, 23
	v_readlane_b32 s100, v128, 23
	v_readlane_b32 s101, v129, 23
	v_fma_f32 v91, s98, v142, 0
	v_fmac_f32_e32 v91, s99, v143
	v_fmac_f32_e32 v91, s100, v144
	v_fmac_f32_e32 v91, s101, v145
	v_readlane_b32 s98, v130, 23
	v_readlane_b32 s99, v131, 23
	v_readlane_b32 s100, v132, 23
	v_readlane_b32 s101, v133, 23
	v_fmac_f32_e32 v91, s98, v146
	v_fmac_f32_e32 v91, s99, v147
	v_fmac_f32_e32 v91, s100, v148
	v_fmac_f32_e32 v91, s101, v149
	v_readlane_b32 s98, v134, 23
	v_readlane_b32 s99, v135, 23
	v_readlane_b32 s100, v136, 23
	v_readlane_b32 s101, v137, 23
	v_fmac_f32_e32 v91, s98, v150
	v_fmac_f32_e32 v91, s99, v151
	v_fmac_f32_e32 v91, s100, v154
	v_fmac_f32_e32 v91, s101, v155
	v_readlane_b32 s98, v138, 23
	v_readlane_b32 s99, v139, 23
	v_readlane_b32 s100, v140, 23
	v_readlane_b32 s101, v141, 23
	v_fmac_f32_e32 v91, s98, v156
	v_fmac_f32_e32 v91, s99, v157
	v_fmac_f32_e32 v91, s100, v158
	v_fmac_f32_e32 v91, s101, v159
	v_readlane_b32 s98, v126, 24
	v_readlane_b32 s99, v127, 24
	v_readlane_b32 s100, v128, 24
	v_readlane_b32 s101, v129, 24
	v_fma_f32 v92, s98, v142, 0
	v_fmac_f32_e32 v92, s99, v143
	v_fmac_f32_e32 v92, s100, v144
	v_fmac_f32_e32 v92, s101, v145
	v_readlane_b32 s98, v130, 24
	v_readlane_b32 s99, v131, 24
	v_readlane_b32 s100, v132, 24
	v_readlane_b32 s101, v133, 24
	v_fmac_f32_e32 v92, s98, v146
	v_fmac_f32_e32 v92, s99, v147
	v_fmac_f32_e32 v92, s100, v148
	v_fmac_f32_e32 v92, s101, v149
	v_readlane_b32 s98, v134, 24
	v_readlane_b32 s99, v135, 24
	v_readlane_b32 s100, v136, 24
	v_readlane_b32 s101, v137, 24
	v_fmac_f32_e32 v92, s98, v150
	v_fmac_f32_e32 v92, s99, v151
	v_fmac_f32_e32 v92, s100, v154
	v_fmac_f32_e32 v92, s101, v155
	v_readlane_b32 s98, v138, 24
	v_readlane_b32 s99, v139, 24
	v_readlane_b32 s100, v140, 24
	v_readlane_b32 s101, v141, 24
	v_fmac_f32_e32 v92, s98, v156
	v_fmac_f32_e32 v92, s99, v157
	v_fmac_f32_e32 v92, s100, v158
	v_fmac_f32_e32 v92, s101, v159
	v_readlane_b32 s98, v126, 25
	v_readlane_b32 s99, v127, 25
	v_readlane_b32 s100, v128, 25
	v_readlane_b32 s101, v129, 25
	v_fma_f32 v93, s98, v142, 0
	v_fmac_f32_e32 v93, s99, v143
	v_fmac_f32_e32 v93, s100, v144
	v_fmac_f32_e32 v93, s101, v145
	v_readlane_b32 s98, v130, 25
	v_readlane_b32 s99, v131, 25
	v_readlane_b32 s100, v132, 25
	v_readlane_b32 s101, v133, 25
	v_fmac_f32_e32 v93, s98, v146
	v_fmac_f32_e32 v93, s99, v147
	v_fmac_f32_e32 v93, s100, v148
	v_fmac_f32_e32 v93, s101, v149
	v_readlane_b32 s98, v134, 25
	v_readlane_b32 s99, v135, 25
	v_readlane_b32 s100, v136, 25
	v_readlane_b32 s101, v137, 25
	v_fmac_f32_e32 v93, s98, v150
	v_fmac_f32_e32 v93, s99, v151
	v_fmac_f32_e32 v93, s100, v154
	v_fmac_f32_e32 v93, s101, v155
	v_readlane_b32 s98, v138, 25
	v_readlane_b32 s99, v139, 25
	v_readlane_b32 s100, v140, 25
	v_readlane_b32 s101, v141, 25
	v_fmac_f32_e32 v93, s98, v156
	v_fmac_f32_e32 v93, s99, v157
	v_fmac_f32_e32 v93, s100, v158
	v_fmac_f32_e32 v93, s101, v159
	v_readlane_b32 s98, v126, 26
	v_readlane_b32 s99, v127, 26
	v_readlane_b32 s100, v128, 26
	v_readlane_b32 s101, v129, 26
	v_fma_f32 v94, s98, v142, 0
	v_fmac_f32_e32 v94, s99, v143
	v_fmac_f32_e32 v94, s100, v144
	v_fmac_f32_e32 v94, s101, v145
	v_readlane_b32 s98, v130, 26
	v_readlane_b32 s99, v131, 26
	v_readlane_b32 s100, v132, 26
; __device__ __forceinline__ void cvt_job(int& tbase, const float* __restrict__ src, int Nsrc, int K, bf16_t* __restrict__ dst, int ndst, int mode,
;                                         const float* __restrict__ gain, const float* __restrict__ up_f, const float* __restrict__ up_b, int bi, int nb) {
;     ...
;             const int dirb = n >> 9, c = n & 511; const float* up = dirb ? up_b : up_f;
;             float upv[16];
; #pragma unroll
;             for (int r = 0; r < 16; ++r) upv[r] = up[r * 512 + c];
; #pragma unroll
;             for (int j = 0; j < 64; ++j) { const float* wp = src + (size_t)(k0 + j) * Nsrc + 3072 + 16 * dirb; float sacc = 0.f;
; #pragma unroll
;                 for (int r = 0; r < 16; ++r) sacc += wp[r] * upv[r];
;                 v[j] = sacc; }
	v_readlane_b32 s101, v133, 26
	v_fmac_f32_e32 v94, s98, v146
	v_fmac_f32_e32 v94, s99, v147
	v_fmac_f32_e32 v94, s100, v148
	v_fmac_f32_e32 v94, s101, v149
	v_readlane_b32 s98, v134, 26
	v_readlane_b32 s99, v135, 26
	v_readlane_b32 s100, v136, 26
	v_readlane_b32 s101, v137, 26
	v_fmac_f32_e32 v94, s98, v150
	v_fmac_f32_e32 v94, s99, v151
	v_fmac_f32_e32 v94, s100, v154
	v_fmac_f32_e32 v94, s101, v155
	v_readlane_b32 s98, v138, 26
	v_readlane_b32 s99, v139, 26
	v_readlane_b32 s100, v140, 26
	v_readlane_b32 s101, v141, 26
	v_fmac_f32_e32 v94, s98, v156
	v_fmac_f32_e32 v94, s99, v157
	v_fmac_f32_e32 v94, s100, v158
	v_fmac_f32_e32 v94, s101, v159
	v_readlane_b32 s98, v126, 27
	v_readlane_b32 s99, v127, 27
	v_readlane_b32 s100, v128, 27
	v_readlane_b32 s101, v129, 27
	v_fma_f32 v95, s98, v142, 0
	v_fmac_f32_e32 v95, s99, v143
	v_fmac_f32_e32 v95, s100, v144
	v_fmac_f32_e32 v95, s101, v145
	v_readlane_b32 s98, v130, 27
	v_readlane_b32 s99, v131, 27
	v_readlane_b32 s100, v132, 27
	v_readlane_b32 s101, v133, 27
	v_fmac_f32_e32 v95, s98, v146
	v_fmac_f32_e32 v95, s99, v147
	v_fmac_f32_e32 v95, s100, v148
	v_fmac_f32_e32 v95, s101, v149
	v_readlane_b32 s98, v134, 27
	v_readlane_b32 s99, v135, 27
	v_readlane_b32 s100, v136, 27
	v_readlane_b32 s101, v137, 27
	v_fmac_f32_e32 v95, s98, v150
	v_fmac_f32_e32 v95, s99, v151
	v_fmac_f32_e32 v95, s100, v154
	v_fmac_f32_e32 v95, s101, v155
	v_readlane_b32 s98, v138, 27
	v_readlane_b32 s99, v139, 27
	v_readlane_b32 s100, v140, 27
	v_readlane_b32 s101, v141, 27
	v_fmac_f32_e32 v95, s98, v156
	v_fmac_f32_e32 v95, s99, v157
	v_fmac_f32_e32 v95, s100, v158
	v_fmac_f32_e32 v95, s101, v159
	v_readlane_b32 s98, v126, 28
	v_readlane_b32 s99, v127, 28
	v_readlane_b32 s100, v128, 28
	v_readlane_b32 s101, v129, 28
	v_fma_f32 v96, s98, v142, 0
	v_fmac_f32_e32 v96, s99, v143
	v_fmac_f32_e32 v96, s100, v144
	v_fmac_f32_e32 v96, s101, v145
	v_readlane_b32 s98, v130, 28
	v_readlane_b32 s99, v131, 28
	v_readlane_b32 s100, v132, 28
	v_readlane_b32 s101, v133, 28
	v_fmac_f32_e32 v96, s98, v146
	v_fmac_f32_e32 v96, s99, v147
	v_fmac_f32_e32 v96, s100, v148
	v_fmac_f32_e32 v96, s101, v149
	v_readlane_b32 s98, v134, 28
	v_readlane_b32 s99, v135, 28
	v_readlane_b32 s100, v136, 28
	v_readlane_b32 s101, v137, 28
	v_fmac_f32_e32 v96, s98, v150
	v_fmac_f32_e32 v96, s99, v151
	v_fmac_f32_e32 v96, s100, v154
	v_fmac_f32_e32 v96, s101, v155
	v_readlane_b32 s98, v138, 28
	v_readlane_b32 s99, v139, 28
	v_readlane_b32 s100, v140, 28
	v_readlane_b32 s101, v141, 28
	v_fmac_f32_e32 v96, s98, v156
	v_fmac_f32_e32 v96, s99, v157
	v_fmac_f32_e32 v96, s100, v158
	v_fmac_f32_e32 v96, s101, v159
	v_readlane_b32 s98, v126, 29
	v_readlane_b32 s99, v127, 29
	v_readlane_b32 s100, v128, 29
	v_readlane_b32 s101, v129, 29
	v_fma_f32 v97, s98, v142, 0
	v_fmac_f32_e32 v97, s99, v143
	v_fmac_f32_e32 v97, s100, v144
	v_fmac_f32_e32 v97, s101, v145
	v_readlane_b32 s98, v130, 29
	v_readlane_b32 s99, v131, 29
	v_readlane_b32 s100, v132, 29
	v_readlane_b32 s101, v133, 29
	v_fmac_f32_e32 v97, s98, v146
	v_fmac_f32_e32 v97, s99, v147
	v_fmac_f32_e32 v97, s100, v148
	v_fmac_f32_e32 v97, s101, v149
	v_readlane_b32 s98, v134, 29
	v_readlane_b32 s99, v135, 29
	v_readlane_b32 s100, v136, 29
	v_readlane_b32 s101, v137, 29
	v_fmac_f32_e32 v97, s98, v150
	v_fmac_f32_e32 v97, s99, v151
	v_fmac_f32_e32 v97, s100, v154
	v_fmac_f32_e32 v97, s101, v155
	v_readlane_b32 s98, v138, 29
	v_readlane_b32 s99, v139, 29
	v_readlane_b32 s100, v140, 29
	v_readlane_b32 s101, v141, 29
	v_fmac_f32_e32 v97, s98, v156
	v_fmac_f32_e32 v97, s99, v157
	v_fmac_f32_e32 v97, s100, v158
	v_fmac_f32_e32 v97, s101, v159
	v_readlane_b32 s98, v126, 30
	v_readlane_b32 s99, v127, 30
	v_readlane_b32 s100, v128, 30
	v_readlane_b32 s101, v129, 30
	v_fma_f32 v98, s98, v142, 0
	v_fmac_f32_e32 v98, s99, v143
	v_fmac_f32_e32 v98, s100, v144
	v_fmac_f32_e32 v98, s101, v145
	v_readlane_b32 s98, v130, 30
	v_readlane_b32 s99, v131, 30
	v_readlane_b32 s100, v132, 30
	v_readlane_b32 s101, v133, 30
	v_fmac_f32_e32 v98, s98, v146
	v_fmac_f32_e32 v98, s99, v147
	v_fmac_f32_e32 v98, s100, v148
	v_fmac_f32_e32 v98, s101, v149
	v_readlane_b32 s98, v134, 30
	v_readlane_b32 s99, v135, 30
	v_readlane_b32 s100, v136, 30
	v_readlane_b32 s101, v137, 30
	v_fmac_f32_e32 v98, s98, v150
	v_fmac_f32_e32 v98, s99, v151
	v_fmac_f32_e32 v98, s100, v154
	v_fmac_f32_e32 v98, s101, v155
	v_readlane_b32 s98, v138, 30
	v_readlane_b32 s99, v139, 30
	v_readlane_b32 s100, v140, 30
	v_readlane_b32 s101, v141, 30
	v_fmac_f32_e32 v98, s98, v156
	v_fmac_f32_e32 v98, s99, v157
	v_fmac_f32_e32 v98, s100, v158
	v_fmac_f32_e32 v98, s101, v159
	v_readlane_b32 s98, v126, 31
	v_readlane_b32 s99, v127, 31
	v_readlane_b32 s100, v128, 31
	v_readlane_b32 s101, v129, 31
	v_fma_f32 v99, s98, v142, 0
	v_fmac_f32_e32 v99, s99, v143
	v_fmac_f32_e32 v99, s100, v144
	v_fmac_f32_e32 v99, s101, v145
	v_readlane_b32 s98, v130, 31
	v_readlane_b32 s99, v131, 31
	v_readlane_b32 s100, v132, 31
	v_readlane_b32 s101, v133, 31
	v_fmac_f32_e32 v99, s98, v146
	v_fmac_f32_e32 v99, s99, v147
	v_fmac_f32_e32 v99, s100, v148
	v_fmac_f32_e32 v99, s101, v149
	v_readlane_b32 s98, v134, 31
	v_readlane_b32 s99, v135, 31
	v_readlane_b32 s100, v136, 31
	v_readlane_b32 s101, v137, 31
	v_fmac_f32_e32 v99, s98, v150
	v_fmac_f32_e32 v99, s99, v151
	v_fmac_f32_e32 v99, s100, v154
	v_fmac_f32_e32 v99, s101, v155
	v_readlane_b32 s98, v138, 31
	v_readlane_b32 s99, v139, 31
	v_readlane_b32 s100, v140, 31
	v_readlane_b32 s101, v141, 31
	v_fmac_f32_e32 v99, s98, v156
	v_fmac_f32_e32 v99, s99, v157
	v_fmac_f32_e32 v99, s100, v158
	v_fmac_f32_e32 v99, s101, v159
	v_readlane_b32 s98, v126, 32
; __device__ __forceinline__ void cvt_job(int& tbase, const float* __restrict__ src, int Nsrc, int K, bf16_t* __restrict__ dst, int ndst, int mode,
;                                         const float* __restrict__ gain, const float* __restrict__ up_f, const float* __restrict__ up_b, int bi, int nb) {
;     ...
;             for (int j = 0; j < 64; ++j) { const float* wp = src + (size_t)(k0 + j) * Nsrc + 3072 + 16 * dirb; float sacc = 0.f;
; #pragma unroll
;                 for (int r = 0; r < 16; ++r) sacc += wp[r] * upv[r];
;                 v[j] = sacc; }
	v_readlane_b32 s99, v127, 32
	v_readlane_b32 s100, v128, 32
	v_readlane_b32 s101, v129, 32
	v_fma_f32 v100, s98, v142, 0
	v_fmac_f32_e32 v100, s99, v143
	v_fmac_f32_e32 v100, s100, v144
	v_fmac_f32_e32 v100, s101, v145
	v_readlane_b32 s98, v130, 32
	v_readlane_b32 s99, v131, 32
	v_readlane_b32 s100, v132, 32
	v_readlane_b32 s101, v133, 32
	v_fmac_f32_e32 v100, s98, v146
	v_fmac_f32_e32 v100, s99, v147
	v_fmac_f32_e32 v100, s100, v148
	v_fmac_f32_e32 v100, s101, v149
	v_readlane_b32 s98, v134, 32
	v_readlane_b32 s99, v135, 32
	v_readlane_b32 s100, v136, 32
	v_readlane_b32 s101, v137, 32
	v_fmac_f32_e32 v100, s98, v150
	v_fmac_f32_e32 v100, s99, v151
	v_fmac_f32_e32 v100, s100, v154
	v_fmac_f32_e32 v100, s101, v155
	v_readlane_b32 s98, v138, 32
	v_readlane_b32 s99, v139, 32
	v_readlane_b32 s100, v140, 32
	v_readlane_b32 s101, v141, 32
	v_fmac_f32_e32 v100, s98, v156
	v_fmac_f32_e32 v100, s99, v157
	v_fmac_f32_e32 v100, s100, v158
	v_fmac_f32_e32 v100, s101, v159
	v_readlane_b32 s98, v126, 33
	v_readlane_b32 s99, v127, 33
	v_readlane_b32 s100, v128, 33
	v_readlane_b32 s101, v129, 33
	v_fma_f32 v101, s98, v142, 0
	v_fmac_f32_e32 v101, s99, v143
	v_fmac_f32_e32 v101, s100, v144
	v_fmac_f32_e32 v101, s101, v145
	v_readlane_b32 s98, v130, 33
	v_readlane_b32 s99, v131, 33
	v_readlane_b32 s100, v132, 33
	v_readlane_b32 s101, v133, 33
	v_fmac_f32_e32 v101, s98, v146
	v_fmac_f32_e32 v101, s99, v147
	v_fmac_f32_e32 v101, s100, v148
	v_fmac_f32_e32 v101, s101, v149
	v_readlane_b32 s98, v134, 33
	v_readlane_b32 s99, v135, 33
	v_readlane_b32 s100, v136, 33
	v_readlane_b32 s101, v137, 33
	v_fmac_f32_e32 v101, s98, v150
	v_fmac_f32_e32 v101, s99, v151
	v_fmac_f32_e32 v101, s100, v154
	v_fmac_f32_e32 v101, s101, v155
	v_readlane_b32 s98, v138, 33
	v_readlane_b32 s99, v139, 33
	v_readlane_b32 s100, v140, 33
	v_readlane_b32 s101, v141, 33
	v_fmac_f32_e32 v101, s98, v156
	v_fmac_f32_e32 v101, s99, v157
	v_fmac_f32_e32 v101, s100, v158
	v_fmac_f32_e32 v101, s101, v159
	v_readlane_b32 s98, v126, 34
	v_readlane_b32 s99, v127, 34
	v_readlane_b32 s100, v128, 34
	v_readlane_b32 s101, v129, 34
	v_fma_f32 v102, s98, v142, 0
	v_fmac_f32_e32 v102, s99, v143
	v_fmac_f32_e32 v102, s100, v144
	v_fmac_f32_e32 v102, s101, v145
	v_readlane_b32 s98, v130, 34
	v_readlane_b32 s99, v131, 34
	v_readlane_b32 s100, v132, 34
	v_readlane_b32 s101, v133, 34
	v_fmac_f32_e32 v102, s98, v146
	v_fmac_f32_e32 v102, s99, v147
	v_fmac_f32_e32 v102, s100, v148
	v_fmac_f32_e32 v102, s101, v149
	v_readlane_b32 s98, v134, 34
	v_readlane_b32 s99, v135, 34
	v_readlane_b32 s100, v136, 34
	v_readlane_b32 s101, v137, 34
	v_fmac_f32_e32 v102, s98, v150
	v_fmac_f32_e32 v102, s99, v151
	v_fmac_f32_e32 v102, s100, v154
	v_fmac_f32_e32 v102, s101, v155
	v_readlane_b32 s98, v138, 34
	v_readlane_b32 s99, v139, 34
	v_readlane_b32 s100, v140, 34
	v_readlane_b32 s101, v141, 34
	v_fmac_f32_e32 v102, s98, v156
	v_fmac_f32_e32 v102, s99, v157
	v_fmac_f32_e32 v102, s100, v158
	v_fmac_f32_e32 v102, s101, v159
	v_readlane_b32 s98, v126, 35
	v_readlane_b32 s99, v127, 35
	v_readlane_b32 s100, v128, 35
	v_readlane_b32 s101, v129, 35
	v_fma_f32 v103, s98, v142, 0
	v_fmac_f32_e32 v103, s99, v143
	v_fmac_f32_e32 v103, s100, v144
	v_fmac_f32_e32 v103, s101, v145
	v_readlane_b32 s98, v130, 35
	v_readlane_b32 s99, v131, 35
	v_readlane_b32 s100, v132, 35
	v_readlane_b32 s101, v133, 35
	v_fmac_f32_e32 v103, s98, v146
	v_fmac_f32_e32 v103, s99, v147
	v_fmac_f32_e32 v103, s100, v148
	v_fmac_f32_e32 v103, s101, v149
	v_readlane_b32 s98, v134, 35
	v_readlane_b32 s99, v135, 35
	v_readlane_b32 s100, v136, 35
	v_readlane_b32 s101, v137, 35
	v_fmac_f32_e32 v103, s98, v150
	v_fmac_f32_e32 v103, s99, v151
	v_fmac_f32_e32 v103, s100, v154
	v_fmac_f32_e32 v103, s101, v155
	v_readlane_b32 s98, v138, 35
	v_readlane_b32 s99, v139, 35
	v_readlane_b32 s100, v140, 35
	v_readlane_b32 s101, v141, 35
	v_fmac_f32_e32 v103, s98, v156
	v_fmac_f32_e32 v103, s99, v157
	v_fmac_f32_e32 v103, s100, v158
	v_fmac_f32_e32 v103, s101, v159
	v_readlane_b32 s98, v126, 36
	v_readlane_b32 s99, v127, 36
	v_readlane_b32 s100, v128, 36
	v_readlane_b32 s101, v129, 36
	v_fma_f32 v104, s98, v142, 0
	v_fmac_f32_e32 v104, s99, v143
	v_fmac_f32_e32 v104, s100, v144
	v_fmac_f32_e32 v104, s101, v145
	v_readlane_b32 s98, v130, 36
	v_readlane_b32 s99, v131, 36
	v_readlane_b32 s100, v132, 36
	v_readlane_b32 s101, v133, 36
	v_fmac_f32_e32 v104, s98, v146
	v_fmac_f32_e32 v104, s99, v147
	v_fmac_f32_e32 v104, s100, v148
	v_fmac_f32_e32 v104, s101, v149
	v_readlane_b32 s98, v134, 36
	v_readlane_b32 s99, v135, 36
	v_readlane_b32 s100, v136, 36
	v_readlane_b32 s101, v137, 36
	v_fmac_f32_e32 v104, s98, v150
	v_fmac_f32_e32 v104, s99, v151
	v_fmac_f32_e32 v104, s100, v154
	v_fmac_f32_e32 v104, s101, v155
	v_readlane_b32 s98, v138, 36
	v_readlane_b32 s99, v139, 36
	v_readlane_b32 s100, v140, 36
	v_readlane_b32 s101, v141, 36
	v_fmac_f32_e32 v104, s98, v156
	v_fmac_f32_e32 v104, s99, v157
	v_fmac_f32_e32 v104, s100, v158
	v_fmac_f32_e32 v104, s101, v159
	v_readlane_b32 s98, v126, 37
	v_readlane_b32 s99, v127, 37
	v_readlane_b32 s100, v128, 37
	v_readlane_b32 s101, v129, 37
	v_fma_f32 v105, s98, v142, 0
	v_fmac_f32_e32 v105, s99, v143
	v_fmac_f32_e32 v105, s100, v144
	v_fmac_f32_e32 v105, s101, v145
	v_readlane_b32 s98, v130, 37
	v_readlane_b32 s99, v131, 37
	v_readlane_b32 s100, v132, 37
	v_readlane_b32 s101, v133, 37
	v_fmac_f32_e32 v105, s98, v146
	v_fmac_f32_e32 v105, s99, v147
	v_fmac_f32_e32 v105, s100, v148
	v_fmac_f32_e32 v105, s101, v149
	v_readlane_b32 s98, v134, 37
	v_readlane_b32 s99, v135, 37
	v_readlane_b32 s100, v136, 37
	v_readlane_b32 s101, v137, 37
; __device__ __forceinline__ void cvt_job(int& tbase, const float* __restrict__ src, int Nsrc, int K, bf16_t* __restrict__ dst, int ndst, int mode,
;                                         const float* __restrict__ gain, const float* __restrict__ up_f, const float* __restrict__ up_b, int bi, int nb) {
;     ...
;             const int dirb = n >> 9, c = n & 511; const float* up = dirb ? up_b : up_f;
;             float upv[16];
; #pragma unroll
;             for (int r = 0; r < 16; ++r) upv[r] = up[r * 512 + c];
; #pragma unroll
;             for (int j = 0; j < 64; ++j) { const float* wp = src + (size_t)(k0 + j) * Nsrc + 3072 + 16 * dirb; float sacc = 0.f;
; #pragma unroll
;                 for (int r = 0; r < 16; ++r) sacc += wp[r] * upv[r];
;                 v[j] = sacc; }
	v_fmac_f32_e32 v105, s98, v150
	v_fmac_f32_e32 v105, s99, v151
	v_fmac_f32_e32 v105, s100, v154
	v_fmac_f32_e32 v105, s101, v155
	v_readlane_b32 s98, v138, 37
	v_readlane_b32 s99, v139, 37
	v_readlane_b32 s100, v140, 37
	v_readlane_b32 s101, v141, 37
	v_fmac_f32_e32 v105, s98, v156
	v_fmac_f32_e32 v105, s99, v157
	v_fmac_f32_e32 v105, s100, v158
	v_fmac_f32_e32 v105, s101, v159
	v_readlane_b32 s98, v126, 38
	v_readlane_b32 s99, v127, 38
	v_readlane_b32 s100, v128, 38
	v_readlane_b32 s101, v129, 38
	v_fma_f32 v106, s98, v142, 0
	v_fmac_f32_e32 v106, s99, v143
	v_fmac_f32_e32 v106, s100, v144
	v_fmac_f32_e32 v106, s101, v145
	v_readlane_b32 s98, v130, 38
	v_readlane_b32 s99, v131, 38
	v_readlane_b32 s100, v132, 38
	v_readlane_b32 s101, v133, 38
	v_fmac_f32_e32 v106, s98, v146
	v_fmac_f32_e32 v106, s99, v147
	v_fmac_f32_e32 v106, s100, v148
	v_fmac_f32_e32 v106, s101, v149
	v_readlane_b32 s98, v134, 38
	v_readlane_b32 s99, v135, 38
	v_readlane_b32 s100, v136, 38
	v_readlane_b32 s101, v137, 38
	v_fmac_f32_e32 v106, s98, v150
	v_fmac_f32_e32 v106, s99, v151
	v_fmac_f32_e32 v106, s100, v154
	v_fmac_f32_e32 v106, s101, v155
	v_readlane_b32 s98, v138, 38
	v_readlane_b32 s99, v139, 38
	v_readlane_b32 s100, v140, 38
	v_readlane_b32 s101, v141, 38
	v_fmac_f32_e32 v106, s98, v156
	v_fmac_f32_e32 v106, s99, v157
	v_fmac_f32_e32 v106, s100, v158
	v_fmac_f32_e32 v106, s101, v159
	v_readlane_b32 s98, v126, 39
	v_readlane_b32 s99, v127, 39
	v_readlane_b32 s100, v128, 39
	v_readlane_b32 s101, v129, 39
	v_fma_f32 v107, s98, v142, 0
	v_fmac_f32_e32 v107, s99, v143
	v_fmac_f32_e32 v107, s100, v144
	v_fmac_f32_e32 v107, s101, v145
	v_readlane_b32 s98, v130, 39
	v_readlane_b32 s99, v131, 39
	v_readlane_b32 s100, v132, 39
	v_readlane_b32 s101, v133, 39
	v_fmac_f32_e32 v107, s98, v146
	v_fmac_f32_e32 v107, s99, v147
	v_fmac_f32_e32 v107, s100, v148
	v_fmac_f32_e32 v107, s101, v149
	v_readlane_b32 s98, v134, 39
	v_readlane_b32 s99, v135, 39
	v_readlane_b32 s100, v136, 39
	v_readlane_b32 s101, v137, 39
	v_fmac_f32_e32 v107, s98, v150
	v_fmac_f32_e32 v107, s99, v151
	v_fmac_f32_e32 v107, s100, v154
	v_fmac_f32_e32 v107, s101, v155
	v_readlane_b32 s98, v138, 39
	v_readlane_b32 s99, v139, 39
	v_readlane_b32 s100, v140, 39
	v_readlane_b32 s101, v141, 39
	v_fmac_f32_e32 v107, s98, v156
	v_fmac_f32_e32 v107, s99, v157
	v_fmac_f32_e32 v107, s100, v158
	v_fmac_f32_e32 v107, s101, v159
	v_readlane_b32 s98, v126, 40
	v_readlane_b32 s99, v127, 40
	v_readlane_b32 s100, v128, 40
	v_readlane_b32 s101, v129, 40
	v_fma_f32 v108, s98, v142, 0
	v_fmac_f32_e32 v108, s99, v143
	v_fmac_f32_e32 v108, s100, v144
	v_fmac_f32_e32 v108, s101, v145
	v_readlane_b32 s98, v130, 40
	v_readlane_b32 s99, v131, 40
	v_readlane_b32 s100, v132, 40
	v_readlane_b32 s101, v133, 40
	v_fmac_f32_e32 v108, s98, v146
	v_fmac_f32_e32 v108, s99, v147
	v_fmac_f32_e32 v108, s100, v148
	v_fmac_f32_e32 v108, s101, v149
	v_readlane_b32 s98, v134, 40
	v_readlane_b32 s99, v135, 40
	v_readlane_b32 s100, v136, 40
	v_readlane_b32 s101, v137, 40
	v_fmac_f32_e32 v108, s98, v150
	v_fmac_f32_e32 v108, s99, v151
	v_fmac_f32_e32 v108, s100, v154
	v_fmac_f32_e32 v108, s101, v155
	v_readlane_b32 s98, v138, 40
	v_readlane_b32 s99, v139, 40
	v_readlane_b32 s100, v140, 40
	v_readlane_b32 s101, v141, 40
	v_fmac_f32_e32 v108, s98, v156
	v_fmac_f32_e32 v108, s99, v157
	v_fmac_f32_e32 v108, s100, v158
	v_fmac_f32_e32 v108, s101, v159
	v_readlane_b32 s98, v126, 41
	v_readlane_b32 s99, v127, 41
	v_readlane_b32 s100, v128, 41
	v_readlane_b32 s101, v129, 41
	v_fma_f32 v109, s98, v142, 0
	v_fmac_f32_e32 v109, s99, v143
	v_fmac_f32_e32 v109, s100, v144
	v_fmac_f32_e32 v109, s101, v145
	v_readlane_b32 s98, v130, 41
	v_readlane_b32 s99, v131, 41
	v_readlane_b32 s100, v132, 41
	v_readlane_b32 s101, v133, 41
	v_fmac_f32_e32 v109, s98, v146
	v_fmac_f32_e32 v109, s99, v147
	v_fmac_f32_e32 v109, s100, v148
	v_fmac_f32_e32 v109, s101, v149
	v_readlane_b32 s98, v134, 41
	v_readlane_b32 s99, v135, 41
	v_readlane_b32 s100, v136, 41
	v_readlane_b32 s101, v137, 41
	v_fmac_f32_e32 v109, s98, v150
	v_fmac_f32_e32 v109, s99, v151
	v_fmac_f32_e32 v109, s100, v154
	v_fmac_f32_e32 v109, s101, v155
	v_readlane_b32 s98, v138, 41
	v_readlane_b32 s99, v139, 41
	v_readlane_b32 s100, v140, 41
	v_readlane_b32 s101, v141, 41
	v_fmac_f32_e32 v109, s98, v156
	v_fmac_f32_e32 v109, s99, v157
	v_fmac_f32_e32 v109, s100, v158
	v_fmac_f32_e32 v109, s101, v159
	v_readlane_b32 s98, v126, 42
	v_readlane_b32 s99, v127, 42
	v_readlane_b32 s100, v128, 42
	v_readlane_b32 s101, v129, 42
	v_fma_f32 v110, s98, v142, 0
	v_fmac_f32_e32 v110, s99, v143
	v_fmac_f32_e32 v110, s100, v144
	v_fmac_f32_e32 v110, s101, v145
	v_readlane_b32 s98, v130, 42
	v_readlane_b32 s99, v131, 42
	v_readlane_b32 s100, v132, 42
	v_readlane_b32 s101, v133, 42
	v_fmac_f32_e32 v110, s98, v146
	v_fmac_f32_e32 v110, s99, v147
	v_fmac_f32_e32 v110, s100, v148
	v_fmac_f32_e32 v110, s101, v149
	v_readlane_b32 s98, v134, 42
	v_readlane_b32 s99, v135, 42
	v_readlane_b32 s100, v136, 42
	v_readlane_b32 s101, v137, 42
	v_fmac_f32_e32 v110, s98, v150
	v_fmac_f32_e32 v110, s99, v151
	v_fmac_f32_e32 v110, s100, v154
	v_fmac_f32_e32 v110, s101, v155
	v_readlane_b32 s98, v138, 42
	v_readlane_b32 s99, v139, 42
	v_readlane_b32 s100, v140, 42
	v_readlane_b32 s101, v141, 42
	v_fmac_f32_e32 v110, s98, v156
	v_fmac_f32_e32 v110, s99, v157
	v_fmac_f32_e32 v110, s100, v158
	v_fmac_f32_e32 v110, s101, v159
	v_readlane_b32 s98, v126, 43
	v_readlane_b32 s99, v127, 43
	v_readlane_b32 s100, v128, 43
	v_readlane_b32 s101, v129, 43
	v_fma_f32 v111, s98, v142, 0
	v_fmac_f32_e32 v111, s99, v143
	v_fmac_f32_e32 v111, s100, v144
; __device__ __forceinline__ void cvt_job(int& tbase, const float* __restrict__ src, int Nsrc, int K, bf16_t* __restrict__ dst, int ndst, int mode,
;                                         const float* __restrict__ gain, const float* __restrict__ up_f, const float* __restrict__ up_b, int bi, int nb) {
;     ...
;             for (int j = 0; j < 64; ++j) { const float* wp = src + (size_t)(k0 + j) * Nsrc + 3072 + 16 * dirb; float sacc = 0.f;
; #pragma unroll
;                 for (int r = 0; r < 16; ++r) sacc += wp[r] * upv[r];
;                 v[j] = sacc; }
	v_fmac_f32_e32 v111, s101, v145
	v_readlane_b32 s98, v130, 43
	v_readlane_b32 s99, v131, 43
	v_readlane_b32 s100, v132, 43
	v_readlane_b32 s101, v133, 43
	v_fmac_f32_e32 v111, s98, v146
	v_fmac_f32_e32 v111, s99, v147
	v_fmac_f32_e32 v111, s100, v148
	v_fmac_f32_e32 v111, s101, v149
	v_readlane_b32 s98, v134, 43
	v_readlane_b32 s99, v135, 43
	v_readlane_b32 s100, v136, 43
	v_readlane_b32 s101, v137, 43
	v_fmac_f32_e32 v111, s98, v150
	v_fmac_f32_e32 v111, s99, v151
	v_fmac_f32_e32 v111, s100, v154
	v_fmac_f32_e32 v111, s101, v155
	v_readlane_b32 s98, v138, 43
	v_readlane_b32 s99, v139, 43
	v_readlane_b32 s100, v140, 43
	v_readlane_b32 s101, v141, 43
	v_fmac_f32_e32 v111, s98, v156
	v_fmac_f32_e32 v111, s99, v157
	v_fmac_f32_e32 v111, s100, v158
	v_fmac_f32_e32 v111, s101, v159
	v_readlane_b32 s98, v126, 44
	v_readlane_b32 s99, v127, 44
	v_readlane_b32 s100, v128, 44
	v_readlane_b32 s101, v129, 44
	v_fma_f32 v112, s98, v142, 0
	v_fmac_f32_e32 v112, s99, v143
	v_fmac_f32_e32 v112, s100, v144
	v_fmac_f32_e32 v112, s101, v145
	v_readlane_b32 s98, v130, 44
	v_readlane_b32 s99, v131, 44
	v_readlane_b32 s100, v132, 44
	v_readlane_b32 s101, v133, 44
	v_fmac_f32_e32 v112, s98, v146
	v_fmac_f32_e32 v112, s99, v147
	v_fmac_f32_e32 v112, s100, v148
	v_fmac_f32_e32 v112, s101, v149
	v_readlane_b32 s98, v134, 44
	v_readlane_b32 s99, v135, 44
	v_readlane_b32 s100, v136, 44
	v_readlane_b32 s101, v137, 44
	v_fmac_f32_e32 v112, s98, v150
	v_fmac_f32_e32 v112, s99, v151
	v_fmac_f32_e32 v112, s100, v154
	v_fmac_f32_e32 v112, s101, v155
	v_readlane_b32 s98, v138, 44
	v_readlane_b32 s99, v139, 44
	v_readlane_b32 s100, v140, 44
	v_readlane_b32 s101, v141, 44
	v_fmac_f32_e32 v112, s98, v156
	v_fmac_f32_e32 v112, s99, v157
	v_fmac_f32_e32 v112, s100, v158
	v_fmac_f32_e32 v112, s101, v159
	v_readlane_b32 s98, v126, 45
	v_readlane_b32 s99, v127, 45
	v_readlane_b32 s100, v128, 45
	v_readlane_b32 s101, v129, 45
	v_fma_f32 v113, s98, v142, 0
	v_fmac_f32_e32 v113, s99, v143
	v_fmac_f32_e32 v113, s100, v144
	v_fmac_f32_e32 v113, s101, v145
	v_readlane_b32 s98, v130, 45
	v_readlane_b32 s99, v131, 45
	v_readlane_b32 s100, v132, 45
	v_readlane_b32 s101, v133, 45
	v_fmac_f32_e32 v113, s98, v146
	v_fmac_f32_e32 v113, s99, v147
	v_fmac_f32_e32 v113, s100, v148
	v_fmac_f32_e32 v113, s101, v149
	v_readlane_b32 s98, v134, 45
	v_readlane_b32 s99, v135, 45
	v_readlane_b32 s100, v136, 45
	v_readlane_b32 s101, v137, 45
	v_fmac_f32_e32 v113, s98, v150
	v_fmac_f32_e32 v113, s99, v151
	v_fmac_f32_e32 v113, s100, v154
	v_fmac_f32_e32 v113, s101, v155
	v_readlane_b32 s98, v138, 45
	v_readlane_b32 s99, v139, 45
	v_readlane_b32 s100, v140, 45
	v_readlane_b32 s101, v141, 45
	v_fmac_f32_e32 v113, s98, v156
	v_fmac_f32_e32 v113, s99, v157
	v_fmac_f32_e32 v113, s100, v158
	v_fmac_f32_e32 v113, s101, v159
	v_readlane_b32 s98, v126, 46
	v_readlane_b32 s99, v127, 46
	v_readlane_b32 s100, v128, 46
	v_readlane_b32 s101, v129, 46
	v_fma_f32 v114, s98, v142, 0
	v_fmac_f32_e32 v114, s99, v143
	v_fmac_f32_e32 v114, s100, v144
	v_fmac_f32_e32 v114, s101, v145
	v_readlane_b32 s98, v130, 46
	v_readlane_b32 s99, v131, 46
	v_readlane_b32 s100, v132, 46
	v_readlane_b32 s101, v133, 46
	v_fmac_f32_e32 v114, s98, v146
	v_fmac_f32_e32 v114, s99, v147
	v_fmac_f32_e32 v114, s100, v148
	v_fmac_f32_e32 v114, s101, v149
	v_readlane_b32 s98, v134, 46
	v_readlane_b32 s99, v135, 46
	v_readlane_b32 s100, v136, 46
	v_readlane_b32 s101, v137, 46
	v_fmac_f32_e32 v114, s98, v150
	v_fmac_f32_e32 v114, s99, v151
	v_fmac_f32_e32 v114, s100, v154
	v_fmac_f32_e32 v114, s101, v155
	v_readlane_b32 s98, v138, 46
	v_readlane_b32 s99, v139, 46
	v_readlane_b32 s100, v140, 46
	v_readlane_b32 s101, v141, 46
	v_fmac_f32_e32 v114, s98, v156
	v_fmac_f32_e32 v114, s99, v157
	v_fmac_f32_e32 v114, s100, v158
	v_fmac_f32_e32 v114, s101, v159
	v_readlane_b32 s98, v126, 47
	v_readlane_b32 s99, v127, 47
	v_readlane_b32 s100, v128, 47
	v_readlane_b32 s101, v129, 47
	v_fma_f32 v115, s98, v142, 0
	v_fmac_f32_e32 v115, s99, v143
	v_fmac_f32_e32 v115, s100, v144
	v_fmac_f32_e32 v115, s101, v145
	v_readlane_b32 s98, v130, 47
	v_readlane_b32 s99, v131, 47
	v_readlane_b32 s100, v132, 47
	v_readlane_b32 s101, v133, 47
	v_fmac_f32_e32 v115, s98, v146
	v_fmac_f32_e32 v115, s99, v147
	v_fmac_f32_e32 v115, s100, v148
	v_fmac_f32_e32 v115, s101, v149
	v_readlane_b32 s98, v134, 47
	v_readlane_b32 s99, v135, 47
	v_readlane_b32 s100, v136, 47
	v_readlane_b32 s101, v137, 47
	v_fmac_f32_e32 v115, s98, v150
	v_fmac_f32_e32 v115, s99, v151
	v_fmac_f32_e32 v115, s100, v154
	v_fmac_f32_e32 v115, s101, v155
	v_readlane_b32 s98, v138, 47
	v_readlane_b32 s99, v139, 47
	v_readlane_b32 s100, v140, 47
	v_readlane_b32 s101, v141, 47
	v_fmac_f32_e32 v115, s98, v156
	v_fmac_f32_e32 v115, s99, v157
	v_fmac_f32_e32 v115, s100, v158
	v_fmac_f32_e32 v115, s101, v159
	v_readlane_b32 s98, v126, 48
	v_readlane_b32 s99, v127, 48
	v_readlane_b32 s100, v128, 48
	v_readlane_b32 s101, v129, 48
	v_fma_f32 v116, s98, v142, 0
	v_fmac_f32_e32 v116, s99, v143
	v_fmac_f32_e32 v116, s100, v144
	v_fmac_f32_e32 v116, s101, v145
	v_readlane_b32 s98, v130, 48
	v_readlane_b32 s99, v131, 48
	v_readlane_b32 s100, v132, 48
	v_readlane_b32 s101, v133, 48
	v_fmac_f32_e32 v116, s98, v146
	v_fmac_f32_e32 v116, s99, v147
	v_fmac_f32_e32 v116, s100, v148
	v_fmac_f32_e32 v116, s101, v149
	v_readlane_b32 s98, v134, 48
	v_readlane_b32 s99, v135, 48
	v_readlane_b32 s100, v136, 48
	v_readlane_b32 s101, v137, 48
	v_fmac_f32_e32 v116, s98, v150
	v_fmac_f32_e32 v116, s99, v151
	v_fmac_f32_e32 v116, s100, v154
	v_fmac_f32_e32 v116, s101, v155
	v_readlane_b32 s98, v138, 48
	v_readlane_b32 s99, v139, 48
; __device__ __forceinline__ void cvt_job(int& tbase, const float* __restrict__ src, int Nsrc, int K, bf16_t* __restrict__ dst, int ndst, int mode,
;                                         const float* __restrict__ gain, const float* __restrict__ up_f, const float* __restrict__ up_b, int bi, int nb) {
;     ...
;             float upv[16];
; #pragma unroll
;             for (int r = 0; r < 16; ++r) upv[r] = up[r * 512 + c];
; #pragma unroll
;             for (int j = 0; j < 64; ++j) { const float* wp = src + (size_t)(k0 + j) * Nsrc + 3072 + 16 * dirb; float sacc = 0.f;
; #pragma unroll
;                 for (int r = 0; r < 16; ++r) sacc += wp[r] * upv[r];
;                 v[j] = sacc; }
	v_readlane_b32 s100, v140, 48
	v_readlane_b32 s101, v141, 48
	v_fmac_f32_e32 v116, s98, v156
	v_fmac_f32_e32 v116, s99, v157
	v_fmac_f32_e32 v116, s100, v158
	v_fmac_f32_e32 v116, s101, v159
	v_readlane_b32 s98, v126, 49
	v_readlane_b32 s99, v127, 49
	v_readlane_b32 s100, v128, 49
	v_readlane_b32 s101, v129, 49
	v_fma_f32 v117, s98, v142, 0
	v_fmac_f32_e32 v117, s99, v143
	v_fmac_f32_e32 v117, s100, v144
	v_fmac_f32_e32 v117, s101, v145
	v_readlane_b32 s98, v130, 49
	v_readlane_b32 s99, v131, 49
	v_readlane_b32 s100, v132, 49
	v_readlane_b32 s101, v133, 49
	v_fmac_f32_e32 v117, s98, v146
	v_fmac_f32_e32 v117, s99, v147
	v_fmac_f32_e32 v117, s100, v148
	v_fmac_f32_e32 v117, s101, v149
	v_readlane_b32 s98, v134, 49
	v_readlane_b32 s99, v135, 49
	v_readlane_b32 s100, v136, 49
	v_readlane_b32 s101, v137, 49
	v_fmac_f32_e32 v117, s98, v150
	v_fmac_f32_e32 v117, s99, v151
	v_fmac_f32_e32 v117, s100, v154
	v_fmac_f32_e32 v117, s101, v155
	v_readlane_b32 s98, v138, 49
	v_readlane_b32 s99, v139, 49
	v_readlane_b32 s100, v140, 49
	v_readlane_b32 s101, v141, 49
	v_fmac_f32_e32 v117, s98, v156
	v_fmac_f32_e32 v117, s99, v157
	v_fmac_f32_e32 v117, s100, v158
	v_fmac_f32_e32 v117, s101, v159
	v_readlane_b32 s98, v126, 50
	v_readlane_b32 s99, v127, 50
	v_readlane_b32 s100, v128, 50
	v_readlane_b32 s101, v129, 50
	v_fma_f32 v118, s98, v142, 0
	v_fmac_f32_e32 v118, s99, v143
	v_fmac_f32_e32 v118, s100, v144
	v_fmac_f32_e32 v118, s101, v145
	v_readlane_b32 s98, v130, 50
	v_readlane_b32 s99, v131, 50
	v_readlane_b32 s100, v132, 50
	v_readlane_b32 s101, v133, 50
	v_fmac_f32_e32 v118, s98, v146
	v_fmac_f32_e32 v118, s99, v147
	v_fmac_f32_e32 v118, s100, v148
	v_fmac_f32_e32 v118, s101, v149
	v_readlane_b32 s98, v134, 50
	v_readlane_b32 s99, v135, 50
	v_readlane_b32 s100, v136, 50
	v_readlane_b32 s101, v137, 50
	v_fmac_f32_e32 v118, s98, v150
	v_fmac_f32_e32 v118, s99, v151
	v_fmac_f32_e32 v118, s100, v154
	v_fmac_f32_e32 v118, s101, v155
	v_readlane_b32 s98, v138, 50
	v_readlane_b32 s99, v139, 50
	v_readlane_b32 s100, v140, 50
	v_readlane_b32 s101, v141, 50
	v_fmac_f32_e32 v118, s98, v156
	v_fmac_f32_e32 v118, s99, v157
	v_fmac_f32_e32 v118, s100, v158
	v_fmac_f32_e32 v118, s101, v159
	v_readlane_b32 s98, v126, 51
	v_readlane_b32 s99, v127, 51
	v_readlane_b32 s100, v128, 51
	v_readlane_b32 s101, v129, 51
	v_fma_f32 v119, s98, v142, 0
	v_fmac_f32_e32 v119, s99, v143
	v_fmac_f32_e32 v119, s100, v144
	v_fmac_f32_e32 v119, s101, v145
	v_readlane_b32 s98, v130, 51
	v_readlane_b32 s99, v131, 51
	v_readlane_b32 s100, v132, 51
	v_readlane_b32 s101, v133, 51
	v_fmac_f32_e32 v119, s98, v146
	v_fmac_f32_e32 v119, s99, v147
	v_fmac_f32_e32 v119, s100, v148
	v_fmac_f32_e32 v119, s101, v149
	v_readlane_b32 s98, v134, 51
	v_readlane_b32 s99, v135, 51
	v_readlane_b32 s100, v136, 51
	v_readlane_b32 s101, v137, 51
	v_fmac_f32_e32 v119, s98, v150
	v_fmac_f32_e32 v119, s99, v151
	v_fmac_f32_e32 v119, s100, v154
	v_fmac_f32_e32 v119, s101, v155
	v_readlane_b32 s98, v138, 51
	v_readlane_b32 s99, v139, 51
	v_readlane_b32 s100, v140, 51
	v_readlane_b32 s101, v141, 51
	v_fmac_f32_e32 v119, s98, v156
	v_fmac_f32_e32 v119, s99, v157
	v_fmac_f32_e32 v119, s100, v158
	v_fmac_f32_e32 v119, s101, v159
	v_readlane_b32 s98, v126, 52
	v_readlane_b32 s99, v127, 52
	v_readlane_b32 s100, v128, 52
	v_readlane_b32 s101, v129, 52
	v_fma_f32 v120, s98, v142, 0
	v_fmac_f32_e32 v120, s99, v143
	v_fmac_f32_e32 v120, s100, v144
	v_fmac_f32_e32 v120, s101, v145
	v_readlane_b32 s98, v130, 52
	v_readlane_b32 s99, v131, 52
	v_readlane_b32 s100, v132, 52
	v_readlane_b32 s101, v133, 52
	v_fmac_f32_e32 v120, s98, v146
	v_fmac_f32_e32 v120, s99, v147
	v_fmac_f32_e32 v120, s100, v148
	v_fmac_f32_e32 v120, s101, v149
	v_readlane_b32 s98, v134, 52
	v_readlane_b32 s99, v135, 52
	v_readlane_b32 s100, v136, 52
	v_readlane_b32 s101, v137, 52
	v_fmac_f32_e32 v120, s98, v150
	v_fmac_f32_e32 v120, s99, v151
	v_fmac_f32_e32 v120, s100, v154
	v_fmac_f32_e32 v120, s101, v155
	v_readlane_b32 s98, v138, 52
	v_readlane_b32 s99, v139, 52
	v_readlane_b32 s100, v140, 52
	v_readlane_b32 s101, v141, 52
	v_fmac_f32_e32 v120, s98, v156
	v_fmac_f32_e32 v120, s99, v157
	v_fmac_f32_e32 v120, s100, v158
	v_fmac_f32_e32 v120, s101, v159
	v_readlane_b32 s98, v126, 53
	v_readlane_b32 s99, v127, 53
	v_readlane_b32 s100, v128, 53
	v_readlane_b32 s101, v129, 53
	v_fma_f32 v121, s98, v142, 0
	v_fmac_f32_e32 v121, s99, v143
	v_fmac_f32_e32 v121, s100, v144
	v_fmac_f32_e32 v121, s101, v145
	v_readlane_b32 s98, v130, 53
	v_readlane_b32 s99, v131, 53
	v_readlane_b32 s100, v132, 53
	v_readlane_b32 s101, v133, 53
	v_fmac_f32_e32 v121, s98, v146
	v_fmac_f32_e32 v121, s99, v147
	v_fmac_f32_e32 v121, s100, v148
	v_fmac_f32_e32 v121, s101, v149
	v_readlane_b32 s98, v134, 53
	v_readlane_b32 s99, v135, 53
	v_readlane_b32 s100, v136, 53
	v_readlane_b32 s101, v137, 53
	v_fmac_f32_e32 v121, s98, v150
	v_fmac_f32_e32 v121, s99, v151
	v_fmac_f32_e32 v121, s100, v154
	v_fmac_f32_e32 v121, s101, v155
	v_readlane_b32 s98, v138, 53
	v_readlane_b32 s99, v139, 53
	v_readlane_b32 s100, v140, 53
	v_readlane_b32 s101, v141, 53
	v_fmac_f32_e32 v121, s98, v156
	v_fmac_f32_e32 v121, s99, v157
	v_fmac_f32_e32 v121, s100, v158
	v_fmac_f32_e32 v121, s101, v159
	v_readlane_b32 s98, v126, 54
	v_readlane_b32 s99, v127, 54
	v_readlane_b32 s100, v128, 54
	v_readlane_b32 s101, v129, 54
	v_fma_f32 v122, s98, v142, 0
	v_fmac_f32_e32 v122, s99, v143
	v_fmac_f32_e32 v122, s100, v144
	v_fmac_f32_e32 v122, s101, v145
	v_readlane_b32 s98, v130, 54
	v_readlane_b32 s99, v131, 54
	v_readlane_b32 s100, v132, 54
	v_readlane_b32 s101, v133, 54
	v_fmac_f32_e32 v122, s98, v146
; __device__ __forceinline__ void cvt_job(int& tbase, const float* __restrict__ src, int Nsrc, int K, bf16_t* __restrict__ dst, int ndst, int mode,
;                                         const float* __restrict__ gain, const float* __restrict__ up_f, const float* __restrict__ up_b, int bi, int nb) {
;     ...
;             for (int j = 0; j < 64; ++j) { const float* wp = src + (size_t)(k0 + j) * Nsrc + 3072 + 16 * dirb; float sacc = 0.f;
; #pragma unroll
;                 for (int r = 0; r < 16; ++r) sacc += wp[r] * upv[r];
;                 v[j] = sacc; }
	v_fmac_f32_e32 v122, s99, v147
	v_fmac_f32_e32 v122, s100, v148
	v_fmac_f32_e32 v122, s101, v149
	v_readlane_b32 s98, v134, 54
	v_readlane_b32 s99, v135, 54
	v_readlane_b32 s100, v136, 54
	v_readlane_b32 s101, v137, 54
	v_fmac_f32_e32 v122, s98, v150
	v_fmac_f32_e32 v122, s99, v151
	v_fmac_f32_e32 v122, s100, v154
	v_fmac_f32_e32 v122, s101, v155
	v_readlane_b32 s98, v138, 54
	v_readlane_b32 s99, v139, 54
	v_readlane_b32 s100, v140, 54
	v_readlane_b32 s101, v141, 54
	v_fmac_f32_e32 v122, s98, v156
	v_fmac_f32_e32 v122, s99, v157
	v_fmac_f32_e32 v122, s100, v158
	v_fmac_f32_e32 v122, s101, v159
	v_readlane_b32 s98, v126, 55
	v_readlane_b32 s99, v127, 55
	v_readlane_b32 s100, v128, 55
	v_readlane_b32 s101, v129, 55
	v_fma_f32 v123, s98, v142, 0
	v_fmac_f32_e32 v123, s99, v143
	v_fmac_f32_e32 v123, s100, v144
	v_fmac_f32_e32 v123, s101, v145
	v_readlane_b32 s98, v130, 55
	v_readlane_b32 s99, v131, 55
	v_readlane_b32 s100, v132, 55
	v_readlane_b32 s101, v133, 55
	v_fmac_f32_e32 v123, s98, v146
	v_fmac_f32_e32 v123, s99, v147
	v_fmac_f32_e32 v123, s100, v148
	v_fmac_f32_e32 v123, s101, v149
	v_readlane_b32 s98, v134, 55
	v_readlane_b32 s99, v135, 55
	v_readlane_b32 s100, v136, 55
	v_readlane_b32 s101, v137, 55
	v_fmac_f32_e32 v123, s98, v150
	v_fmac_f32_e32 v123, s99, v151
	v_fmac_f32_e32 v123, s100, v154
	v_fmac_f32_e32 v123, s101, v155
	v_readlane_b32 s98, v138, 55
	v_readlane_b32 s99, v139, 55
	v_readlane_b32 s100, v140, 55
	v_readlane_b32 s101, v141, 55
	v_fmac_f32_e32 v123, s98, v156
	v_fmac_f32_e32 v123, s99, v157
	v_fmac_f32_e32 v123, s100, v158
	v_fmac_f32_e32 v123, s101, v159
	v_readlane_b32 s98, v126, 56
	v_readlane_b32 s99, v127, 56
	v_readlane_b32 s100, v128, 56
	v_readlane_b32 s101, v129, 56
	v_fma_f32 v124, s98, v142, 0
	v_fmac_f32_e32 v124, s99, v143
	v_fmac_f32_e32 v124, s100, v144
	v_fmac_f32_e32 v124, s101, v145
	v_readlane_b32 s98, v130, 56
	v_readlane_b32 s99, v131, 56
	v_readlane_b32 s100, v132, 56
	v_readlane_b32 s101, v133, 56
	v_fmac_f32_e32 v124, s98, v146
	v_fmac_f32_e32 v124, s99, v147
	v_fmac_f32_e32 v124, s100, v148
	v_fmac_f32_e32 v124, s101, v149
	v_readlane_b32 s98, v134, 56
	v_readlane_b32 s99, v135, 56
	v_readlane_b32 s100, v136, 56
	v_readlane_b32 s101, v137, 56
	v_fmac_f32_e32 v124, s98, v150
	v_fmac_f32_e32 v124, s99, v151
	v_fmac_f32_e32 v124, s100, v154
	v_fmac_f32_e32 v124, s101, v155
	v_readlane_b32 s98, v138, 56
	v_readlane_b32 s99, v139, 56
	v_readlane_b32 s100, v140, 56
	v_readlane_b32 s101, v141, 56
	v_fmac_f32_e32 v124, s98, v156
	v_fmac_f32_e32 v124, s99, v157
	v_fmac_f32_e32 v124, s100, v158
	v_fmac_f32_e32 v124, s101, v159
	v_readlane_b32 s98, v126, 57
	v_readlane_b32 s99, v127, 57
	v_readlane_b32 s100, v128, 57
	v_readlane_b32 s101, v129, 57
	v_fma_f32 v125, s98, v142, 0
	v_fmac_f32_e32 v125, s99, v143
	v_fmac_f32_e32 v125, s100, v144
	v_fmac_f32_e32 v125, s101, v145
	v_readlane_b32 s98, v130, 57
	v_readlane_b32 s99, v131, 57
	v_readlane_b32 s100, v132, 57
	v_readlane_b32 s101, v133, 57
	v_fmac_f32_e32 v125, s98, v146
	v_fmac_f32_e32 v125, s99, v147
	v_fmac_f32_e32 v125, s100, v148
	v_fmac_f32_e32 v125, s101, v149
	v_readlane_b32 s98, v134, 57
	v_readlane_b32 s99, v135, 57
	v_readlane_b32 s100, v136, 57
	v_readlane_b32 s101, v137, 57
	v_fmac_f32_e32 v125, s98, v150
	v_fmac_f32_e32 v125, s99, v151
	v_fmac_f32_e32 v125, s100, v154
	v_fmac_f32_e32 v125, s101, v155
	v_readlane_b32 s98, v138, 57
	v_readlane_b32 s99, v139, 57
	v_readlane_b32 s100, v140, 57
	v_readlane_b32 s101, v141, 57
	v_fmac_f32_e32 v125, s98, v156
	v_fmac_f32_e32 v125, s99, v157
	v_fmac_f32_e32 v125, s100, v158
	v_fmac_f32_e32 v125, s101, v159
	v_readlane_b32 s98, v126, 58
	v_readlane_b32 s99, v127, 58
	v_readlane_b32 s100, v128, 58
	v_readlane_b32 s101, v129, 58
	v_fma_f32 v32, s98, v142, 0
	v_fmac_f32_e32 v32, s99, v143
	v_fmac_f32_e32 v32, s100, v144
	v_fmac_f32_e32 v32, s101, v145
	v_readlane_b32 s98, v130, 58
	v_readlane_b32 s99, v131, 58
	v_readlane_b32 s100, v132, 58
	v_readlane_b32 s101, v133, 58
	v_fmac_f32_e32 v32, s98, v146
	v_fmac_f32_e32 v32, s99, v147
	v_fmac_f32_e32 v32, s100, v148
	v_fmac_f32_e32 v32, s101, v149
	v_readlane_b32 s98, v134, 58
	v_readlane_b32 s99, v135, 58
	v_readlane_b32 s100, v136, 58
	v_readlane_b32 s101, v137, 58
	v_fmac_f32_e32 v32, s98, v150
	v_fmac_f32_e32 v32, s99, v151
	v_fmac_f32_e32 v32, s100, v154
	v_fmac_f32_e32 v32, s101, v155
	v_readlane_b32 s98, v138, 58
	v_readlane_b32 s99, v139, 58
	v_readlane_b32 s100, v140, 58
	v_readlane_b32 s101, v141, 58
	v_fmac_f32_e32 v32, s98, v156
	v_fmac_f32_e32 v32, s99, v157
	v_fmac_f32_e32 v32, s100, v158
	v_fmac_f32_e32 v32, s101, v159
	v_readlane_b32 s98, v126, 59
	v_readlane_b32 s99, v127, 59
	v_readlane_b32 s100, v128, 59
	v_readlane_b32 s101, v129, 59
	v_fma_f32 v12, s98, v142, 0
	v_fmac_f32_e32 v12, s99, v143
	v_fmac_f32_e32 v12, s100, v144
	v_fmac_f32_e32 v12, s101, v145
	v_readlane_b32 s98, v130, 59
	v_readlane_b32 s99, v131, 59
	v_readlane_b32 s100, v132, 59
	v_readlane_b32 s101, v133, 59
	v_fmac_f32_e32 v12, s98, v146
	v_fmac_f32_e32 v12, s99, v147
	v_fmac_f32_e32 v12, s100, v148
	v_fmac_f32_e32 v12, s101, v149
	v_readlane_b32 s98, v134, 59
	v_readlane_b32 s99, v135, 59
	v_readlane_b32 s100, v136, 59
	v_readlane_b32 s101, v137, 59
	v_fmac_f32_e32 v12, s98, v150
	v_fmac_f32_e32 v12, s99, v151
	v_fmac_f32_e32 v12, s100, v154
	v_fmac_f32_e32 v12, s101, v155
	v_readlane_b32 s98, v138, 59
	v_readlane_b32 s99, v139, 59
	v_readlane_b32 s100, v140, 59
	v_readlane_b32 s101, v141, 59
	v_fmac_f32_e32 v12, s98, v156
	v_fmac_f32_e32 v12, s99, v157
	v_fmac_f32_e32 v12, s100, v158
	v_fmac_f32_e32 v12, s101, v159
	v_readlane_b32 s98, v126, 60
; __device__ __forceinline__ void cvt_job(int& tbase, const float* __restrict__ src, int Nsrc, int K, bf16_t* __restrict__ dst, int ndst, int mode,
;                                         const float* __restrict__ gain, const float* __restrict__ up_f, const float* __restrict__ up_b, int bi, int nb) {
;     ...
;             for (int j = 0; j < 64; ++j) { const float* wp = src + (size_t)(k0 + j) * Nsrc + 3072 + 16 * dirb; float sacc = 0.f;
; #pragma unroll
;                 for (int r = 0; r < 16; ++r) sacc += wp[r] * upv[r];
;                 v[j] = sacc; }
;         } else {
;             const float* sp = src + (size_t)k0 * Nsrc + col;
; #pragma unroll
;             for (int j = 0; j < 64; ++j) v[j] = sp[(size_t)j * Nsrc];
;         }
;         bf16_t* dp = dst + (size_t)n * K + k0;
;         if (gain) {
	v_readlane_b32 s99, v127, 60
	v_readlane_b32 s100, v128, 60
	v_readlane_b32 s101, v129, 60
	v_fma_f32 v13, s98, v142, 0
	v_fmac_f32_e32 v13, s99, v143
	v_fmac_f32_e32 v13, s100, v144
	v_fmac_f32_e32 v13, s101, v145
	v_readlane_b32 s98, v130, 60
	v_readlane_b32 s99, v131, 60
	v_readlane_b32 s100, v132, 60
	v_readlane_b32 s101, v133, 60
	v_fmac_f32_e32 v13, s98, v146
	v_fmac_f32_e32 v13, s99, v147
	v_fmac_f32_e32 v13, s100, v148
	v_fmac_f32_e32 v13, s101, v149
	v_readlane_b32 s98, v134, 60
	v_readlane_b32 s99, v135, 60
	v_readlane_b32 s100, v136, 60
	v_readlane_b32 s101, v137, 60
	v_fmac_f32_e32 v13, s98, v150
	v_fmac_f32_e32 v13, s99, v151
	v_fmac_f32_e32 v13, s100, v154
	v_fmac_f32_e32 v13, s101, v155
	v_readlane_b32 s98, v138, 60
	v_readlane_b32 s99, v139, 60
	v_readlane_b32 s100, v140, 60
	v_readlane_b32 s101, v141, 60
	v_fmac_f32_e32 v13, s98, v156
	v_fmac_f32_e32 v13, s99, v157
	v_fmac_f32_e32 v13, s100, v158
	v_fmac_f32_e32 v13, s101, v159
	v_readlane_b32 s98, v126, 61
	v_readlane_b32 s99, v127, 61
	v_readlane_b32 s100, v128, 61
	v_readlane_b32 s101, v129, 61
	v_fma_f32 v14, s98, v142, 0
	v_fmac_f32_e32 v14, s99, v143
	v_fmac_f32_e32 v14, s100, v144
	v_fmac_f32_e32 v14, s101, v145
	v_readlane_b32 s98, v130, 61
	v_readlane_b32 s99, v131, 61
	v_readlane_b32 s100, v132, 61
	v_readlane_b32 s101, v133, 61
	v_fmac_f32_e32 v14, s98, v146
	v_fmac_f32_e32 v14, s99, v147
	v_fmac_f32_e32 v14, s100, v148
	v_fmac_f32_e32 v14, s101, v149
	v_readlane_b32 s98, v134, 61
	v_readlane_b32 s99, v135, 61
	v_readlane_b32 s100, v136, 61
	v_readlane_b32 s101, v137, 61
	v_fmac_f32_e32 v14, s98, v150
	v_fmac_f32_e32 v14, s99, v151
	v_fmac_f32_e32 v14, s100, v154
	v_fmac_f32_e32 v14, s101, v155
	v_readlane_b32 s98, v138, 61
	v_readlane_b32 s99, v139, 61
	v_readlane_b32 s100, v140, 61
	v_readlane_b32 s101, v141, 61
	v_fmac_f32_e32 v14, s98, v156
	v_fmac_f32_e32 v14, s99, v157
	v_fmac_f32_e32 v14, s100, v158
	v_fmac_f32_e32 v14, s101, v159
	v_readlane_b32 s98, v126, 62
	v_readlane_b32 s99, v127, 62
	v_readlane_b32 s100, v128, 62
	v_readlane_b32 s101, v129, 62
	v_fma_f32 v15, s98, v142, 0
	v_fmac_f32_e32 v15, s99, v143
	v_fmac_f32_e32 v15, s100, v144
	v_fmac_f32_e32 v15, s101, v145
	v_readlane_b32 s98, v130, 62
	v_readlane_b32 s99, v131, 62
	v_readlane_b32 s100, v132, 62
	v_readlane_b32 s101, v133, 62
	v_fmac_f32_e32 v15, s98, v146
	v_fmac_f32_e32 v15, s99, v147
	v_fmac_f32_e32 v15, s100, v148
	v_fmac_f32_e32 v15, s101, v149
	v_readlane_b32 s98, v134, 62
	v_readlane_b32 s99, v135, 62
	v_readlane_b32 s100, v136, 62
	v_readlane_b32 s101, v137, 62
	v_fmac_f32_e32 v15, s98, v150
	v_fmac_f32_e32 v15, s99, v151
	v_fmac_f32_e32 v15, s100, v154
	v_fmac_f32_e32 v15, s101, v155
	v_readlane_b32 s98, v138, 62
	v_readlane_b32 s99, v139, 62
	v_readlane_b32 s100, v140, 62
	v_readlane_b32 s101, v141, 62
	v_fmac_f32_e32 v15, s98, v156
	v_fmac_f32_e32 v15, s99, v157
	v_fmac_f32_e32 v15, s100, v158
	v_fmac_f32_e32 v15, s101, v159
	v_readlane_b32 s98, v126, 63
	v_readlane_b32 s99, v127, 63
	v_readlane_b32 s100, v128, 63
	v_readlane_b32 s101, v129, 63
	v_fma_f32 v16, s98, v142, 0
	v_fmac_f32_e32 v16, s99, v143
	v_fmac_f32_e32 v16, s100, v144
	v_fmac_f32_e32 v16, s101, v145
	v_readlane_b32 s98, v130, 63
	v_readlane_b32 s99, v131, 63
	v_readlane_b32 s100, v132, 63
	v_readlane_b32 s101, v133, 63
	v_fmac_f32_e32 v16, s98, v146
	v_fmac_f32_e32 v16, s99, v147
	v_fmac_f32_e32 v16, s100, v148
	v_fmac_f32_e32 v16, s101, v149
	v_readlane_b32 s98, v134, 63
	v_readlane_b32 s99, v135, 63
	v_readlane_b32 s100, v136, 63
	v_readlane_b32 s101, v137, 63
	v_fmac_f32_e32 v16, s98, v150
	v_fmac_f32_e32 v16, s99, v151
	v_fmac_f32_e32 v16, s100, v154
	v_fmac_f32_e32 v16, s101, v155
	v_readlane_b32 s98, v138, 63
	v_readlane_b32 s99, v139, 63
	v_readlane_b32 s100, v140, 63
	v_readlane_b32 s101, v141, 63
	v_fmac_f32_e32 v16, s98, v156
	v_fmac_f32_e32 v16, s99, v157
	v_fmac_f32_e32 v16, s100, v158
	v_fmac_f32_e32 v16, s101, v159
	v_ashrrev_i32_e32 v43, 31, v42
	v_lshlrev_b64 v[0:1], 11, v[42:43]
	v_lshl_add_u64 v[0:1], s[4:5], 0, v[0:1]
	v_lshl_add_u64 v[8:9], v[40:41], 1, v[0:1]
	s_and_b64 vcc, exec, s[24:25]
	s_cbranch_vccz .LBB0_104
; __device__ __forceinline__ unsigned cvt_pk_bf16(float lo, float hi) { unsigned r; asm volatile("v_cvt_pk_bf16_f32 %0, %1, %2" : "=v"(r) : "v"(lo), "v"(hi)); return r; }
; __device__ __forceinline__ void cvt_job(int& tbase, const float* __restrict__ src, int Nsrc, int K, bf16_t* __restrict__ dst, int ndst, int mode,
;                                         const float* __restrict__ gain, const float* __restrict__ up_f, const float* __restrict__ up_b, int bi, int nb) {
;     ...
;         if (gain) {
; #pragma unroll
;             for (int j8 = 0; j8 < 8; ++j8) { const f32x4 g0 = *(const f32x4*)(gain + k0 + 8 * j8), g1 = *(const f32x4*)(gain + k0 + 8 * j8 + 4);
;                 u32x4 w; w.x = cvt_pk_bf16(v[8 * j8] * g0[0] * scale, v[8 * j8 + 1] * g0[1] * scale); w.y = cvt_pk_bf16(v[8 * j8 + 2] * g0[2] * scale, v[8 * j8 + 3] * g0[3] * scale);
;                 w.z = cvt_pk_bf16(v[8 * j8 + 4] * g1[0] * scale, v[8 * j8 + 5] * g1[1] * scale); w.w = cvt_pk_bf16(v[8 * j8 + 6] * g1[2] * scale, v[8 * j8 + 7] * g1[3] * scale);
;                 *(u32x4*)(dp + 8 * j8) = w; }
	v_lshl_add_u64 v[10:11], v[40:41], 2, s[14:15]
	global_load_dwordx4 v[0:3], v[10:11], off
	global_load_dwordx4 v[4:7], v[10:11], off offset:16
	s_waitcnt vmcnt(1)
	v_mul_f32_e32 v0, v36, v0
	v_mul_f32_e32 v1, v61, v1
	v_mul_f32_e32 v2, v62, v2
	v_mul_f32_e32 v3, v63, v3
	s_waitcnt vmcnt(0)
	v_mul_f32_e32 v4, v64, v4
	v_mul_f32_e32 v5, v65, v5
	v_mul_f32_e32 v6, v66, v6
	v_mul_f32_e32 v7, v71, v7
	v_cvt_pk_bf16_f32 v0, v0, v1
	v_cvt_pk_bf16_f32 v1, v2, v3
	v_cvt_pk_bf16_f32 v2, v4, v5
	v_cvt_pk_bf16_f32 v3, v6, v7
	global_store_dwordx4 v[8:9], v[0:3], off
	global_load_dwordx4 v[0:3], v[10:11], off offset:32
	s_nop 0
	global_load_dwordx4 v[4:7], v[10:11], off offset:48
	s_waitcnt vmcnt(1)
	v_mul_f32_e32 v0, v72, v0
	v_mul_f32_e32 v1, v73, v1
	v_mul_f32_e32 v2, v74, v2
	v_mul_f32_e32 v3, v79, v3
	s_waitcnt vmcnt(0)
	v_mul_f32_e32 v4, v80, v4
	v_mul_f32_e32 v5, v81, v5
	v_mul_f32_e32 v6, v82, v6
	v_mul_f32_e32 v7, v83, v7
	v_cvt_pk_bf16_f32 v0, v0, v1
	v_cvt_pk_bf16_f32 v1, v2, v3
	v_cvt_pk_bf16_f32 v2, v4, v5
	v_cvt_pk_bf16_f32 v3, v6, v7
	global_store_dwordx4 v[8:9], v[0:3], off offset:16
	global_load_dwordx4 v[0:3], v[10:11], off offset:64
	s_nop 0
	global_load_dwordx4 v[4:7], v[10:11], off offset:80
	s_waitcnt vmcnt(1)
	v_mul_f32_e32 v0, v84, v0
	v_mul_f32_e32 v1, v85, v1
	v_mul_f32_e32 v2, v86, v2
	v_mul_f32_e32 v3, v87, v3
	s_waitcnt vmcnt(0)
	v_mul_f32_e32 v4, v88, v4
	v_mul_f32_e32 v5, v89, v5
	v_mul_f32_e32 v6, v90, v6
	v_mul_f32_e32 v7, v91, v7
	v_cvt_pk_bf16_f32 v0, v0, v1
	v_cvt_pk_bf16_f32 v1, v2, v3
	v_cvt_pk_bf16_f32 v2, v4, v5
	v_cvt_pk_bf16_f32 v3, v6, v7
	global_store_dwordx4 v[8:9], v[0:3], off offset:32
	global_load_dwordx4 v[0:3], v[10:11], off offset:96
	s_nop 0
	global_load_dwordx4 v[4:7], v[10:11], off offset:112
	s_waitcnt vmcnt(1)
	v_mul_f32_e32 v0, v92, v0
	v_mul_f32_e32 v1, v93, v1
	v_mul_f32_e32 v2, v94, v2
	v_mul_f32_e32 v3, v95, v3
	s_waitcnt vmcnt(0)
	v_mul_f32_e32 v4, v96, v4
	v_mul_f32_e32 v5, v97, v5
	v_mul_f32_e32 v6, v98, v6
	v_mul_f32_e32 v7, v99, v7
	v_cvt_pk_bf16_f32 v0, v0, v1
	v_cvt_pk_bf16_f32 v1, v2, v3
	v_cvt_pk_bf16_f32 v2, v4, v5
	v_cvt_pk_bf16_f32 v3, v6, v7
	global_store_dwordx4 v[8:9], v[0:3], off offset:48
	global_load_dwordx4 v[0:3], v[10:11], off offset:128
	s_nop 0
	global_load_dwordx4 v[4:7], v[10:11], off offset:144
	s_waitcnt vmcnt(1)
	v_mul_f32_e32 v0, v100, v0
	v_mul_f32_e32 v1, v101, v1
	v_mul_f32_e32 v2, v102, v2
	v_mul_f32_e32 v3, v103, v3
	s_waitcnt vmcnt(0)
	v_mul_f32_e32 v4, v104, v4
	v_mul_f32_e32 v5, v105, v5
	v_mul_f32_e32 v6, v106, v6
	v_mul_f32_e32 v7, v107, v7
	v_cvt_pk_bf16_f32 v0, v0, v1
	v_cvt_pk_bf16_f32 v1, v2, v3
	v_cvt_pk_bf16_f32 v2, v4, v5
	v_cvt_pk_bf16_f32 v3, v6, v7
	global_store_dwordx4 v[8:9], v[0:3], off offset:64
	global_load_dwordx4 v[0:3], v[10:11], off offset:160
	s_nop 0
	global_load_dwordx4 v[4:7], v[10:11], off offset:176
	s_waitcnt vmcnt(1)
	v_mul_f32_e32 v0, v108, v0
	v_mul_f32_e32 v1, v109, v1
	v_mul_f32_e32 v2, v110, v2
	v_mul_f32_e32 v3, v111, v3
	s_waitcnt vmcnt(0)
	v_mul_f32_e32 v4, v112, v4
	v_mul_f32_e32 v5, v113, v5
	v_mul_f32_e32 v6, v114, v6
	v_mul_f32_e32 v7, v115, v7
	v_cvt_pk_bf16_f32 v0, v0, v1
	v_cvt_pk_bf16_f32 v1, v2, v3
	v_cvt_pk_bf16_f32 v2, v4, v5
	v_cvt_pk_bf16_f32 v3, v6, v7
	global_store_dwordx4 v[8:9], v[0:3], off offset:80
	global_load_dwordx4 v[0:3], v[10:11], off offset:192
	s_nop 0
	global_load_dwordx4 v[4:7], v[10:11], off offset:208
	s_waitcnt vmcnt(1)
	v_mul_f32_e32 v0, v116, v0
	v_mul_f32_e32 v1, v117, v1
	v_mul_f32_e32 v2, v118, v2
	v_mul_f32_e32 v3, v119, v3
	s_waitcnt vmcnt(0)
	v_mul_f32_e32 v4, v120, v4
	v_mul_f32_e32 v5, v121, v5
	v_mul_f32_e32 v6, v122, v6
	v_mul_f32_e32 v7, v123, v7
	v_cvt_pk_bf16_f32 v0, v0, v1
	v_cvt_pk_bf16_f32 v1, v2, v3
	v_cvt_pk_bf16_f32 v2, v4, v5
	v_cvt_pk_bf16_f32 v3, v6, v7
	global_load_dwordx4 v[4:7], v[10:11], off offset:224
	global_load_dwordx4 v[18:21], v[10:11], off offset:240
	s_waitcnt vmcnt(1)
	v_mul_f32_e32 v4, v124, v4
	v_mul_f32_e32 v5, v125, v5
	v_mul_f32_e32 v6, v32, v6
	v_mul_f32_e32 v7, v12, v7
	s_waitcnt vmcnt(0)
	v_mul_f32_e32 v10, v13, v18
	v_mul_f32_e32 v11, v14, v19
	v_mul_f32_e32 v17, v15, v20
	v_mul_f32_e32 v18, v16, v21
	v_cvt_pk_bf16_f32 v4, v4, v5
	v_cvt_pk_bf16_f32 v5, v6, v7
	v_cvt_pk_bf16_f32 v6, v10, v11
	v_cvt_pk_bf16_f32 v7, v17, v18
	s_cbranch_execnz .LBB0_101
	s_branch .LBB0_105

; __device__ __forceinline__ float bf_lo(unsigned u) { return __uint_as_float(u << 16); }
; __device__ __forceinline__ void gla_phase(unsigned char* lds, const bf16_t* __restrict__ Z1, bf16_t* __restrict__ Of, bf16_t* __restrict__ Ob, int bi, int nb, int nitems) {
;     ...
;                 for (int tt = 0; tt < 8; ++tt) { ga[tt] = bf_lo(rg[tt]); gb[tt] = bf_hi(rg[tt]); }
;                 if (!dir) {
; #pragma unroll
;                     for (int tt = 1; tt < 8; ++tt) { ga[tt] += ga[tt - 1]; gb[tt] += gb[tt - 1]; }
;                     *(float2*)(SEG + w * 128 + d2) = make_float2(ga[7], gb[7]);
;                 } else {
; #pragma unroll
;     ...
;                     *(float2*)(SEG + w * 128 + d2) = make_float2(ga[0], gb[0]);
;                 }
;                 { u32x4 va, vb;
;                   va.x = (rv[0] & 0xffffu) | (rv[1] << 16); va.y = (rv[2] & 0xffffu) | (rv[3] << 16); va.z = (rv[4] & 0xffffu) | (rv[5] << 16); va.w = (rv[6] & 0xffffu) | (rv[7] << 16);
;                   vb.x = (rv[0] >> 16) | (rv[1] & 0xffff0000u); vb.y = (rv[2] >> 16) | (rv[3] & 0xffff0000u); vb.z = (rv[4] >> 16) | (rv[5] & 0xffff0000u); vb.w = (rv[6] >> 16) | (rv[7] & 0xffff0000u);
;                   *(u32x4*)(VTy + d2 * 72 + 8 * w) = va; *(u32x4*)(VTy + (d2 + 1) * 72 + 8 * w) = vb; }
;                 if (pref) { const size_t co = (size_t)(cnn * 64) * NZ1;
; #pragma unroll
;                     for (int tt = 0; tt < 8; ++tt) { const size_t o = co + (size_t)tt * NZ1; rg[tt] = *(const unsigned*)(zg + o); rv[tt] = *(const unsigned*)(zv + o); } }
;             }
;             LBAR();
;             if (cons) {
;                 const bf16x8 v0 = *(const bf16x8*)(VTx + (16 * w + r) * 72 + 8 * q), v1 = *(const bf16x8*)(VTx + (16 * w + r) * 72 + 32 + 8 * q);
; #pragma unroll
;                 for (int hb = 0; hb < 2; ++hb) { bf16x8 kd0[4], kd1[4]; f32x4 dc[4];
; #pragma unroll
;                     for (int m4 = 0; m4 < 4; ++m4) { const int mb = 4 * hb + m4; dc[m4] = *(const f32x4*)(DECx + 16 * mb + 4 * q);
;                         kd0[m4] = *(const bf16x8*)(KDx + (16 * mb + r) * 72 + 8 * q); kd1[m4] = *(const bf16x8*)(KDx + (16 * mb + r) * 72 + 32 + 8 * q); }
;                     GLA_WAIT();
; #pragma unroll
;                     for (int m4 = 0; m4 < 4; ++m4) { const int mb = 4 * hb + m4; S[mb] = S[mb] * dc[m4];
.LBB0_588:
	s_and_b64 s[8:9], s[54:55], exec
	s_mov_b32 s8, 0x40000
	s_cselect_b32 s8, s8, 0x780000
	s_or_b32 s9, s8, 0x1000
	s_lshl_b32 s68, s9, 1
	s_or_b32 s9, s8, 0x2000
	s_lshl_b32 s70, s9, 1
	s_or_b32 s9, s8, 0x3000
	s_lshl_b32 s76, s9, 1
	s_or_b32 s9, s8, 0x4000
	s_lshl_b32 s66, s8, 1
	s_mov_b32 s67, s1
	s_lshl_b32 s78, s9, 1
	s_or_b32 s9, s8, 0x5000
	v_lshl_add_u64 v[18:19], v[98:99], 0, s[66:67]
	s_mov_b32 s69, s1
	s_mov_b32 s71, s1
	s_mov_b32 s77, s1
	s_mov_b32 s79, s1
	s_lshl_b32 s80, s9, 1
	s_or_b32 s9, s8, 0x6000
	s_or_b32 s8, s8, 0x7000
	v_lshl_add_u64 v[20:21], v[92:93], 0, s[66:67]
	v_lshl_add_u64 v[22:23], v[98:99], 0, s[68:69]
	v_lshl_add_u64 v[24:25], v[94:95], 0, s[68:69]
	v_lshl_add_u64 v[26:27], v[98:99], 0, s[70:71]
	v_lshl_add_u64 v[28:29], v[94:95], 0, s[70:71]
	v_lshl_add_u64 v[30:31], v[98:99], 0, s[76:77]
	v_lshl_add_u64 v[32:33], v[94:95], 0, s[76:77]
	global_load_dword v126, v[18:19], off
	global_load_dword v127, v[20:21], off offset:2048
	global_load_dword v128, v[22:23], off
	global_load_dword v129, v[24:25], off
	global_load_dword v130, v[26:27], off
	global_load_dword v131, v[28:29], off
	global_load_dword v132, v[30:31], off
	global_load_dword v133, v[32:33], off
	v_lshl_add_u64 v[18:19], v[98:99], 0, s[78:79]
	s_mov_b32 s81, s1
	s_lshl_b32 s82, s9, 1
	s_mov_b32 s83, s1
	s_lshl_b32 s84, s8, 1
	s_mov_b32 s85, s1
	v_lshl_add_u64 v[20:21], v[94:95], 0, s[78:79]
	v_lshl_add_u64 v[22:23], v[98:99], 0, s[80:81]
	v_lshl_add_u64 v[24:25], v[94:95], 0, s[80:81]
	v_lshl_add_u64 v[26:27], v[98:99], 0, s[82:83]
	v_lshl_add_u64 v[28:29], v[94:95], 0, s[82:83]
	v_lshl_add_u64 v[30:31], v[98:99], 0, s[84:85]
	v_lshl_add_u64 v[32:33], v[94:95], 0, s[84:85]
	global_load_dword v134, v[18:19], off
	global_load_dword v135, v[20:21], off
	global_load_dword v136, v[22:23], off
	global_load_dword v137, v[24:25], off
	global_load_dword v138, v[26:27], off
	global_load_dword v139, v[28:29], off
	global_load_dword v140, v[30:31], off
	global_load_dword v141, v[32:33], off
	ds_write_b64 v125, v[16:17]
	v_and_b32_e32 v16, 0xffff, v50
	v_and_b32_e32 v17, 0xffff, v52
	v_and_b32_e32 v18, 0xffff, v54
	s_waitcnt vmcnt(20)
	v_and_b32_e32 v19, 0xffff, v56
	v_lshl_or_b32 v16, v51, 16, v16
	v_lshl_or_b32 v17, v53, 16, v17
	v_lshl_or_b32 v18, v55, 16, v18
	s_waitcnt vmcnt(18)
	v_lshl_or_b32 v19, v57, 16, v19
	v_lshrrev_b32_e32 v20, 16, v50
	v_lshrrev_b32_e32 v21, 16, v52
	v_lshrrev_b32_e32 v22, 16, v54
	v_lshrrev_b32_e32 v23, 16, v56
	v_and_or_b32 v20, v51, s6, v20
	v_and_or_b32 v21, v53, s6, v21
	v_and_or_b32 v22, v55, s6, v22
	v_and_or_b32 v23, v57, s6, v23
	ds_write_b128 v115, v[16:19] offset:35840
	ds_write_b128 v115, v[20:23] offset:35984
	s_waitcnt lgkmcnt(0)
	s_barrier
	ds_read2st64_b64 v[28:31], v104 offset1:1
	ds_read2st64_b64 v[24:27], v104 offset0:2 offset1:3
	ds_read2st64_b64 v[20:23], v104 offset0:4 offset1:5
	s_waitcnt lgkmcnt(2)
	v_add_f32_e32 v32, 0, v28
	v_add_f32_e32 v33, 0, v29
	v_add_f32_e32 v16, v32, v30
	v_add_f32_e32 v17, v33, v31
	s_waitcnt lgkmcnt(1)
	v_add_f32_e32 v16, v16, v24
	v_add_f32_e32 v17, v17, v25
	v_add_f32_e32 v28, v16, v26
	v_add_f32_e32 v29, v17, v27
	ds_read2st64_b64 v[16:19], v104 offset0:6 offset1:7
	s_waitcnt lgkmcnt(1)
	v_add_f32_e32 v28, v28, v20
	v_add_f32_e32 v29, v29, v21
	v_add_f32_e32 v28, v28, v22
	v_add_f32_e32 v29, v29, v23
	s_waitcnt lgkmcnt(0)
	v_add_f32_e32 v28, v28, v16
	v_add_f32_e32 v29, v29, v17
	v_add_f32_e32 v28, v28, v18
	v_add_f32_e32 v29, v29, v19
	v_mul_f32_e32 v28, 0x3fb8aa3b, v28
	v_mul_f32_e32 v29, 0x3fb8aa3b, v29
	v_exp_f32_e32 v28, v28
	v_exp_f32_e32 v29, v29
	s_and_saveexec_b64 s[56:57], s[2:3]
	ds_write_b64 v116, v[28:29] offset:63488
	s_or_b64 exec, exec, s[56:57]
	v_readlane_b32 s8, v244, 2
	v_readlane_b32 s9, v244, 3
	v_cndmask_b32_e64 v54, 0, 1, s[16:17]
	v_cndmask_b32_e64 v55, 0, 1, s[20:21]
	v_cndmask_b32_e64 v50, 0, 1, s[8:9]
	v_readlane_b32 s8, v244, 0
	v_readlane_b32 s9, v244, 1
	v_cndmask_b32_e64 v56, 0, 1, s[24:25]
	v_cndmask_b32_e64 v57, 0, 1, s[28:29]
	v_cndmask_b32_e64 v51, 0, 1, s[8:9]
	v_readlane_b32 s8, v244, 6
	v_readlane_b32 s9, v244, 7
	v_cndmask_b32_e64 v50, v51, v50, s[54:55]
	v_and_b32_e32 v50, 1, v50
	v_cndmask_b32_e64 v51, 0, 1, s[8:9]
	v_readlane_b32 s8, v244, 4
	v_readlane_b32 s9, v244, 5
	v_cmp_eq_u32_e64 s[56:57], 1, v50
	v_cndmask_b32_e64 v58, 0, 1, s[34:35]
	v_cndmask_b32_e64 v52, 0, 1, s[8:9]
	v_readlane_b32 s8, v244, 8
	v_readlane_b32 s9, v244, 9
	v_cndmask_b32_e64 v51, v52, v51, s[54:55]
	v_cndmask_b32_e64 v52, 0, 1, s[14:15]
	v_cndmask_b32_e64 v53, 0, 1, s[8:9]
	v_and_b32_e32 v51, 1, v51
	v_cndmask_b32_e64 v52, v53, v52, s[54:55]
	v_cndmask_b32_e64 v53, 0, 1, s[18:19]
	v_and_b32_e32 v52, 1, v52
	v_cndmask_b32_e64 v53, v54, v53, s[54:55]
	v_cmp_eq_u32_e64 s[58:59], 1, v51
	v_and_b32_e32 v53, 1, v53
	v_cndmask_b32_e64 v54, 0, 1, s[22:23]
	v_cndmask_b32_e64 v32, 0, v32, s[56:57]
	v_cndmask_b32_e64 v30, 0, v30, s[58:59]
	v_cmp_eq_u32_e64 s[60:61], 1, v52
	v_cndmask_b32_e64 v54, v55, v54, s[54:55]
	v_cndmask_b32_e64 v33, 0, v33, s[56:57]
	v_add_f32_e32 v30, v32, v30
	v_cndmask_b32_e64 v31, 0, v31, s[58:59]
	v_cndmask_b32_e64 v24, 0, v24, s[60:61]
	v_cmp_eq_u32_e64 s[62:63], 1, v53
	v_and_b32_e32 v54, 1, v54
	v_cndmask_b32_e64 v55, 0, 1, s[26:27]
	v_add_f32_e32 v31, v33, v31
	v_add_f32_e32 v24, v30, v24
	v_cndmask_b32_e64 v25, 0, v25, s[60:61]
	v_cndmask_b32_e64 v26, 0, v26, s[62:63]
	v_cndmask_b32_e64 v55, v56, v55, s[54:55]
	v_cndmask_b32_e64 v56, 0, 1, s[30:31]
	v_add_f32_e32 v25, v31, v25
	v_add_f32_e32 v24, v24, v26
	v_cndmask_b32_e64 v26, 0, v27, s[62:63]
	v_cmp_eq_u32_e64 s[64:65], 1, v54
	v_and_b32_e32 v55, 1, v55
; __device__ __forceinline__ unsigned cvt_pk_bf16(float lo, float hi) { unsigned r; asm volatile("v_cvt_pk_bf16_f32 %0, %1, %2" : "=v"(r) : "v"(lo), "v"(hi)); return r; }
; __device__ __forceinline__ float bf_lo(unsigned u) { return __uint_as_float(u << 16); }
; __device__ __forceinline__ float bf_hi(unsigned u) { return __uint_as_float(u & 0xffff0000u); }
; __device__ __forceinline__ void gla_phase(unsigned char* lds, const bf16_t* __restrict__ Z1, bf16_t* __restrict__ Of, bf16_t* __restrict__ Ob, int bi, int nb, int nitems) {
;     ...
;                 float offa = 0.f, offb = 0.f, tota = 0.f, totb = 0.f;
; #pragma unroll
;                 for (int s = 0; s < 8; ++s) { const float2 v = *(const float2*)(SEG + s * 128 + d2); tota += v.x; totb += v.y; const bool inc = dir ? (s > w) : (s < w); offa += inc ? v.x : 0.f; offb += inc ? v.y : 0.f; }
;                 const float eta = __expf(tota), etb = __expf(totb);
;                 if (w == 0) *(float2*)(DECy + d2) = make_float2(eta, etb);
;                 float kda[8], kdb[8];
; #pragma unroll
;                 for (int tt = 0; tt < 8; ++tt) { const float ba = offa + ga[tt], bb = offb + gb[tt];
;                     const float ea = __expf(ba), eb = __expf(bb), iea = __expf(-ba), ieb = __expf(-bb);
;                     const float ksa = bf_lo(rk[tt]) * iea, ksb = bf_hi(rk[tt]) * ieb;
;                     *(unsigned*)(QSy + (8 * w + tt) * 136 + d2) = cvt_pk_bf16(bf_lo(rq[tt]) * ea, bf_hi(rq[tt]) * eb);
;                     *(unsigned*)(KS + (8 * w + tt) * 136 + d2) = cvt_pk_bf16(ksa, ksb);
;                     kda[tt] = ksa * eta; kdb[tt] = ksb * etb; }
	v_cndmask_b32_e64 v56, v57, v56, s[54:55]
	v_cndmask_b32_e64 v57, 0, 1, s[36:37]
	v_add_f32_e32 v25, v25, v26
	v_cndmask_b32_e64 v20, 0, v20, s[64:65]
	v_cndmask_b32_e64 v21, 0, v21, s[64:65]
	v_and_b32_e32 v56, 1, v56
	v_cndmask_b32_e64 v57, v58, v57, s[54:55]
	v_add_f32_e32 v20, v24, v20
	v_add_f32_e32 v21, v25, v21
	v_lshl_add_u64 v[24:25], v[90:91], 0, s[66:67]
	v_cmp_eq_u32_e64 s[66:67], 1, v55
	v_and_b32_e32 v57, 1, v57
	v_lshl_add_u64 v[26:27], v[90:91], 0, s[68:69]
	v_cndmask_b32_e64 v22, 0, v22, s[66:67]
	v_lshl_add_u64 v[30:31], v[96:97], 0, s[68:69]
	v_cmp_eq_u32_e64 s[68:69], 1, v56
	v_add_f32_e32 v20, v20, v22
	v_cndmask_b32_e64 v22, 0, v23, s[66:67]
	v_cndmask_b32_e64 v16, 0, v16, s[68:69]
	v_lshl_add_u64 v[32:33], v[90:91], 0, s[70:71]
	v_lshl_add_u64 v[50:51], v[96:97], 0, s[70:71]
	v_cmp_eq_u32_e64 s[70:71], 1, v57
	v_add_f32_e32 v21, v21, v22
	v_add_f32_e32 v16, v20, v16
	v_cndmask_b32_e64 v17, 0, v17, s[68:69]
	v_cndmask_b32_e64 v18, 0, v18, s[70:71]
	v_add_f32_e32 v17, v21, v17
	v_add_f32_e32 v16, v16, v18
	v_cndmask_b32_e64 v18, 0, v19, s[70:71]
	v_add_f32_e32 v17, v17, v18
	v_add_f32_e32 v18, v8, v16
	v_add_f32_e32 v19, v0, v17
	v_mul_f32_e32 v20, 0x3fb8aa3b, v18
	v_mul_f32_e32 v18, 0xbfb8aa3b, v18
	v_mul_f32_e32 v21, 0x3fb8aa3b, v19
	v_exp_f32_e32 v18, v18
	v_mul_f32_e32 v19, 0xbfb8aa3b, v19
	v_exp_f32_e32 v19, v19
	v_exp_f32_e32 v20, v20
	v_exp_f32_e32 v21, v21
	v_lshlrev_b32_e32 v22, 16, v49
	v_mul_f32_e32 v18, v18, v22
	v_and_b32_e32 v22, 0xffff0000, v49
	v_mul_f32_e32 v19, v19, v22
	v_lshlrev_b32_e32 v22, 16, v48
	v_mul_f32_e32 v20, v20, v22
	v_and_b32_e32 v22, 0xffff0000, v48
	v_mul_f32_e32 v21, v21, v22
	v_cvt_pk_bf16_f32 v20, v20, v21
	ds_write_b32 v117, v20
	v_cvt_pk_bf16_f32 v20, v18, v19
	v_add_f32_e32 v21, v1, v17
	ds_write_b32 v114, v20
	v_mul_f32_e32 v20, v29, v19
	v_add_f32_e32 v19, v9, v16
	v_mul_f32_e32 v23, 0x3fb8aa3b, v21
	v_mul_f32_e32 v21, 0xbfb8aa3b, v21
	v_mul_f32_e32 v22, 0x3fb8aa3b, v19
	v_exp_f32_e32 v21, v21
	v_exp_f32_e32 v22, v22
	v_exp_f32_e32 v23, v23
	v_mul_f32_e32 v19, 0xbfb8aa3b, v19
	v_exp_f32_e32 v19, v19
	v_lshlrev_b32_e32 v48, 16, v46
	v_and_b32_e32 v46, 0xffff0000, v46
	v_mul_f32_e32 v21, v21, v46
	v_lshlrev_b32_e32 v46, 16, v44
	v_mul_f32_e32 v22, v22, v46
	v_and_b32_e32 v44, 0xffff0000, v44
	v_mul_f32_e32 v23, v23, v44
	v_cvt_pk_bf16_f32 v22, v22, v23
	v_mul_f32_e32 v19, v19, v48
	ds_write_b32 v117, v22 offset:272
	v_cvt_pk_bf16_f32 v22, v19, v21
	v_add_f32_e32 v23, v2, v17
	ds_write_b32 v114, v22 offset:272
	v_add_f32_e32 v22, v10, v16
	v_mul_f32_e32 v46, 0x3fb8aa3b, v23
	v_mul_f32_e32 v23, 0xbfb8aa3b, v23
	v_mul_f32_e32 v44, 0x3fb8aa3b, v22
	v_exp_f32_e32 v23, v23
	v_exp_f32_e32 v44, v44
	v_exp_f32_e32 v46, v46
	v_mul_f32_e32 v22, 0xbfb8aa3b, v22
	v_exp_f32_e32 v22, v22
	v_lshlrev_b32_e32 v48, 16, v47
	v_and_b32_e32 v47, 0xffff0000, v47
	v_mul_f32_e32 v23, v23, v47
	v_lshlrev_b32_e32 v47, 16, v45
	v_and_b32_e32 v45, 0xffff0000, v45
	v_mul_f32_e32 v44, v44, v47
	v_mul_f32_e32 v45, v46, v45
	v_cvt_pk_bf16_f32 v44, v44, v45
	v_add_f32_e32 v45, v3, v17
	v_mul_f32_e32 v22, v22, v48
	ds_write_b32 v117, v44 offset:544
	v_cvt_pk_bf16_f32 v44, v22, v23
	v_mul_f32_e32 v47, 0x3fb8aa3b, v45
	v_mul_f32_e32 v45, 0xbfb8aa3b, v45
	ds_write_b32 v114, v44 offset:544
	v_add_f32_e32 v44, v11, v16
	v_exp_f32_e32 v45, v45
	v_mul_f32_e32 v46, 0x3fb8aa3b, v44
	v_exp_f32_e32 v47, v47
	v_exp_f32_e32 v46, v46
	v_mul_f32_e32 v44, 0xbfb8aa3b, v44
	v_exp_f32_e32 v44, v44
	v_lshlrev_b32_e32 v48, 16, v42
	v_and_b32_e32 v42, 0xffff0000, v42
	v_mul_f32_e32 v42, v45, v42
	v_lshlrev_b32_e32 v45, 16, v40
	v_and_b32_e32 v40, 0xffff0000, v40
	v_mul_f32_e32 v40, v47, v40
	v_mul_f32_e32 v45, v46, v45
	v_cvt_pk_bf16_f32 v40, v45, v40
	v_mul_f32_e32 v44, v44, v48
	ds_write_b32 v117, v40 offset:816
	v_cvt_pk_bf16_f32 v40, v44, v42
	v_add_f32_e32 v45, v4, v17
	ds_write_b32 v114, v40 offset:816
	v_mul_f32_e32 v40, v28, v44
	v_add_f32_e32 v44, v12, v16
	v_mul_f32_e32 v47, 0x3fb8aa3b, v45
	v_mul_f32_e32 v45, 0xbfb8aa3b, v45
	v_mul_f32_e32 v46, 0x3fb8aa3b, v44
	v_exp_f32_e32 v45, v45
	v_exp_f32_e32 v46, v46
	v_exp_f32_e32 v47, v47
	v_mul_f32_e32 v44, 0xbfb8aa3b, v44
	v_exp_f32_e32 v44, v44
	v_lshlrev_b32_e32 v48, 16, v43
	v_and_b32_e32 v43, 0xffff0000, v43
	v_mul_f32_e32 v43, v45, v43
	v_lshlrev_b32_e32 v45, 16, v41
	v_and_b32_e32 v41, 0xffff0000, v41
	v_mul_f32_e32 v45, v46, v45
	v_mul_f32_e32 v41, v47, v41
	v_cvt_pk_bf16_f32 v41, v45, v41
	v_add_f32_e32 v45, v5, v17
	v_mul_f32_e32 v44, v44, v48
	ds_write_b32 v117, v41 offset:1088
	v_cvt_pk_bf16_f32 v41, v44, v43
	v_mul_f32_e32 v47, 0x3fb8aa3b, v45
	v_mul_f32_e32 v45, 0xbfb8aa3b, v45
	ds_write_b32 v114, v41 offset:1088
	v_mul_f32_e32 v41, v28, v44
	v_add_f32_e32 v44, v13, v16
	v_exp_f32_e32 v45, v45
	v_mul_f32_e32 v46, 0x3fb8aa3b, v44
	v_exp_f32_e32 v47, v47
	v_exp_f32_e32 v46, v46
	v_mul_f32_e32 v44, 0xbfb8aa3b, v44
	v_exp_f32_e32 v44, v44
	v_lshlrev_b32_e32 v48, 16, v38
	v_and_b32_e32 v38, 0xffff0000, v38
	v_mul_f32_e32 v38, v45, v38
	v_lshlrev_b32_e32 v45, 16, v36
	v_and_b32_e32 v36, 0xffff0000, v36
	v_mul_f32_e32 v36, v47, v36
	v_mul_f32_e32 v45, v46, v45
	v_cvt_pk_bf16_f32 v36, v45, v36
	v_mul_f32_e32 v44, v44, v48
	ds_write_b32 v117, v36 offset:1360
	v_cvt_pk_bf16_f32 v36, v44, v38
	v_add_f32_e32 v45, v6, v17
	ds_write_b32 v114, v36 offset:1360
	v_mul_f32_e32 v36, v28, v44
	v_add_f32_e32 v44, v14, v16
	v_mul_f32_e32 v47, 0x3fb8aa3b, v45
	v_mul_f32_e32 v45, 0xbfb8aa3b, v45
	v_mul_f32_e32 v46, 0x3fb8aa3b, v44
	v_exp_f32_e32 v45, v45
	v_exp_f32_e32 v46, v46
	v_exp_f32_e32 v47, v47
	v_mul_f32_e32 v44, 0xbfb8aa3b, v44
	v_exp_f32_e32 v44, v44
	s_waitcnt vmcnt(16)
; __device__ __forceinline__ unsigned cvt_pk_bf16(float lo, float hi) { unsigned r; asm volatile("v_cvt_pk_bf16_f32 %0, %1, %2" : "=v"(r) : "v"(lo), "v"(hi)); return r; }
; __device__ __forceinline__ float bf_lo(unsigned u) { return __uint_as_float(u << 16); }
; __device__ __forceinline__ float bf_hi(unsigned u) { return __uint_as_float(u & 0xffff0000u); }
; #define LBAR() do { asm volatile("s_waitcnt lgkmcnt(0)" ::: "memory"); __builtin_amdgcn_s_barrier(); asm volatile("" ::: "memory"); } while (0)
; __device__ __forceinline__ void gla_phase(unsigned char* lds, const bf16_t* __restrict__ Z1, bf16_t* __restrict__ Of, bf16_t* __restrict__ Ob, int bi, int nb, int nitems) {
;     ...
;                 for (int tt = 0; tt < 8; ++tt) { const float ba = offa + ga[tt], bb = offb + gb[tt];
;                     const float ea = __expf(ba), eb = __expf(bb), iea = __expf(-ba), ieb = __expf(-bb);
;                     const float ksa = bf_lo(rk[tt]) * iea, ksb = bf_hi(rk[tt]) * ieb;
;                     *(unsigned*)(QSy + (8 * w + tt) * 136 + d2) = cvt_pk_bf16(bf_lo(rq[tt]) * ea, bf_hi(rq[tt]) * eb);
;                     *(unsigned*)(KS + (8 * w + tt) * 136 + d2) = cvt_pk_bf16(ksa, ksb);
;                     kda[tt] = ksa * eta; kdb[tt] = ksb * etb; }
;                 u32x4 ka, kb;
;                 ka.x = cvt_pk_bf16(kda[0], kda[1]); ka.y = cvt_pk_bf16(kda[2], kda[3]); ka.z = cvt_pk_bf16(kda[4], kda[5]); ka.w = cvt_pk_bf16(kda[6], kda[7]);
;                 kb.x = cvt_pk_bf16(kdb[0], kdb[1]); kb.y = cvt_pk_bf16(kdb[2], kdb[3]); kb.z = cvt_pk_bf16(kdb[4], kdb[5]); kb.w = cvt_pk_bf16(kdb[6], kdb[7]);
;                 *(u32x4*)(KDy + d2 * 72 + 8 * w) = ka; *(u32x4*)(KDy + (d2 + 1) * 72 + 8 * w) = kb;
;                 if (pref) { const size_t co = (size_t)(cnn * 64) * NZ1;
; #pragma unroll
;                     for (int tt = 0; tt < 8; ++tt) { const size_t o = co + (size_t)tt * NZ1; rq[tt] = *(const unsigned*)(zq + o); rk[tt] = *(const unsigned*)(zk + o); } }
;             }
;             LBAR();
	v_lshlrev_b32_e32 v48, 16, v39
	v_and_b32_e32 v39, 0xffff0000, v39
	v_mul_f32_e32 v39, v45, v39
	v_lshlrev_b32_e32 v45, 16, v37
	v_and_b32_e32 v37, 0xffff0000, v37
	v_mul_f32_e32 v45, v46, v45
	v_mul_f32_e32 v37, v47, v37
	v_add_f32_e32 v17, v7, v17
	v_cvt_pk_bf16_f32 v37, v45, v37
	v_mul_f32_e32 v45, 0x3fb8aa3b, v17
	v_mul_f32_e32 v17, 0xbfb8aa3b, v17
	v_mul_f32_e32 v44, v44, v48
	ds_write_b32 v117, v37 offset:1632
	v_cvt_pk_bf16_f32 v37, v44, v39
	v_add_f32_e32 v16, v15, v16
	v_exp_f32_e32 v17, v17
	ds_write_b32 v114, v37 offset:1632
	v_mul_f32_e32 v37, v28, v44
	v_mul_f32_e32 v44, 0x3fb8aa3b, v16
	v_exp_f32_e32 v45, v45
	v_mul_f32_e32 v16, 0xbfb8aa3b, v16
	v_exp_f32_e32 v44, v44
	v_exp_f32_e32 v16, v16
	v_lshlrev_b32_e32 v46, 16, v35
	v_and_b32_e32 v35, 0xffff0000, v35
	v_mul_f32_e32 v17, v17, v35
	v_lshlrev_b32_e32 v35, 16, v34
	v_and_b32_e32 v34, 0xffff0000, v34
	v_mul_f32_e32 v34, v45, v34
	v_mul_f32_e32 v16, v16, v46
	v_mul_f32_e32 v35, v44, v35
	v_cvt_pk_bf16_f32 v34, v35, v34
	v_mul_f32_e32 v18, v28, v18
	v_mul_f32_e32 v19, v28, v19
	v_mul_f32_e32 v21, v29, v21
	v_mul_f32_e32 v22, v28, v22
	v_mul_f32_e32 v23, v29, v23
	v_mul_f32_e32 v42, v29, v42
	v_mul_f32_e32 v43, v29, v43
	v_mul_f32_e32 v38, v29, v38
	v_mul_f32_e32 v39, v29, v39
	ds_write_b32 v117, v34 offset:1904
	v_cvt_pk_bf16_f32 v34, v16, v17
	v_mul_f32_e32 v28, v28, v16
	v_mul_f32_e32 v29, v29, v17
	ds_write_b32 v114, v34 offset:1904
	v_cvt_pk_bf16_f32 v16, v18, v19
	v_cvt_pk_bf16_f32 v17, v22, v40
	v_cvt_pk_bf16_f32 v18, v41, v36
	v_cvt_pk_bf16_f32 v19, v37, v28
	v_cvt_pk_bf16_f32 v20, v20, v21
	v_cvt_pk_bf16_f32 v21, v23, v42
	v_cvt_pk_bf16_f32 v22, v43, v38
	v_cvt_pk_bf16_f32 v23, v39, v29
	v_lshl_add_u64 v[28:29], v[90:91], 0, s[76:77]
	v_lshl_add_u64 v[34:35], v[96:97], 0, s[76:77]
	global_load_dword v142, v[24:25], off
	global_load_dword v143, v[24:25], off offset:1024
	global_load_dword v144, v[26:27], off
	global_load_dword v145, v[30:31], off
	global_load_dword v146, v[32:33], off
	global_load_dword v147, v[50:51], off
	global_load_dword v148, v[28:29], off
	global_load_dword v149, v[34:35], off
	v_lshl_add_u64 v[24:25], v[90:91], 0, s[78:79]
	v_lshl_add_u64 v[26:27], v[96:97], 0, s[78:79]
	v_lshl_add_u64 v[28:29], v[90:91], 0, s[80:81]
	v_lshl_add_u64 v[30:31], v[96:97], 0, s[80:81]
	v_lshl_add_u64 v[32:33], v[90:91], 0, s[82:83]
	v_lshl_add_u64 v[34:35], v[96:97], 0, s[82:83]
	v_lshl_add_u64 v[36:37], v[90:91], 0, s[84:85]
	v_lshl_add_u64 v[38:39], v[96:97], 0, s[84:85]
	global_load_dword v150, v[24:25], off
	global_load_dword v151, v[26:27], off
	global_load_dword v153, v[28:29], off
	global_load_dword v154, v[30:31], off
	global_load_dword v155, v[32:33], off
	global_load_dword v156, v[34:35], off
	global_load_dword v157, v[36:37], off
	global_load_dword v158, v[38:39], off
	s_and_b64 s[10:11], s[54:55], exec
	v_readlane_b32 s8, v245, 25
	v_readlane_b32 s10, v245, 29
	s_cselect_b32 s8, s10, s8
	v_readlane_b32 s10, v245, 24
	v_readlane_b32 s11, v245, 28
	s_cselect_b32 s10, s11, s10
	s_add_u32 s12, s10, s5
	s_addc_u32 s8, s8, 0
	s_ashr_i32 s73, s72, 31
	s_lshl_b64 s[10:11], s[72:73], 11
	s_add_u32 s10, s12, s10
	s_addc_u32 s8, s8, s11
	s_lshl_b32 s0, s0, 1
	s_add_u32 s0, s10, s0
	s_addc_u32 s8, s8, 0
	s_add_u32 s10, s0, s74
	s_addc_u32 s11, s8, 0
	v_lshl_add_u64 v[24:25], v[84:85], 1, s[10:11]
	ds_write_b128 v115, v[16:19] offset:17408
	ds_write_b128 v115, v[20:23] offset:17552
	v_lshl_add_u64 v[24:25], v[24:25], 0, v[82:83]
	v_mov_b32_e32 v89, v83
	s_waitcnt lgkmcnt(0)
	s_barrier
; __device__ __forceinline__ unsigned short f2bf_rne(float f) { unsigned u = __float_as_uint(f); u += 0x7FFFu + ((u >> 16) & 1u); return (unsigned short)(u >> 16); }
; #define LBAR() do { asm volatile("s_waitcnt lgkmcnt(0)" ::: "memory"); __builtin_amdgcn_s_barrier(); asm volatile("" ::: "memory"); } while (0)
; #define GLA_WAIT() do { asm volatile("s_waitcnt lgkmcnt(0)" ::: "memory"); __builtin_amdgcn_sched_barrier(0); } while (0)
; __device__ __forceinline__ void gla_phase(unsigned char* lds, const bf16_t* __restrict__ Z1, bf16_t* __restrict__ Of, bf16_t* __restrict__ Ob, int bi, int nb, int nitems) {
;     ...
;         f32x4 S[8];
; #pragma unroll
;         for (int mb = 0; mb < 8; ++mb) S[mb] = (f32x4){0.f, 0.f, 0.f, 0.f};
;     ...
;             if (prod) {
;                 const int tb = w >> 1; f32x4 p0 = (f32x4){0.f, 0.f, 0.f, 0.f}, p1 = p0;
;                 bf16x8 pa[4], pb0[4], pb1[4];
; #pragma unroll
;                 for (int kk = 0; kk < 4; ++kk) { pa[kk] = *(const bf16x8*)(QSy + (16 * tb + r) * 136 + 32 * kk + 8 * q);
;                     pb0[kk] = *(const bf16x8*)(KS + (32 * (w & 1) + r) * 136 + 32 * kk + 8 * q); pb1[kk] = *(const bf16x8*)(KS + (32 * (w & 1) + 16 + r) * 136 + 32 * kk + 8 * q); }
;                 GLA_WAIT();
; #pragma unroll
;                 for (int kk = 0; kk < 4; ++kk) { p0 = __builtin_amdgcn_mfma_f32_16x16x32_bf16(pa[kk], pb0[kk], p0, 0, 0, 0); p1 = __builtin_amdgcn_mfma_f32_16x16x32_bf16(pa[kk], pb1[kk], p1, 0, 0, 0); }
;                 const int j0 = 32 * (w & 1) + r, j1 = j0 + 16;
; #pragma unroll
;                 for (int i = 0; i < 4; ++i) { const int it = 16 * tb + 4 * q + i;
;                     const bool k0 = dir ? (j0 > it) : (j0 <= it), k1 = dir ? (j1 > it) : (j1 <= it);
;                     PPy[it * 72 + j0] = attn::f2bf_rne(k0 ? p0[i] : 0.f); PPy[it * 72 + j1] = attn::f2bf_rne(k1 ? p1[i] : 0.f); }
;             }
;             LBAR();
	v_lshl_add_u64 v[100:101], v[24:25], 0, v[88:89]
	ds_read_b128 v[16:19], v118
	ds_read_b128 v[20:23], v118 offset:64
	ds_read_b128 v[24:27], v110
	ds_read_b128 v[28:31], v110 offset:64
	ds_read_b128 v[32:35], v110 offset:4352
	ds_read_b128 v[36:39], v110 offset:4416
	ds_read_b128 v[40:43], v118 offset:128
	ds_read_b128 v[44:47], v118 offset:192
	ds_read_b128 v[48:51], v110 offset:128
	ds_read_b128 v[52:55], v110 offset:192
	ds_read_b128 v[56:59], v110 offset:4480
	ds_read_b128 v[60:63], v110 offset:4544
	s_waitcnt lgkmcnt(0)
	s_and_b64 s[10:11], s[54:55], exec
	s_mov_b32 s9, 0
	s_cselect_b32 s8, 2, -2
	s_xor_b64 s[72:73], s[38:39], s[54:55]
	s_xor_b64 s[74:75], s[40:41], s[54:55]
	s_xor_b64 s[76:77], s[42:43], s[54:55]
	s_xor_b64 s[78:79], s[44:45], s[54:55]
	s_xor_b64 s[80:81], s[46:47], s[54:55]
	s_xor_b64 s[82:83], s[48:49], s[54:55]
	s_xor_b64 s[84:85], s[50:51], s[54:55]
	s_xor_b64 s[86:87], s[52:53], s[54:55]
	s_waitcnt lgkmcnt(9)
	v_mfma_f32_16x16x32_bf16 v[24:27], v[16:19], v[24:27], 0
	s_mov_b32 s10, 31
	s_waitcnt lgkmcnt(7)
	v_mfma_f32_16x16x32_bf16 v[16:19], v[16:19], v[32:35], 0
	v_mfma_f32_16x16x32_bf16 v[24:27], v[20:23], v[28:31], v[24:27]
	s_waitcnt lgkmcnt(6)
	v_mfma_f32_16x16x32_bf16 v[16:19], v[20:23], v[36:39], v[16:19]
	s_waitcnt lgkmcnt(3)
	v_mfma_f32_16x16x32_bf16 v[20:23], v[40:43], v[48:51], v[24:27]
	s_waitcnt lgkmcnt(1)
	v_mfma_f32_16x16x32_bf16 v[16:19], v[40:43], v[56:59], v[16:19]
	v_mfma_f32_16x16x32_bf16 v[20:23], v[44:47], v[52:55], v[20:23]
	s_waitcnt lgkmcnt(0)
	v_mfma_f32_16x16x32_bf16 v[16:19], v[44:47], v[60:63], v[16:19]
	s_nop 5
	v_cndmask_b32_e64 v20, 0, v20, s[72:73]
	v_bfe_u32 v24, v20, 16, 1
	v_add3_u32 v20, v20, v24, s7
	v_cndmask_b32_e64 v16, 0, v16, s[74:75]
	ds_write_b16_d16_hi v121, v20 offset:54272
	v_bfe_u32 v20, v16, 16, 1
	v_add3_u32 v16, v16, v20, s7
	ds_write_b16_d16_hi v121, v16 offset:54304
	v_cndmask_b32_e64 v16, 0, v21, s[76:77]
	v_bfe_u32 v20, v16, 16, 1
	v_add3_u32 v16, v16, v20, s7
	ds_write_b16_d16_hi v122, v16 offset:54272
	v_cndmask_b32_e64 v16, 0, v17, s[78:79]
	v_bfe_u32 v17, v16, 16, 1
	v_add3_u32 v16, v16, v17, s7
	ds_write_b16_d16_hi v122, v16 offset:54304
	v_cndmask_b32_e64 v16, 0, v22, s[80:81]
	v_bfe_u32 v17, v16, 16, 1
	v_add3_u32 v16, v16, v17, s7
	ds_write_b16_d16_hi v123, v16 offset:54272
	v_cndmask_b32_e64 v16, 0, v18, s[82:83]
	v_bfe_u32 v17, v16, 16, 1
	v_add3_u32 v16, v16, v17, s7
	ds_write_b16_d16_hi v123, v16 offset:54304
	v_cndmask_b32_e64 v16, 0, v23, s[84:85]
	v_bfe_u32 v17, v16, 16, 1
	v_add3_u32 v16, v16, v17, s7
	ds_write_b16_d16_hi v124, v16 offset:54272
	v_cndmask_b32_e64 v16, 0, v19, s[86:87]
	v_bfe_u32 v17, v16, 16, 1
	v_add3_u32 v16, v16, v17, s7
	ds_write_b16_d16_hi v124, v16 offset:54304
	s_waitcnt lgkmcnt(0)
	s_barrier
	v_mov_b32_e32 v16, 0
	v_mov_b32_e32 v17, v16
	v_mov_b32_e32 v18, v16
	v_mov_b32_e32 v19, v16
	v_mov_b32_e32 v20, v16
	v_mov_b32_e32 v21, v16
	v_mov_b32_e32 v22, v16
	v_mov_b32_e32 v23, v16
	v_mov_b32_e32 v24, v16
	v_mov_b32_e32 v25, v16
	v_mov_b32_e32 v26, v16
	v_mov_b32_e32 v27, v16
	v_mov_b32_e32 v28, v16
	v_mov_b32_e32 v29, v16
	v_mov_b32_e32 v30, v16
	v_mov_b32_e32 v31, v16
	v_mov_b32_e32 v32, v16
	v_mov_b32_e32 v33, v16
	v_mov_b32_e32 v34, v16
	v_mov_b32_e32 v35, v16
	v_mov_b32_e32 v36, v16
	v_mov_b32_e32 v37, v16
	v_mov_b32_e32 v38, v16
	v_mov_b32_e32 v39, v16
	v_mov_b32_e32 v40, v16
	v_mov_b32_e32 v41, v16
	v_mov_b32_e32 v42, v16
	v_mov_b32_e32 v43, v16
	v_mov_b32_e32 v44, v16
	v_mov_b32_e32 v45, v16
	v_mov_b32_e32 v46, v16
	v_mov_b32_e32 v47, v16
	s_branch .LBB0_592

; __device__ __forceinline__ void gla_phase(unsigned char* lds, const bf16_t* __restrict__ Z1, bf16_t* __restrict__ Of, bf16_t* __restrict__ Ob, int bi, int nb, int nitems) {
;     ...
;         for (int step = -1; step < 32; ++step) {
;             const int c = dir ? 31 - step : step;
;             const int cnn = dir ? c - 2 : c + 2;
;             const bool prod = step + 1 < 32, cons = step >= 0, pref = step + 2 < 32;
;             unsigned char* bx = lds + (step & 1) * BUF_B;
;             unsigned char* by = lds + ((step + 1) & 1) * BUF_B;
;             bf16_t* QSx = (bf16_t*)bx; bf16_t* KDx = (bf16_t*)(bx + QS_B); bf16_t* VTx = (bf16_t*)(bx + QS_B + KD_B); bf16_t* PPx = (bf16_t*)(bx + QS_B + KD_B + VT_B); float* DECx = (float*)(bx + QS_B + KD_B + VT_B + PP_B);
;             bf16_t* QSy = (bf16_t*)by; bf16_t* KDy = (bf16_t*)(by + QS_B); bf16_t* VTy = (bf16_t*)(by + QS_B + KD_B); bf16_t* PPy = (bf16_t*)(by + QS_B + KD_B + VT_B); float* DECy = (float*)(by + QS_B + KD_B + VT_B + PP_B);
;             f32x4 O[4];
;             O[0] = (f32x4){0.f, 0.f, 0.f, 0.f}; O[1] = O[0]; O[2] = O[0]; O[3] = O[0];
;             if (cons) {
;                 bf16x8 sbf[4];
; #pragma unroll
;                 for (int kk = 0; kk < 4; ++kk) { u32x4 t; t.x = cvt_pk_bf16(S[2 * kk][0], S[2 * kk][1]); t.y = cvt_pk_bf16(S[2 * kk][2], S[2 * kk][3]); t.z = cvt_pk_bf16(S[2 * kk + 1][0], S[2 * kk + 1][1]); t.w = cvt_pk_bf16(S[2 * kk + 1][2], S[2 * kk + 1][3]); sbf[kk] = *reinterpret_cast<bf16x8*>(&t); }
; #pragma unroll
;                 for (int tp = 0; tp < 2; ++tp) { u32x4 af[2][4];
; #pragma unroll
;                     for (int t2 = 0; t2 < 2; ++t2)
; #pragma unroll
;                         for (int kk = 0; kk < 4; ++kk) { const bf16_t* ap = QSx + (16 * (2 * tp + t2) + r) * 136 + 32 * kk + 4 * q; const u32x2 lo = *(const u32x2*)ap, hi = *(const u32x2*)(ap + 16); af[t2][kk] = (u32x4){lo.x, lo.y, hi.x, hi.y}; }
;                     GLA_WAIT();
; #pragma unroll
;                     for (int t2 = 0; t2 < 2; ++t2)
; #pragma unroll
;                         for (int kk = 0; kk < 4; ++kk) O[2 * tp + t2] = __builtin_amdgcn_mfma_f32_16x16x32_bf16(*reinterpret_cast<bf16x8*>(&af[t2][kk]), sbf[kk], O[2 * tp + t2], 0, 0, 0);
;                     __builtin_amdgcn_sched_barrier(0); }
;             }
;             if (prod) {
; #pragma unroll
.LBB0_592:
	s_and_b64 s[12:13], s[54:55], exec
	s_cselect_b32 s0, s9, s10
	s_mov_b32 s88, s9
	s_add_i32 s12, s0, s8
	s_add_i32 s9, s9, 1
	s_cmp_lg_u32 s88, 31
	s_cselect_b64 s[94:95], -1, 0
	s_cmp_lt_u32 s88, 30
	s_cselect_b64 s[92:93], -1, 0
	s_bitcmp1_b32 s88, 0
	s_cselect_b32 s11, 0xfa00, 0
	s_add_i32 s13, s11, 0
	v_add3_u32 v89, s13, v105, v111
	v_add_u32_e32 v102, 0x1000, v89
	v_cvt_pk_bf16_f32 v56, v16, v17
	v_cvt_pk_bf16_f32 v57, v18, v19
	v_cvt_pk_bf16_f32 v58, v20, v21
	v_cvt_pk_bf16_f32 v59, v22, v23
	v_cvt_pk_bf16_f32 v64, v24, v25
	v_cvt_pk_bf16_f32 v65, v26, v27
	v_cvt_pk_bf16_f32 v66, v28, v29
	v_cvt_pk_bf16_f32 v67, v30, v31
	v_cvt_pk_bf16_f32 v68, v32, v33
	v_cvt_pk_bf16_f32 v69, v34, v35
	v_cvt_pk_bf16_f32 v70, v36, v37
	v_cvt_pk_bf16_f32 v71, v38, v39
	v_cvt_pk_bf16_f32 v72, v40, v41
	v_cvt_pk_bf16_f32 v73, v42, v43
	v_cvt_pk_bf16_f32 v74, v44, v45
	v_cvt_pk_bf16_f32 v75, v46, v47
	ds_read2_b64 v[48:51], v89 offset1:4
	ds_read2_b64 v[52:55], v89 offset0:8 offset1:12
	ds_read2_b64 v[60:63], v89 offset0:16 offset1:20
	ds_read2_b64 v[76:79], v89 offset0:24 offset1:28
	ds_read2_b64 v[160:163], v102 offset0:32 offset1:36
	ds_read2_b64 v[166:169], v102 offset0:40 offset1:44
	ds_read2_b64 v[170:173], v102 offset0:48 offset1:52
	ds_read2_b64 v[182:185], v102 offset0:56 offset1:60
	s_bitcmp1_b32 s9, 0
	s_waitcnt lgkmcnt(0)
	s_cselect_b32 s11, 0xfa00, 0
	s_add_i32 s11, s11, 0
	s_cmp_eq_u32 s88, 31
	s_waitcnt lgkmcnt(7)
	v_mfma_f32_16x16x32_bf16 v[48:51], v[48:51], v[56:59], 0
	s_waitcnt lgkmcnt(6)
	v_mfma_f32_16x16x32_bf16 v[48:51], v[52:55], v[64:67], v[48:51]
	s_waitcnt lgkmcnt(5)
	v_mfma_f32_16x16x32_bf16 v[48:51], v[60:63], v[68:71], v[48:51]
	s_waitcnt lgkmcnt(4)
	v_mfma_f32_16x16x32_bf16 v[52:55], v[76:79], v[72:75], v[48:51]
	s_waitcnt lgkmcnt(3)
	v_mfma_f32_16x16x32_bf16 v[48:51], v[160:163], v[56:59], 0
	s_waitcnt lgkmcnt(2)
	v_mfma_f32_16x16x32_bf16 v[48:51], v[166:169], v[64:67], v[48:51]
	s_waitcnt lgkmcnt(1)
	v_mfma_f32_16x16x32_bf16 v[48:51], v[170:173], v[68:71], v[48:51]
	s_waitcnt lgkmcnt(0)
	v_mfma_f32_16x16x32_bf16 v[48:51], v[182:185], v[72:75], v[48:51]
	v_add_u32_e32 v102, 0x2000, v89
	v_add_u32_e32 v89, 0x3000, v89
	ds_read2_b64 v[60:63], v102 offset0:64 offset1:68
	ds_read2_b64 v[76:79], v102 offset0:72 offset1:76
	ds_read2_b64 v[160:163], v102 offset0:80 offset1:84
	ds_read2_b64 v[166:169], v102 offset0:88 offset1:92
	ds_read2_b64 v[170:173], v89 offset0:96 offset1:100
	ds_read2_b64 v[182:185], v89 offset0:104 offset1:108
	ds_read2_b64 v[190:193], v89 offset0:112 offset1:116
	ds_read2_b64 v[194:197], v89 offset0:120 offset1:124
	s_waitcnt lgkmcnt(0)
	s_waitcnt lgkmcnt(7)
	v_mfma_f32_16x16x32_bf16 v[60:63], v[60:63], v[56:59], 0
	s_waitcnt lgkmcnt(3)
	v_mfma_f32_16x16x32_bf16 v[56:59], v[170:173], v[56:59], 0
	v_mfma_f32_16x16x32_bf16 v[60:63], v[76:79], v[64:67], v[60:63]
	s_waitcnt lgkmcnt(2)
	v_mfma_f32_16x16x32_bf16 v[56:59], v[182:185], v[64:67], v[56:59]
	v_mfma_f32_16x16x32_bf16 v[60:63], v[160:163], v[68:71], v[60:63]
	s_waitcnt lgkmcnt(1)
	v_mfma_f32_16x16x32_bf16 v[56:59], v[190:193], v[68:71], v[56:59]
	v_mfma_f32_16x16x32_bf16 v[60:63], v[166:169], v[72:75], v[60:63]
	s_waitcnt lgkmcnt(0)
	v_mfma_f32_16x16x32_bf16 v[56:59], v[194:197], v[72:75], v[56:59]
	s_cbranch_scc1 .LBB0_599
	s_waitcnt vmcnt(31)
	v_lshlrev_b32_e32 v64, 16, v126
	v_and_b32_e32 v65, 0xffff0000, v126
	s_waitcnt vmcnt(29)
	v_lshlrev_b32_e32 v66, 16, v128
	v_and_b32_e32 v67, 0xffff0000, v128
	s_waitcnt vmcnt(27)
	v_lshlrev_b32_e32 v68, 16, v130
	v_and_b32_e32 v69, 0xffff0000, v130
	s_waitcnt vmcnt(25)
	v_lshlrev_b32_e32 v70, 16, v132
	v_and_b32_e32 v71, 0xffff0000, v132
	s_waitcnt vmcnt(23)
	v_lshlrev_b32_e32 v72, 16, v134
	v_and_b32_e32 v73, 0xffff0000, v134
	s_waitcnt vmcnt(21)
	v_lshlrev_b32_e32 v76, 16, v136
	v_and_b32_e32 v77, 0xffff0000, v136
	s_waitcnt vmcnt(19)
	v_lshlrev_b32_e32 v102, 16, v138
	v_and_b32_e32 v103, 0xffff0000, v138
	s_waitcnt vmcnt(17)
	v_lshlrev_b32_e32 v74, 16, v140
	v_and_b32_e32 v75, 0xffff0000, v140
	s_andn2_b64 vcc, exec, s[96:97]
	s_mov_b64 s[88:89], -1
	s_cbranch_vccnz .LBB0_595
	v_pk_add_f32 v[6:7], v[102:103], v[74:75]
	v_mov_b32_e32 v15, v74
	v_pk_add_f32 v[4:5], v[6:7], v[76:77]
	v_mov_b32_e32 v14, v6
	v_pk_add_f32 v[160:161], v[4:5], v[72:73]
	v_mov_b32_e32 v13, v4
	v_pk_add_f32 v[2:3], v[160:161], v[70:71]
	v_mov_b32_e32 v12, v160
	v_pk_add_f32 v[162:163], v[2:3], v[68:69]
	v_mov_b32_e32 v11, v2
	v_pk_add_f32 v[0:1], v[162:163], v[66:67]
	v_mov_b32_e32 v10, v162
	v_pk_add_f32 v[78:79], v[0:1], v[64:65]
	v_mov_b32_e32 v9, v0
	v_mov_b32_e32 v8, v78
	v_mov_b32_e32 v0, v79
	v_mov_b32_e32 v2, v163
	v_mov_b32_e32 v4, v161
	v_mov_b32_e32 v6, v7
	v_mov_b32_e32 v7, v75
	s_mov_b64 s[88:89], 0

; #define LBAR() do { asm volatile("s_waitcnt lgkmcnt(0)" ::: "memory"); __builtin_amdgcn_s_barrier(); asm volatile("" ::: "memory"); } while (0)
; #define GLA_WAIT() do { asm volatile("s_waitcnt lgkmcnt(0)" ::: "memory"); __builtin_amdgcn_sched_barrier(0); } while (0)
; __device__ __forceinline__ void gla_phase(unsigned char* lds, const bf16_t* __restrict__ Z1, bf16_t* __restrict__ Of, bf16_t* __restrict__ Ob, int bi, int nb, int nitems) {
;     ...
;                 { u32x4 va, vb;
;                   va.x = (rv[0] & 0xffffu) | (rv[1] << 16); va.y = (rv[2] & 0xffffu) | (rv[3] << 16); va.z = (rv[4] & 0xffffu) | (rv[5] << 16); va.w = (rv[6] & 0xffffu) | (rv[7] << 16);
;                   vb.x = (rv[0] >> 16) | (rv[1] & 0xffff0000u); vb.y = (rv[2] >> 16) | (rv[3] & 0xffff0000u); vb.z = (rv[4] >> 16) | (rv[5] & 0xffff0000u); vb.w = (rv[6] >> 16) | (rv[7] & 0xffff0000u);
;                   *(u32x4*)(VTy + d2 * 72 + 8 * w) = va; *(u32x4*)(VTy + (d2 + 1) * 72 + 8 * w) = vb; }
;                 if (pref) { const size_t co = (size_t)(cnn * 64) * NZ1;
; #pragma unroll
;                     for (int tt = 0; tt < 8; ++tt) { const size_t o = co + (size_t)tt * NZ1; rg[tt] = *(const unsigned*)(zg + o); rv[tt] = *(const unsigned*)(zv + o); } }
;             }
;             LBAR();
;             if (cons) {
;                 const bf16x8 v0 = *(const bf16x8*)(VTx + (16 * w + r) * 72 + 8 * q), v1 = *(const bf16x8*)(VTx + (16 * w + r) * 72 + 32 + 8 * q);
; #pragma unroll
;                 for (int hb = 0; hb < 2; ++hb) { bf16x8 kd0[4], kd1[4]; f32x4 dc[4];
; #pragma unroll
;                     for (int m4 = 0; m4 < 4; ++m4) { const int mb = 4 * hb + m4; dc[m4] = *(const f32x4*)(DECx + 16 * mb + 4 * q);
;                         kd0[m4] = *(const bf16x8*)(KDx + (16 * mb + r) * 72 + 8 * q); kd1[m4] = *(const bf16x8*)(KDx + (16 * mb + r) * 72 + 32 + 8 * q); }
;                     GLA_WAIT();
; #pragma unroll
;                     for (int m4 = 0; m4 < 4; ++m4) { const int mb = 4 * hb + m4; S[mb] = S[mb] * dc[m4];
;                         S[mb] = __builtin_amdgcn_mfma_f32_16x16x32_bf16(kd0[m4], v0, S[mb], 0, 0, 0); S[mb] = __builtin_amdgcn_mfma_f32_16x16x32_bf16(kd1[m4], v1, S[mb], 0, 0, 0); }
.LBB0_597:
	v_and_b32_e32 v64, 0xffff, v127
	v_and_b32_e32 v65, 0xffff, v131
	v_and_b32_e32 v66, 0xffff, v135
	v_and_b32_e32 v67, 0xffff, v139
	v_lshrrev_b32_e32 v68, 16, v127
	v_lshrrev_b32_e32 v69, 16, v131
	v_lshrrev_b32_e32 v70, 16, v135
	v_lshrrev_b32_e32 v71, 16, v139
	v_lshlrev_b32_e32 v72, 1, v81
	v_lshl_or_b32 v64, v129, 16, v64
	v_lshl_or_b32 v65, v133, 16, v65
	v_lshl_or_b32 v66, v137, 16, v66
	s_waitcnt vmcnt(16)
	v_lshl_or_b32 v67, v141, 16, v67
	v_and_or_b32 v68, v129, s6, v68
	v_and_or_b32 v69, v133, s6, v69
	v_and_or_b32 v70, v137, s6, v70
	v_and_or_b32 v71, v141, s6, v71
	v_add3_u32 v72, s11, v106, v72
	s_andn2_b64 vcc, exec, s[92:93]
	ds_write_b64 v125, v[78:79]
	ds_write_b128 v72, v[64:67] offset:35840
	ds_write_b128 v72, v[68:71] offset:35984
	s_cbranch_vccnz .LBB0_599
	s_lshl_b32 s88, s12, 6
	s_ashr_i32 s89, s88, 31
	s_lshl_b64 s[88:89], s[88:89], 13
	v_lshl_add_u64 v[64:65], v[98:99], 0, s[88:89]
	global_load_dword v126, v[64:65], off
	v_lshl_add_u64 v[64:65], v[92:93], 0, s[88:89]
	s_or_b32 vcc_lo, s88, 0x2000
	s_mov_b32 vcc_hi, s89
	global_load_dword v127, v[64:65], off offset:2048
	v_lshl_add_u64 v[64:65], v[98:99], 0, vcc
	global_load_dword v128, v[64:65], off
	v_lshl_add_u64 v[64:65], v[94:95], 0, vcc
	s_or_b32 vcc_lo, s88, 0x4000
	global_load_dword v129, v[64:65], off
	v_lshl_add_u64 v[64:65], v[98:99], 0, vcc
	global_load_dword v130, v[64:65], off
	v_lshl_add_u64 v[64:65], v[94:95], 0, vcc
	s_or_b32 vcc_lo, s88, 0x6000
	global_load_dword v131, v[64:65], off
	v_lshl_add_u64 v[64:65], v[98:99], 0, vcc
	global_load_dword v132, v[64:65], off
	v_lshl_add_u64 v[64:65], v[94:95], 0, vcc
	s_or_b32 vcc_lo, s88, 0x8000
	global_load_dword v133, v[64:65], off
	v_lshl_add_u64 v[64:65], v[98:99], 0, vcc
	global_load_dword v134, v[64:65], off
	v_lshl_add_u64 v[64:65], v[94:95], 0, vcc
	s_or_b32 vcc_lo, s88, 0xa000
	global_load_dword v135, v[64:65], off
	v_lshl_add_u64 v[64:65], v[98:99], 0, vcc
	global_load_dword v136, v[64:65], off
	v_lshl_add_u64 v[64:65], v[94:95], 0, vcc
	s_or_b32 vcc_lo, s88, 0xc000
	global_load_dword v137, v[64:65], off
	v_lshl_add_u64 v[64:65], v[98:99], 0, vcc
	global_load_dword v138, v[64:65], off
	v_lshl_add_u64 v[64:65], v[94:95], 0, vcc
	s_or_b32 s88, s88, 0xe000
	global_load_dword v139, v[64:65], off
	v_lshl_add_u64 v[64:65], v[98:99], 0, s[88:89]
	global_load_dword v140, v[64:65], off
	v_lshl_add_u64 v[64:65], v[94:95], 0, s[88:89]
	global_load_dword v141, v[64:65], off
.LBB0_599:
	v_lshlrev_b32_e32 v89, 1, v105
	s_waitcnt lgkmcnt(0)
	s_barrier
	v_add3_u32 v103, s13, v107, v89
	v_add3_u32 v102, s13, v112, v89
	ds_read_b128 v[64:67], v103 offset:35840
	ds_read_b128 v[68:71], v103 offset:35904
	v_add_u32_e32 v159, s13, v108
	ds_read_b128 v[72:75], v102 offset:17408
	ds_read_b128 v[76:79], v102 offset:17472
	ds_read_b128 v[160:163], v159 offset:63488
	ds_read_b128 v[166:169], v159 offset:63552
	ds_read_b128 v[170:173], v102 offset:19712
	ds_read_b128 v[182:185], v102 offset:19776
	ds_read_b128 v[190:193], v102 offset:22016
	ds_read_b128 v[194:197], v102 offset:22080
	ds_read_b128 v[198:201], v159 offset:63616
	ds_read_b128 v[202:205], v159 offset:63680
	ds_read_b128 v[206:209], v102 offset:24320
	ds_read_b128 v[210:213], v102 offset:24384
	s_waitcnt lgkmcnt(0)
	s_waitcnt lgkmcnt(9)
	v_pk_mul_f32 v[16:17], v[16:17], v[160:161]
	v_pk_mul_f32 v[18:19], v[18:19], v[162:163]
	s_waitcnt lgkmcnt(8)
	v_pk_mul_f32 v[20:21], v[20:21], v[166:167]
	v_pk_mul_f32 v[22:23], v[22:23], v[168:169]
	s_waitcnt lgkmcnt(3)
	v_pk_mul_f32 v[24:25], v[24:25], v[198:199]
	v_pk_mul_f32 v[26:27], v[26:27], v[200:201]
	s_waitcnt lgkmcnt(2)
	v_pk_mul_f32 v[28:29], v[28:29], v[202:203]
	v_pk_mul_f32 v[30:31], v[30:31], v[204:205]
	v_mfma_f32_16x16x32_bf16 v[16:19], v[72:75], v[64:67], v[16:19]
	v_mfma_f32_16x16x32_bf16 v[20:23], v[170:173], v[64:67], v[20:23]
	v_mfma_f32_16x16x32_bf16 v[24:27], v[190:193], v[64:67], v[24:27]
	s_waitcnt lgkmcnt(1)
	v_mfma_f32_16x16x32_bf16 v[28:31], v[206:209], v[64:67], v[28:31]
	v_mfma_f32_16x16x32_bf16 v[16:19], v[76:79], v[68:71], v[16:19]
	v_mfma_f32_16x16x32_bf16 v[20:23], v[182:185], v[68:71], v[20:23]
	v_mfma_f32_16x16x32_bf16 v[24:27], v[194:197], v[68:71], v[24:27]
	s_waitcnt lgkmcnt(0)
	v_mfma_f32_16x16x32_bf16 v[28:31], v[210:213], v[68:71], v[28:31]
	ds_read_b128 v[72:75], v102 offset:26624
	ds_read_b128 v[76:79], v102 offset:26688
	ds_read_b128 v[160:163], v159 offset:63744
	ds_read_b128 v[166:169], v159 offset:63808
	ds_read_b128 v[170:173], v102 offset:28928
	ds_read_b128 v[182:185], v102 offset:28992
	ds_read_b128 v[190:193], v102 offset:31232
	ds_read_b128 v[194:197], v102 offset:31296
	ds_read_b128 v[198:201], v159 offset:63872
	ds_read_b128 v[202:205], v159 offset:63936
	ds_read_b128 v[206:209], v102 offset:33536
	ds_read_b128 v[210:213], v102 offset:33600
	s_waitcnt lgkmcnt(0)
	s_waitcnt lgkmcnt(9)
	v_pk_mul_f32 v[32:33], v[32:33], v[160:161]
	v_pk_mul_f32 v[34:35], v[34:35], v[162:163]
	s_waitcnt lgkmcnt(8)
	v_pk_mul_f32 v[36:37], v[36:37], v[166:167]
	v_pk_mul_f32 v[38:39], v[38:39], v[168:169]
	s_waitcnt lgkmcnt(3)
	v_pk_mul_f32 v[40:41], v[40:41], v[198:199]
	v_pk_mul_f32 v[42:43], v[42:43], v[200:201]
	s_waitcnt lgkmcnt(2)
	v_pk_mul_f32 v[44:45], v[44:45], v[202:203]
	v_pk_mul_f32 v[46:47], v[46:47], v[204:205]
	v_mfma_f32_16x16x32_bf16 v[32:35], v[72:75], v[64:67], v[32:35]
	v_mfma_f32_16x16x32_bf16 v[36:39], v[170:173], v[64:67], v[36:39]
	v_mfma_f32_16x16x32_bf16 v[40:43], v[190:193], v[64:67], v[40:43]
	s_waitcnt lgkmcnt(1)
	v_mfma_f32_16x16x32_bf16 v[44:47], v[206:209], v[64:67], v[44:47]
	v_mfma_f32_16x16x32_bf16 v[32:35], v[76:79], v[68:71], v[32:35]
	v_mfma_f32_16x16x32_bf16 v[36:39], v[182:185], v[68:71], v[36:39]
	v_mfma_f32_16x16x32_bf16 v[40:43], v[194:197], v[68:71], v[40:43]
	s_waitcnt lgkmcnt(0)
	v_mfma_f32_16x16x32_bf16 v[44:47], v[210:213], v[68:71], v[44:47]
	v_cndmask_b32_e64 v64, 0, 1, s[94:95]
	v_cmp_ne_u32_e64 s[88:89], 1, v64
	s_andn2_b64 vcc, exec, s[94:95]
	s_cbranch_vccnz .LBB0_604
; __device__ __forceinline__ unsigned cvt_pk_bf16(float lo, float hi) { unsigned r; asm volatile("v_cvt_pk_bf16_f32 %0, %1, %2" : "=v"(r) : "v"(lo), "v"(hi)); return r; }
; __device__ __forceinline__ float bf_lo(unsigned u) { return __uint_as_float(u << 16); }
; __device__ __forceinline__ float bf_hi(unsigned u) { return __uint_as_float(u & 0xffff0000u); }
; __device__ __forceinline__ void gla_phase(unsigned char* lds, const bf16_t* __restrict__ Z1, bf16_t* __restrict__ Of, bf16_t* __restrict__ Ob, int bi, int nb, int nitems) {
;     ...
;                 float offa = 0.f, offb = 0.f, tota = 0.f, totb = 0.f;
; #pragma unroll
;                 for (int s = 0; s < 8; ++s) { const float2 v = *(const float2*)(SEG + s * 128 + d2); tota += v.x; totb += v.y; const bool inc = dir ? (s > w) : (s < w); offa += inc ? v.x : 0.f; offb += inc ? v.y : 0.f; }
;                 const float eta = __expf(tota), etb = __expf(totb);
;                 if (w == 0) *(float2*)(DECy + d2) = make_float2(eta, etb);
;                 float kda[8], kdb[8];
; #pragma unroll
;                 for (int tt = 0; tt < 8; ++tt) { const float ba = offa + ga[tt], bb = offb + gb[tt];
;                     const float ea = __expf(ba), eb = __expf(bb), iea = __expf(-ba), ieb = __expf(-bb);
;                     const float ksa = bf_lo(rk[tt]) * iea, ksb = bf_hi(rk[tt]) * ieb;
;                     *(unsigned*)(QSy + (8 * w + tt) * 136 + d2) = cvt_pk_bf16(bf_lo(rq[tt]) * ea, bf_hi(rq[tt]) * eb);
;                     *(unsigned*)(KS + (8 * w + tt) * 136 + d2) = cvt_pk_bf16(ksa, ksb);
;                     kda[tt] = ksa * eta; kdb[tt] = ksb * etb; }
	ds_read2st64_b64 v[72:75], v104 offset1:1
	ds_read2st64_b64 v[68:71], v104 offset0:2 offset1:3
	ds_read2st64_b64 v[64:67], v104 offset0:4 offset1:5
	ds_read2st64_b64 v[76:79], v104 offset0:6 offset1:7
	s_waitcnt lgkmcnt(3)
	v_add_f32_e32 v159, 0, v72
	v_add_f32_e32 v160, 0, v73
	v_add_f32_e32 v72, v159, v74
	v_add_f32_e32 v73, v160, v75
	s_waitcnt lgkmcnt(2)
	v_add_f32_e32 v72, v72, v68
	v_add_f32_e32 v73, v73, v69
	v_add_f32_e32 v72, v72, v70
	v_add_f32_e32 v73, v73, v71
	s_waitcnt lgkmcnt(1)
	v_add_f32_e32 v72, v72, v64
	v_add_f32_e32 v73, v73, v65
	v_add_f32_e32 v72, v72, v66
	v_add_f32_e32 v73, v73, v67
	s_waitcnt lgkmcnt(0)
	v_add_f32_e32 v72, v72, v76
	v_add_f32_e32 v73, v73, v77
	v_add_f32_e32 v72, v72, v78
	v_add_f32_e32 v73, v73, v79
	v_mul_f32_e32 v72, 0x3fb8aa3b, v72
	v_mul_f32_e32 v73, 0x3fb8aa3b, v73
	v_exp_f32_e32 v72, v72
	v_exp_f32_e32 v73, v73
	s_and_saveexec_b64 s[94:95], s[2:3]
	v_lshl_add_u32 v161, v80, 2, s11
	ds_write_b64 v161, v[72:73] offset:63488
	s_or_b64 exec, exec, s[94:95]
	v_cndmask_b32_e64 v159, 0, v159, s[56:57]
	v_cndmask_b32_e64 v74, 0, v74, s[58:59]
	v_cndmask_b32_e64 v160, 0, v160, s[56:57]
	v_add_f32_e32 v74, v159, v74
	v_cndmask_b32_e64 v75, 0, v75, s[58:59]
	v_cndmask_b32_e64 v68, 0, v68, s[60:61]
	v_add_f32_e32 v75, v160, v75
	v_add_f32_e32 v68, v74, v68
	v_cndmask_b32_e64 v69, 0, v69, s[60:61]
	v_cndmask_b32_e64 v70, 0, v70, s[62:63]
	v_add_f32_e32 v69, v75, v69
	v_add_f32_e32 v68, v68, v70
	v_cndmask_b32_e64 v70, 0, v71, s[62:63]
	v_cndmask_b32_e64 v64, 0, v64, s[64:65]
	v_add_f32_e32 v69, v69, v70
	v_add_f32_e32 v64, v68, v64
	v_cndmask_b32_e64 v65, 0, v65, s[64:65]
	v_cndmask_b32_e64 v66, 0, v66, s[66:67]
	v_add_f32_e32 v65, v69, v65
	v_add_f32_e32 v64, v64, v66
	v_cndmask_b32_e64 v66, 0, v67, s[66:67]
	v_add_f32_e32 v65, v65, v66
	v_cndmask_b32_e64 v66, 0, v76, s[68:69]
	v_add_f32_e32 v64, v64, v66
	v_cndmask_b32_e64 v66, 0, v77, s[68:69]
	v_add_f32_e32 v65, v65, v66
	v_cndmask_b32_e64 v66, 0, v78, s[70:71]
	v_add_f32_e32 v64, v64, v66
	v_cndmask_b32_e64 v66, 0, v79, s[70:71]
	v_add_f32_e32 v65, v65, v66
	v_add_f32_e32 v67, v8, v64
	v_add_f32_e32 v68, v0, v65
	v_mul_f32_e32 v69, 0x3fb8aa3b, v67
	v_mul_f32_e32 v67, 0xbfb8aa3b, v67
	v_mul_f32_e32 v70, 0x3fb8aa3b, v68
	v_exp_f32_e32 v67, v67
	v_mul_f32_e32 v68, 0xbfb8aa3b, v68
	v_exp_f32_e32 v68, v68
	v_exp_f32_e32 v69, v69
	v_exp_f32_e32 v70, v70
	s_waitcnt vmcnt(14)
	v_lshlrev_b32_e32 v71, 16, v143
	v_mul_f32_e32 v67, v67, v71
	v_and_b32_e32 v71, 0xffff0000, v143
	v_mul_f32_e32 v68, v68, v71
	v_lshlrev_b32_e32 v71, 16, v142
	v_lshlrev_b32_e32 v66, 1, v80
	v_mul_f32_e32 v69, v69, v71
	v_and_b32_e32 v71, 0xffff0000, v142
	v_mul_f32_e32 v70, v70, v71
	v_cvt_pk_bf16_f32 v69, v69, v70
	v_add3_u32 v66, s11, v66, v113
	ds_write_b32 v66, v69
	v_cvt_pk_bf16_f32 v69, v67, v68
	ds_write_b32 v114, v69
	v_add_f32_e32 v69, v9, v64
	v_add_f32_e32 v70, v1, v65
	v_mul_f32_e32 v71, 0x3fb8aa3b, v69
	v_mul_f32_e32 v69, 0xbfb8aa3b, v69
	v_mul_f32_e32 v74, 0x3fb8aa3b, v70
	v_exp_f32_e32 v69, v69
	v_mul_f32_e32 v70, 0xbfb8aa3b, v70
	v_exp_f32_e32 v70, v70
	v_exp_f32_e32 v71, v71
	v_exp_f32_e32 v74, v74
	s_waitcnt vmcnt(12)
	v_lshlrev_b32_e32 v75, 16, v145
	v_mul_f32_e32 v69, v69, v75
	v_and_b32_e32 v75, 0xffff0000, v145
	v_mul_f32_e32 v70, v70, v75
	v_lshlrev_b32_e32 v75, 16, v144
	v_mul_f32_e32 v71, v71, v75
	v_and_b32_e32 v75, 0xffff0000, v144
	v_mul_f32_e32 v74, v74, v75
	v_cvt_pk_bf16_f32 v71, v71, v74
	ds_write_b32 v66, v71 offset:272
	v_cvt_pk_bf16_f32 v71, v69, v70
	ds_write_b32 v114, v71 offset:272
	v_add_f32_e32 v71, v10, v64
	v_add_f32_e32 v74, v2, v65
	v_mul_f32_e32 v75, 0x3fb8aa3b, v71
	v_mul_f32_e32 v71, 0xbfb8aa3b, v71
	v_mul_f32_e32 v76, 0x3fb8aa3b, v74
	v_exp_f32_e32 v71, v71
	v_mul_f32_e32 v74, 0xbfb8aa3b, v74
	v_exp_f32_e32 v74, v74
	v_exp_f32_e32 v75, v75
	v_exp_f32_e32 v76, v76
	s_waitcnt vmcnt(10)
	v_lshlrev_b32_e32 v77, 16, v147
	v_mul_f32_e32 v71, v71, v77
	v_and_b32_e32 v77, 0xffff0000, v147
	v_mul_f32_e32 v74, v74, v77
	v_lshlrev_b32_e32 v77, 16, v146
	v_mul_f32_e32 v75, v75, v77
	v_and_b32_e32 v77, 0xffff0000, v146
	v_mul_f32_e32 v76, v76, v77
	v_cvt_pk_bf16_f32 v75, v75, v76
	ds_write_b32 v66, v75 offset:544
	v_cvt_pk_bf16_f32 v75, v71, v74
	ds_write_b32 v114, v75 offset:544
	v_add_f32_e32 v75, v11, v64
	v_add_f32_e32 v76, v3, v65
	v_mul_f32_e32 v77, 0x3fb8aa3b, v75
	v_mul_f32_e32 v75, 0xbfb8aa3b, v75
	v_mul_f32_e32 v78, 0x3fb8aa3b, v76
	v_exp_f32_e32 v75, v75
	v_mul_f32_e32 v76, 0xbfb8aa3b, v76
	v_exp_f32_e32 v76, v76
	v_exp_f32_e32 v77, v77
	v_exp_f32_e32 v78, v78
	s_waitcnt vmcnt(8)
	v_lshlrev_b32_e32 v79, 16, v149
	v_mul_f32_e32 v75, v75, v79
	v_and_b32_e32 v79, 0xffff0000, v149
	v_mul_f32_e32 v76, v76, v79
	v_lshlrev_b32_e32 v79, 16, v148
	v_mul_f32_e32 v77, v77, v79
	v_and_b32_e32 v79, 0xffff0000, v148
	v_mul_f32_e32 v78, v78, v79
	v_cvt_pk_bf16_f32 v77, v77, v78
	ds_write_b32 v66, v77 offset:816
	v_cvt_pk_bf16_f32 v77, v75, v76
	ds_write_b32 v114, v77 offset:816
	v_add_f32_e32 v77, v12, v64
	v_add_f32_e32 v78, v4, v65
	v_mul_f32_e32 v79, 0x3fb8aa3b, v77
	v_mul_f32_e32 v77, 0xbfb8aa3b, v77
	v_mul_f32_e32 v159, 0x3fb8aa3b, v78
	v_exp_f32_e32 v77, v77
	v_mul_f32_e32 v78, 0xbfb8aa3b, v78
	v_exp_f32_e32 v78, v78
	v_exp_f32_e32 v79, v79
	v_exp_f32_e32 v159, v159
	s_waitcnt vmcnt(6)
; __device__ __forceinline__ unsigned cvt_pk_bf16(float lo, float hi) { unsigned r; asm volatile("v_cvt_pk_bf16_f32 %0, %1, %2" : "=v"(r) : "v"(lo), "v"(hi)); return r; }
; __device__ __forceinline__ float bf_lo(unsigned u) { return __uint_as_float(u << 16); }
; __device__ __forceinline__ float bf_hi(unsigned u) { return __uint_as_float(u & 0xffff0000u); }
; __device__ __forceinline__ void gla_phase(unsigned char* lds, const bf16_t* __restrict__ Z1, bf16_t* __restrict__ Of, bf16_t* __restrict__ Ob, int bi, int nb, int nitems) {
;     ...
;                 for (int tt = 0; tt < 8; ++tt) { const float ba = offa + ga[tt], bb = offb + gb[tt];
;                     const float ea = __expf(ba), eb = __expf(bb), iea = __expf(-ba), ieb = __expf(-bb);
;                     const float ksa = bf_lo(rk[tt]) * iea, ksb = bf_hi(rk[tt]) * ieb;
;                     *(unsigned*)(QSy + (8 * w + tt) * 136 + d2) = cvt_pk_bf16(bf_lo(rq[tt]) * ea, bf_hi(rq[tt]) * eb);
;                     *(unsigned*)(KS + (8 * w + tt) * 136 + d2) = cvt_pk_bf16(ksa, ksb);
;                     kda[tt] = ksa * eta; kdb[tt] = ksb * etb; }
;                 u32x4 ka, kb;
;                 ka.x = cvt_pk_bf16(kda[0], kda[1]); ka.y = cvt_pk_bf16(kda[2], kda[3]); ka.z = cvt_pk_bf16(kda[4], kda[5]); ka.w = cvt_pk_bf16(kda[6], kda[7]);
;                 kb.x = cvt_pk_bf16(kdb[0], kdb[1]); kb.y = cvt_pk_bf16(kdb[2], kdb[3]); kb.z = cvt_pk_bf16(kdb[4], kdb[5]); kb.w = cvt_pk_bf16(kdb[6], kdb[7]);
;                 *(u32x4*)(KDy + d2 * 72 + 8 * w) = ka; *(u32x4*)(KDy + (d2 + 1) * 72 + 8 * w) = kb;
;                 if (pref) { const size_t co = (size_t)(cnn * 64) * NZ1;
; #pragma unroll
;                     for (int tt = 0; tt < 8; ++tt) { const size_t o = co + (size_t)tt * NZ1; rq[tt] = *(const unsigned*)(zq + o); rk[tt] = *(const unsigned*)(zk + o); } }
	v_lshlrev_b32_e32 v160, 16, v151
	v_mul_f32_e32 v77, v77, v160
	v_and_b32_e32 v160, 0xffff0000, v151
	v_mul_f32_e32 v78, v78, v160
	v_lshlrev_b32_e32 v160, 16, v150
	v_mul_f32_e32 v79, v79, v160
	v_and_b32_e32 v160, 0xffff0000, v150
	v_mul_f32_e32 v159, v159, v160
	v_cvt_pk_bf16_f32 v79, v79, v159
	ds_write_b32 v66, v79 offset:1088
	v_cvt_pk_bf16_f32 v79, v77, v78
	ds_write_b32 v114, v79 offset:1088
	v_add_f32_e32 v79, v13, v64
	v_add_f32_e32 v159, v5, v65
	v_mul_f32_e32 v160, 0x3fb8aa3b, v79
	v_mul_f32_e32 v79, 0xbfb8aa3b, v79
	v_mul_f32_e32 v161, 0x3fb8aa3b, v159
	v_exp_f32_e32 v79, v79
	v_mul_f32_e32 v159, 0xbfb8aa3b, v159
	v_exp_f32_e32 v159, v159
	v_exp_f32_e32 v160, v160
	v_exp_f32_e32 v161, v161
	s_waitcnt vmcnt(4)
	v_lshlrev_b32_e32 v162, 16, v154
	v_mul_f32_e32 v79, v79, v162
	v_and_b32_e32 v162, 0xffff0000, v154
	v_mul_f32_e32 v159, v159, v162
	v_lshlrev_b32_e32 v162, 16, v153
	v_mul_f32_e32 v160, v160, v162
	v_and_b32_e32 v162, 0xffff0000, v153
	v_mul_f32_e32 v161, v161, v162
	v_cvt_pk_bf16_f32 v160, v160, v161
	ds_write_b32 v66, v160 offset:1360
	v_cvt_pk_bf16_f32 v160, v79, v159
	ds_write_b32 v114, v160 offset:1360
	v_add_f32_e32 v160, v14, v64
	v_add_f32_e32 v161, v6, v65
	v_mul_f32_e32 v162, 0x3fb8aa3b, v160
	v_mul_f32_e32 v160, 0xbfb8aa3b, v160
	v_mul_f32_e32 v163, 0x3fb8aa3b, v161
	v_exp_f32_e32 v160, v160
	v_mul_f32_e32 v161, 0xbfb8aa3b, v161
	v_exp_f32_e32 v161, v161
	v_exp_f32_e32 v162, v162
	v_exp_f32_e32 v163, v163
	s_waitcnt vmcnt(2)
	v_lshlrev_b32_e32 v164, 16, v156
	v_mul_f32_e32 v160, v160, v164
	v_and_b32_e32 v164, 0xffff0000, v156
	v_mul_f32_e32 v161, v161, v164
	v_lshlrev_b32_e32 v164, 16, v155
	v_mul_f32_e32 v162, v162, v164
	v_and_b32_e32 v164, 0xffff0000, v155
	v_mul_f32_e32 v163, v163, v164
	v_cvt_pk_bf16_f32 v162, v162, v163
	ds_write_b32 v66, v162 offset:1632
	v_cvt_pk_bf16_f32 v162, v160, v161
	v_add_f32_e32 v64, v15, v64
	ds_write_b32 v114, v162 offset:1632
	v_add_f32_e32 v65, v7, v65
	v_mul_f32_e32 v162, 0x3fb8aa3b, v64
	v_mul_f32_e32 v64, 0xbfb8aa3b, v64
	v_mul_f32_e32 v163, 0x3fb8aa3b, v65
	v_exp_f32_e32 v64, v64
	v_mul_f32_e32 v65, 0xbfb8aa3b, v65
	v_exp_f32_e32 v65, v65
	v_exp_f32_e32 v162, v162
	v_exp_f32_e32 v163, v163
	s_waitcnt vmcnt(0)
	v_lshlrev_b32_e32 v164, 16, v158
	v_mul_f32_e32 v64, v64, v164
	v_and_b32_e32 v164, 0xffff0000, v158
	v_mul_f32_e32 v65, v65, v164
	v_lshlrev_b32_e32 v164, 16, v157
	v_mul_f32_e32 v162, v162, v164
	v_and_b32_e32 v164, 0xffff0000, v157
	v_mul_f32_e32 v67, v72, v67
	v_mul_f32_e32 v69, v72, v69
	v_mul_f32_e32 v71, v72, v71
	v_mul_f32_e32 v75, v72, v75
	v_mul_f32_e32 v77, v72, v77
	v_mul_f32_e32 v79, v72, v79
	v_mul_f32_e32 v160, v72, v160
	v_mul_f32_e32 v163, v163, v164
	v_cvt_pk_bf16_f32 v162, v162, v163
	ds_write_b32 v66, v162 offset:1904
	v_cvt_pk_bf16_f32 v66, v64, v65
	v_mul_f32_e32 v72, v72, v64
	v_mul_f32_e32 v68, v73, v68
	v_mul_f32_e32 v70, v73, v70
	v_mul_f32_e32 v74, v73, v74
	v_mul_f32_e32 v76, v73, v76
	v_mul_f32_e32 v78, v73, v78
	v_mul_f32_e32 v159, v73, v159
	v_mul_f32_e32 v161, v73, v161
	ds_write_b32 v114, v66 offset:1904
	v_mul_f32_e32 v73, v73, v65
	v_cvt_pk_bf16_f32 v64, v67, v69
	v_cvt_pk_bf16_f32 v65, v71, v75
	v_cvt_pk_bf16_f32 v66, v77, v79
	v_cvt_pk_bf16_f32 v67, v160, v72
	v_lshlrev_b32_e32 v72, 1, v81
	v_add3_u32 v72, s11, v106, v72
	s_andn2_b64 vcc, exec, s[92:93]
	v_cvt_pk_bf16_f32 v68, v68, v70
	v_cvt_pk_bf16_f32 v69, v74, v76
	v_cvt_pk_bf16_f32 v70, v78, v159
	v_cvt_pk_bf16_f32 v71, v161, v73
	ds_write_b128 v72, v[64:67] offset:17408
	ds_write_b128 v72, v[68:71] offset:17552
	s_cbranch_vccnz .LBB0_604
	s_lshl_b32 s12, s12, 6
	s_ashr_i32 s13, s12, 31
	s_lshl_b64 s[92:93], s[12:13], 13
	v_lshl_add_u64 v[64:65], v[90:91], 0, s[92:93]
	s_or_b32 s12, s92, 0x2000
	s_mov_b32 s13, s93
	global_load_dword v142, v[64:65], off
	global_load_dword v143, v[64:65], off offset:1024
	v_lshl_add_u64 v[64:65], v[90:91], 0, s[12:13]
	global_load_dword v144, v[64:65], off
	v_lshl_add_u64 v[64:65], v[96:97], 0, s[12:13]
	s_or_b32 s12, s92, 0x4000
	global_load_dword v145, v[64:65], off
	v_lshl_add_u64 v[64:65], v[90:91], 0, s[12:13]
	global_load_dword v146, v[64:65], off
	v_lshl_add_u64 v[64:65], v[96:97], 0, s[12:13]
	s_or_b32 s12, s92, 0x6000
	global_load_dword v147, v[64:65], off
	v_lshl_add_u64 v[64:65], v[90:91], 0, s[12:13]
	global_load_dword v148, v[64:65], off
	v_lshl_add_u64 v[64:65], v[96:97], 0, s[12:13]
	s_or_b32 s12, s92, 0x8000
	global_load_dword v149, v[64:65], off
	v_lshl_add_u64 v[64:65], v[90:91], 0, s[12:13]
	global_load_dword v150, v[64:65], off
	v_lshl_add_u64 v[64:65], v[96:97], 0, s[12:13]
	s_or_b32 s12, s92, 0xa000
	global_load_dword v151, v[64:65], off
	v_lshl_add_u64 v[64:65], v[90:91], 0, s[12:13]
	global_load_dword v153, v[64:65], off
	v_lshl_add_u64 v[64:65], v[96:97], 0, s[12:13]
	s_or_b32 s12, s92, 0xc000
	global_load_dword v154, v[64:65], off
	v_lshl_add_u64 v[64:65], v[90:91], 0, s[12:13]
	global_load_dword v155, v[64:65], off
	v_lshl_add_u64 v[64:65], v[96:97], 0, s[12:13]
	s_or_b32 s92, s92, 0xe000
	global_load_dword v156, v[64:65], off
	v_lshl_add_u64 v[64:65], v[90:91], 0, s[92:93]
	global_load_dword v157, v[64:65], off
	v_lshl_add_u64 v[64:65], v[96:97], 0, s[92:93]
	global_load_dword v158, v[64:65], off

; __global__ void __launch_bounds__(512, 2) mk_fwd(Args a) {
;     extern __shared__ __attribute__((aligned(16))) unsigned char lds[];
	.amdhsa_kernel _ZN2mk6mk_fwdENS_4ArgsE
		.amdhsa_group_segment_fixed_size 0
		.amdhsa_private_segment_fixed_size 0
		.amdhsa_kernarg_size 456
		.amdhsa_user_sgpr_count 2
		.amdhsa_user_sgpr_dispatch_ptr 0
		.amdhsa_user_sgpr_queue_ptr 0
		.amdhsa_user_sgpr_kernarg_segment_ptr 1
		.amdhsa_user_sgpr_dispatch_id 0
		.amdhsa_user_sgpr_kernarg_preload_length 0
		.amdhsa_user_sgpr_kernarg_preload_offset 0
		.amdhsa_user_sgpr_private_segment_size 0
		.amdhsa_uses_dynamic_stack 0
		.amdhsa_enable_private_segment 0
		.amdhsa_system_sgpr_workgroup_id_x 1
		.amdhsa_system_sgpr_workgroup_id_y 0
		.amdhsa_system_sgpr_workgroup_id_z 0
		.amdhsa_system_sgpr_workgroup_info 0
		.amdhsa_system_vgpr_workitem_id 2
		.amdhsa_next_free_vgpr 246
		.amdhsa_next_free_sgpr 102
		.amdhsa_accum_offset 248
		.amdhsa_reserve_vcc 1
		.amdhsa_float_round_mode_32 0
		.amdhsa_float_round_mode_16_64 0
		.amdhsa_float_denorm_mode_32 3
		.amdhsa_float_denorm_mode_16_64 3
		.amdhsa_dx10_clamp 1
		.amdhsa_ieee_mode 1
		.amdhsa_fp16_overflow 0
		.amdhsa_tg_split 0
		.amdhsa_exception_fp_ieee_invalid_op 0
		.amdhsa_exception_fp_denorm_src 0
		.amdhsa_exception_fp_ieee_div_zero 0
		.amdhsa_exception_fp_ieee_overflow 0
		.amdhsa_exception_fp_ieee_underflow 0
		.amdhsa_exception_fp_ieee_inexact 0
		.amdhsa_exception_int_div_zero 0
	.end_amdhsa_kernel

; __global__ void __launch_bounds__(512, 2) mk_fwd(Args a) {
;     extern __shared__ __attribute__((aligned(16))) unsigned char lds[];
amdhsa.kernels:
  - .agpr_count:     0
    .args:
      - .offset:         0
        .size:           200
        .value_kind:     by_value
      - .offset:         200
        .size:           4
        .value_kind:     hidden_block_count_x
      - .offset:         204
        .size:           4
        .value_kind:     hidden_block_count_y
      - .offset:         208
        .size:           4
        .value_kind:     hidden_block_count_z
      - .offset:         212
        .size:           2
        .value_kind:     hidden_group_size_x
      - .offset:         214
        .size:           2
        .value_kind:     hidden_group_size_y
      - .offset:         216
        .size:           2
        .value_kind:     hidden_group_size_z
      - .offset:         218
        .size:           2
        .value_kind:     hidden_remainder_x
      - .offset:         220
        .size:           2
        .value_kind:     hidden_remainder_y
      - .offset:         222
        .size:           2
        .value_kind:     hidden_remainder_z
      - .offset:         240
        .size:           8
        .value_kind:     hidden_global_offset_x
      - .offset:         248
        .size:           8
        .value_kind:     hidden_global_offset_y
      - .offset:         256
        .size:           8
        .value_kind:     hidden_global_offset_z
      - .offset:         264
        .size:           2
        .value_kind:     hidden_grid_dims
      - .offset:         288
        .size:           8
        .value_kind:     hidden_multigrid_sync_arg
      - .offset:         320
        .size:           4
        .value_kind:     hidden_dynamic_lds_size
    .group_segment_fixed_size: 0
    .kernarg_segment_align: 8
    .kernarg_segment_size: 456
    .language:       OpenCL C
    .language_version:
      - 2
      - 0
    .max_flat_workgroup_size: 512
    .name:           _ZN2mk6mk_fwdENS_4ArgsE
    .private_segment_fixed_size: 0
    .sgpr_count:     108
    .sgpr_spill_count: 74
    .symbol:         _ZN2mk6mk_fwdENS_4ArgsE.kd
    .uniform_work_group_size: 1
    .uses_dynamic_stack: false
    .vgpr_count:     246
    .vgpr_spill_count: 0
    .wavefront_size: 64
